# v30 + GEMM K-loops: s_setprio 1 issued before each compute segment's opening barrier and s_setprio 0 after its closing barrier (both off the barrier-to-first-MFMA hand-over path)
# speedup vs baseline: 1.0139x; 1.0001x over previous
.LBB0_161:
	s_ashr_i32 s23, s22, 31
	s_lshl_b64 s[8:9], s[22:23], 20
	v_readlane_b32 s20, v254, 38
	v_readlane_b32 s21, v254, 39
	s_add_u32 s8, s20, s8
	s_addc_u32 s9, s21, s9
	s_and_b64 s[20:21], s[40:41], exec
	s_cselect_b32 s13, s9, s43
	s_cselect_b32 s20, s8, s42
	s_ashr_i32 s19, s18, 31
	s_lshl_b64 s[28:29], s[18:19], 20
	v_readlane_b32 s30, v254, 22
	v_readlane_b32 s31, v254, 23
	s_add_u32 s28, s30, s28
	s_addc_u32 s29, s31, s29
	s_and_b64 s[30:31], s[40:41], exec
	s_cselect_b32 s19, s29, s45
	s_cselect_b32 s21, s28, s44
	s_add_u32 s42, s42, 0x80080
	s_addc_u32 s43, s43, 0
	s_add_u32 s23, s44, 0x100
	s_addc_u32 s25, s45, 0
	s_mov_b32 s30, -2
	v_readlane_b32 s52, v255, 20
	v_readlane_b32 s53, v255, 21
	v_readlane_b32 s72, v255, 22
	v_readlane_b32 s73, v255, 23
	s_mov_b64 s[74:75], 0x80
	s_add_u32 s31, s42, 0xfff80080
	s_addc_u32 s44, s43, -1
	s_add_i32 s47, 0, 0x10000
	s_cmp_eq_u32 s30, 28
	s_cselect_b32 s49, s13, s44
	s_cselect_b32 s48, s20, s31
	ds_read_b128 v[144:147], v1
	ds_read_b128 v[148:151], v141
	s_cselect_b32 s45, s19, s25
	s_cselect_b32 s44, s21, s23
	s_add_i32 s31, 0, 0x14000
	ds_read_b128 v[152:155], v1 offset:2048
	ds_read_b128 v[156:159], v141 offset:2048
	ds_read_b128 v[160:163], v1 offset:16384
	ds_read_b128 v[164:167], v141 offset:16384
	ds_read_b128 v[168:171], v1 offset:18432
	ds_read_b128 v[172:175], v141 offset:18432
	s_add_i32 m0, s34, 0xc000
	ds_read_b128 v[176:179], v142
	ds_read_b128 v[184:187], v142 offset:2048
	ds_read_b128 v[188:191], v143
	ds_read_b128 v[192:195], v143 offset:2048
	ds_read_b128 v[196:199], v142 offset:4096
	ds_read_b128 v[200:203], v142 offset:6144
	ds_read_b128 v[204:207], v143 offset:4096
	ds_read_b128 v[208:211], v143 offset:6144
	global_load_lds_dwordx4 v138, s[42:43]
	s_add_i32 m0, s34, 0xe000
	s_nop 0
	global_load_lds_dwordx4 v134, s[42:43]
	s_waitcnt vmcnt(8)
	s_waitcnt lgkmcnt(0)
	s_setprio 1
	s_barrier
	v_mfma_f32_16x16x32_bf16 v[128:131], v[144:147], v[176:179], 0
	v_mfma_f32_16x16x32_bf16 v[124:127], v[152:155], v[176:179], 0
	v_mfma_f32_16x16x32_bf16 v[112:115], v[144:147], v[184:187], 0
	v_mfma_f32_16x16x32_bf16 v[108:111], v[152:155], v[184:187], 0
	v_mfma_f32_16x16x32_bf16 v[96:99], v[144:147], v[196:199], 0
	v_mfma_f32_16x16x32_bf16 v[92:95], v[152:155], v[196:199], 0
	v_mfma_f32_16x16x32_bf16 v[80:83], v[144:147], v[200:203], 0
	v_mfma_f32_16x16x32_bf16 v[76:79], v[152:155], v[200:203], 0
	v_mfma_f32_16x16x32_bf16 v[128:131], v[148:151], v[188:191], v[128:131]
	v_mfma_f32_16x16x32_bf16 v[124:127], v[156:159], v[188:191], v[124:127]
	v_mfma_f32_16x16x32_bf16 v[112:115], v[148:151], v[192:195], v[112:115]
	v_mfma_f32_16x16x32_bf16 v[108:111], v[156:159], v[192:195], v[108:111]
	v_mfma_f32_16x16x32_bf16 v[96:99], v[148:151], v[204:207], v[96:99]
	v_mfma_f32_16x16x32_bf16 v[92:95], v[156:159], v[204:207], v[92:95]
	v_mfma_f32_16x16x32_bf16 v[80:83], v[148:151], v[208:211], v[80:83]
	v_mfma_f32_16x16x32_bf16 v[76:79], v[156:159], v[208:211], v[76:79]
	s_setprio 0
	s_setprio 1
	v_mfma_f32_16x16x32_bf16 v[120:123], v[160:163], v[176:179], 0
	v_mfma_f32_16x16x32_bf16 v[116:119], v[168:171], v[176:179], 0
	v_mfma_f32_16x16x32_bf16 v[104:107], v[160:163], v[184:187], 0
	v_mfma_f32_16x16x32_bf16 v[100:103], v[168:171], v[184:187], 0
	v_mfma_f32_16x16x32_bf16 v[88:91], v[160:163], v[196:199], 0
	v_mfma_f32_16x16x32_bf16 v[84:87], v[168:171], v[196:199], 0
	v_mfma_f32_16x16x32_bf16 v[72:75], v[160:163], v[200:203], 0
	v_mfma_f32_16x16x32_bf16 v[68:71], v[168:171], v[200:203], 0
	v_mfma_f32_16x16x32_bf16 v[120:123], v[164:167], v[188:191], v[120:123]
	v_mfma_f32_16x16x32_bf16 v[116:119], v[172:175], v[188:191], v[116:119]
	v_mfma_f32_16x16x32_bf16 v[104:107], v[164:167], v[192:195], v[104:107]
	v_mfma_f32_16x16x32_bf16 v[100:103], v[172:175], v[192:195], v[100:103]
	v_mfma_f32_16x16x32_bf16 v[88:91], v[164:167], v[204:207], v[88:91]
	v_mfma_f32_16x16x32_bf16 v[84:87], v[172:175], v[204:207], v[84:87]
	v_mfma_f32_16x16x32_bf16 v[72:75], v[164:167], v[208:211], v[72:75]
	v_mfma_f32_16x16x32_bf16 v[68:71], v[172:175], v[208:211], v[68:71]
	s_barrier
	s_setprio 0
	s_add_i32 s47, s47, s33
	s_mov_b32 m0, s47
	ds_read_b128 v[176:179], v142 offset:16384
	ds_read_b128 v[184:187], v142 offset:18432
	ds_read_b128 v[188:191], v143 offset:16384
	ds_read_b128 v[192:195], v143 offset:18432
	ds_read_b128 v[196:199], v142 offset:20480
	ds_read_b128 v[200:203], v142 offset:22528
	ds_read_b128 v[204:207], v143 offset:20480
	ds_read_b128 v[208:211], v143 offset:22528
	global_load_lds_dwordx4 v136, s[44:45]
	s_add_i32 m0, s47, 0x2000
	s_add_u32 s50, s44, 0x80000
	s_addc_u32 s51, s45, 0
	s_add_i32 s31, s31, s33
	global_load_lds_dwordx4 v132, s[44:45]
	s_mov_b32 m0, s31
	s_nop 0
	global_load_lds_dwordx4 v136, s[50:51]
	s_add_i32 m0, s31, 0x2000
	s_nop 0
	global_load_lds_dwordx4 v132, s[50:51]
	s_mov_b32 m0, s34
	s_nop 0
	global_load_lds_dwordx4 v138, s[48:49]
	s_mov_b32 m0, s35
	s_nop 0
	global_load_lds_dwordx4 v134, s[48:49]
	s_waitcnt vmcnt(8)
	s_waitcnt lgkmcnt(0)
	s_setprio 1
	s_barrier
	v_mfma_f32_16x16x32_bf16 v[64:67], v[144:147], v[176:179], 0
	v_mfma_f32_16x16x32_bf16 v[60:63], v[152:155], v[176:179], 0
	v_mfma_f32_16x16x32_bf16 v[48:51], v[144:147], v[184:187], 0
	v_mfma_f32_16x16x32_bf16 v[44:47], v[152:155], v[184:187], 0
	v_mfma_f32_16x16x32_bf16 v[30:33], v[144:147], v[196:199], 0
	v_mfma_f32_16x16x32_bf16 v[26:29], v[152:155], v[196:199], 0
	v_mfma_f32_16x16x32_bf16 v[14:17], v[144:147], v[200:203], 0
	v_mfma_f32_16x16x32_bf16 v[10:13], v[152:155], v[200:203], 0
	v_mfma_f32_16x16x32_bf16 v[64:67], v[148:151], v[188:191], v[64:67]
	v_mfma_f32_16x16x32_bf16 v[60:63], v[156:159], v[188:191], v[60:63]
	v_mfma_f32_16x16x32_bf16 v[48:51], v[148:151], v[192:195], v[48:51]
	v_mfma_f32_16x16x32_bf16 v[44:47], v[156:159], v[192:195], v[44:47]
	v_mfma_f32_16x16x32_bf16 v[30:33], v[148:151], v[204:207], v[30:33]
	v_mfma_f32_16x16x32_bf16 v[26:29], v[156:159], v[204:207], v[26:29]
	v_mfma_f32_16x16x32_bf16 v[14:17], v[148:151], v[208:211], v[14:17]
	v_mfma_f32_16x16x32_bf16 v[10:13], v[156:159], v[208:211], v[10:13]
	s_setprio 0
	s_setprio 1
	v_mfma_f32_16x16x32_bf16 v[56:59], v[160:163], v[176:179], 0
	v_mfma_f32_16x16x32_bf16 v[52:55], v[168:171], v[176:179], 0
	v_mfma_f32_16x16x32_bf16 v[40:43], v[160:163], v[184:187], 0
	v_mfma_f32_16x16x32_bf16 v[36:39], v[168:171], v[184:187], 0
	v_mfma_f32_16x16x32_bf16 v[22:25], v[160:163], v[196:199], 0
	v_mfma_f32_16x16x32_bf16 v[18:21], v[168:171], v[196:199], 0
	v_mfma_f32_16x16x32_bf16 v[6:9], v[160:163], v[200:203], 0
	v_mfma_f32_16x16x32_bf16 v[2:5], v[168:171], v[200:203], 0
	v_mfma_f32_16x16x32_bf16 v[56:59], v[164:167], v[188:191], v[56:59]
	v_mfma_f32_16x16x32_bf16 v[52:55], v[172:175], v[188:191], v[52:55]
	v_mfma_f32_16x16x32_bf16 v[40:43], v[164:167], v[192:195], v[40:43]
	v_mfma_f32_16x16x32_bf16 v[36:39], v[172:175], v[192:195], v[36:39]
	v_mfma_f32_16x16x32_bf16 v[22:25], v[164:167], v[204:207], v[22:25]
	v_mfma_f32_16x16x32_bf16 v[18:21], v[172:175], v[204:207], v[18:21]
	v_mfma_f32_16x16x32_bf16 v[6:9], v[164:167], v[208:211], v[6:9]
	v_mfma_f32_16x16x32_bf16 v[2:5], v[172:175], v[208:211], v[2:5]
	s_barrier
	s_setprio 0
	s_add_i32 s31, 0, 0x18000
	ds_read_b128 v[144:147], v1 offset:32768
	ds_read_b128 v[148:151], v141 offset:32768
	s_add_i32 s47, 0, 0x1c000
	ds_read_b128 v[152:155], v1 offset:34816
	ds_read_b128 v[156:159], v141 offset:34816
	ds_read_b128 v[160:163], v1 offset:49152
	ds_read_b128 v[164:167], v141 offset:49152
	ds_read_b128 v[168:171], v1 offset:51200
	ds_read_b128 v[172:175], v141 offset:51200
	s_mov_b64 s[100:101], s[48:49]
	s_add_u32 s48, s48, 0x80000
	s_addc_u32 s49, s49, 0
	s_mov_b32 m0, s54
	ds_read_b128 v[176:179], v142 offset:32768
	ds_read_b128 v[184:187], v142 offset:34816
	ds_read_b128 v[188:191], v143 offset:32768
	ds_read_b128 v[192:195], v143 offset:34816
	ds_read_b128 v[196:199], v142 offset:36864
	ds_read_b128 v[200:203], v142 offset:38912
	ds_read_b128 v[204:207], v143 offset:36864
	ds_read_b128 v[208:211], v143 offset:38912
	global_load_lds_dwordx4 v138, s[48:49]
	s_mov_b32 m0, s55
	s_nop 0
	global_load_lds_dwordx4 v134, s[48:49]
	s_waitcnt vmcnt(8)
	s_waitcnt lgkmcnt(0)
	s_setprio 1
	s_barrier
	v_mfma_f32_16x16x32_bf16 v[128:131], v[144:147], v[176:179], v[128:131]
	v_mfma_f32_16x16x32_bf16 v[124:127], v[152:155], v[176:179], v[124:127]
	v_mfma_f32_16x16x32_bf16 v[112:115], v[144:147], v[184:187], v[112:115]
	v_mfma_f32_16x16x32_bf16 v[108:111], v[152:155], v[184:187], v[108:111]
	v_mfma_f32_16x16x32_bf16 v[96:99], v[144:147], v[196:199], v[96:99]
	v_mfma_f32_16x16x32_bf16 v[92:95], v[152:155], v[196:199], v[92:95]
	v_mfma_f32_16x16x32_bf16 v[80:83], v[144:147], v[200:203], v[80:83]
	v_mfma_f32_16x16x32_bf16 v[76:79], v[152:155], v[200:203], v[76:79]
	v_mfma_f32_16x16x32_bf16 v[128:131], v[148:151], v[188:191], v[128:131]
	v_mfma_f32_16x16x32_bf16 v[124:127], v[156:159], v[188:191], v[124:127]
	v_mfma_f32_16x16x32_bf16 v[112:115], v[148:151], v[192:195], v[112:115]
	v_mfma_f32_16x16x32_bf16 v[108:111], v[156:159], v[192:195], v[108:111]
	v_mfma_f32_16x16x32_bf16 v[96:99], v[148:151], v[204:207], v[96:99]
	v_mfma_f32_16x16x32_bf16 v[92:95], v[156:159], v[204:207], v[92:95]
	v_mfma_f32_16x16x32_bf16 v[80:83], v[148:151], v[208:211], v[80:83]
	v_mfma_f32_16x16x32_bf16 v[76:79], v[156:159], v[208:211], v[76:79]
	s_setprio 0
	s_setprio 1
	v_mfma_f32_16x16x32_bf16 v[120:123], v[160:163], v[176:179], v[120:123]
	v_mfma_f32_16x16x32_bf16 v[116:119], v[168:171], v[176:179], v[116:119]
	v_mfma_f32_16x16x32_bf16 v[104:107], v[160:163], v[184:187], v[104:107]
	v_mfma_f32_16x16x32_bf16 v[100:103], v[168:171], v[184:187], v[100:103]
	v_mfma_f32_16x16x32_bf16 v[88:91], v[160:163], v[196:199], v[88:91]
	v_mfma_f32_16x16x32_bf16 v[84:87], v[168:171], v[196:199], v[84:87]
	v_mfma_f32_16x16x32_bf16 v[72:75], v[160:163], v[200:203], v[72:75]
	v_mfma_f32_16x16x32_bf16 v[68:71], v[168:171], v[200:203], v[68:71]
	v_mfma_f32_16x16x32_bf16 v[120:123], v[164:167], v[188:191], v[120:123]
	v_mfma_f32_16x16x32_bf16 v[116:119], v[172:175], v[188:191], v[116:119]
	v_mfma_f32_16x16x32_bf16 v[104:107], v[164:167], v[192:195], v[104:107]
	v_mfma_f32_16x16x32_bf16 v[100:103], v[172:175], v[192:195], v[100:103]
	v_mfma_f32_16x16x32_bf16 v[88:91], v[164:167], v[204:207], v[88:91]
	v_mfma_f32_16x16x32_bf16 v[84:87], v[172:175], v[204:207], v[84:87]
	v_mfma_f32_16x16x32_bf16 v[72:75], v[164:167], v[208:211], v[72:75]
	v_mfma_f32_16x16x32_bf16 v[68:71], v[172:175], v[208:211], v[68:71]
	s_barrier
	s_setprio 0
	s_add_i32 s31, s31, s33
	s_add_i32 m0, s31, 0xffffff80
	ds_read_b128 v[176:179], v142 offset:49152
	ds_read_b128 v[184:187], v142 offset:51200
	ds_read_b128 v[188:191], v143 offset:49152
	ds_read_b128 v[192:195], v143 offset:51200
	ds_read_b128 v[196:199], v142 offset:53248
	ds_read_b128 v[200:203], v142 offset:55296
	ds_read_b128 v[204:207], v143 offset:53248
	ds_read_b128 v[208:211], v143 offset:55296
	global_load_lds_dwordx4 v136, s[44:45] offset:128
	s_add_i32 m0, s31, 0x1f80
	s_mov_b64 s[98:99], s[44:45]
	s_add_u32 s44, s44, 0x80080
	s_addc_u32 s45, s45, 0
	s_add_i32 s31, s47, s33
	global_load_lds_dwordx4 v132, s[98:99] offset:128
	s_mov_b32 m0, s31
	s_nop 0
	global_load_lds_dwordx4 v136, s[44:45]
	s_add_i32 m0, s31, 0x2000
	s_nop 0
	global_load_lds_dwordx4 v132, s[44:45]
	s_add_i32 m0, s56, 0xffffff80
	s_nop 0
	global_load_lds_dwordx4 v138, s[100:101] offset:128
	s_add_i32 m0, s57, 0xffffff80
	s_nop 0
	global_load_lds_dwordx4 v134, s[100:101] offset:128
	s_waitcnt vmcnt(8)
	s_waitcnt lgkmcnt(0)
	s_setprio 1
	s_barrier
	v_mfma_f32_16x16x32_bf16 v[64:67], v[144:147], v[176:179], v[64:67]
	v_mfma_f32_16x16x32_bf16 v[60:63], v[152:155], v[176:179], v[60:63]
	v_mfma_f32_16x16x32_bf16 v[48:51], v[144:147], v[184:187], v[48:51]
	v_mfma_f32_16x16x32_bf16 v[44:47], v[152:155], v[184:187], v[44:47]
	v_mfma_f32_16x16x32_bf16 v[30:33], v[144:147], v[196:199], v[30:33]
	v_mfma_f32_16x16x32_bf16 v[26:29], v[152:155], v[196:199], v[26:29]
	v_mfma_f32_16x16x32_bf16 v[14:17], v[144:147], v[200:203], v[14:17]
	v_mfma_f32_16x16x32_bf16 v[10:13], v[152:155], v[200:203], v[10:13]
	v_mfma_f32_16x16x32_bf16 v[64:67], v[148:151], v[188:191], v[64:67]
	v_mfma_f32_16x16x32_bf16 v[60:63], v[156:159], v[188:191], v[60:63]
	v_mfma_f32_16x16x32_bf16 v[48:51], v[148:151], v[192:195], v[48:51]
	v_mfma_f32_16x16x32_bf16 v[44:47], v[156:159], v[192:195], v[44:47]
	v_mfma_f32_16x16x32_bf16 v[30:33], v[148:151], v[204:207], v[30:33]
	v_mfma_f32_16x16x32_bf16 v[26:29], v[156:159], v[204:207], v[26:29]
	v_mfma_f32_16x16x32_bf16 v[14:17], v[148:151], v[208:211], v[14:17]
	v_mfma_f32_16x16x32_bf16 v[10:13], v[156:159], v[208:211], v[10:13]
	s_setprio 0
	s_setprio 1
	v_mfma_f32_16x16x32_bf16 v[56:59], v[160:163], v[176:179], v[56:59]
	v_mfma_f32_16x16x32_bf16 v[52:55], v[168:171], v[176:179], v[52:55]
	v_mfma_f32_16x16x32_bf16 v[40:43], v[160:163], v[184:187], v[40:43]
	v_mfma_f32_16x16x32_bf16 v[36:39], v[168:171], v[184:187], v[36:39]
	v_mfma_f32_16x16x32_bf16 v[22:25], v[160:163], v[196:199], v[22:25]
	v_mfma_f32_16x16x32_bf16 v[18:21], v[168:171], v[196:199], v[18:21]
	v_mfma_f32_16x16x32_bf16 v[6:9], v[160:163], v[200:203], v[6:9]
	v_mfma_f32_16x16x32_bf16 v[2:5], v[168:171], v[200:203], v[2:5]
	v_mfma_f32_16x16x32_bf16 v[56:59], v[164:167], v[188:191], v[56:59]
	v_mfma_f32_16x16x32_bf16 v[52:55], v[172:175], v[188:191], v[52:55]
	v_mfma_f32_16x16x32_bf16 v[40:43], v[164:167], v[192:195], v[40:43]
	v_mfma_f32_16x16x32_bf16 v[36:39], v[172:175], v[192:195], v[36:39]
	v_mfma_f32_16x16x32_bf16 v[22:25], v[164:167], v[204:207], v[22:25]
	v_mfma_f32_16x16x32_bf16 v[18:21], v[172:175], v[204:207], v[18:21]
	v_mfma_f32_16x16x32_bf16 v[6:9], v[164:167], v[208:211], v[6:9]
	v_mfma_f32_16x16x32_bf16 v[2:5], v[172:175], v[208:211], v[2:5]
	s_barrier
	s_setprio 0
	s_add_i32 s30, s30, 2
	s_add_u32 s42, s42, 0x100
	s_addc_u32 s43, s43, 0
	s_add_u32 s23, s23, 0x100
	s_addc_u32 s25, s25, 0
	s_cmp_gt_u32 s30, 29
	s_cbranch_scc1 .Lpeel_done_P1
.LBB0_162:
	s_add_u32 s31, s42, 0xfff80080
	s_addc_u32 s44, s43, -1
	s_add_i32 s47, 0, 0x10000
	s_cmp_eq_u32 s30, 28
	s_cselect_b32 s49, s13, s44
	s_cselect_b32 s48, s20, s31
	ds_read_b128 v[144:147], v1
	ds_read_b128 v[148:151], v141
	s_cselect_b32 s45, s19, s25
	s_cselect_b32 s44, s21, s23
	s_add_i32 s31, 0, 0x14000
	ds_read_b128 v[152:155], v1 offset:2048
	ds_read_b128 v[156:159], v141 offset:2048
	ds_read_b128 v[160:163], v1 offset:16384
	ds_read_b128 v[164:167], v141 offset:16384
	ds_read_b128 v[168:171], v1 offset:18432
	ds_read_b128 v[172:175], v141 offset:18432
	s_add_i32 m0, s34, 0xc000
	ds_read_b128 v[176:179], v142
	ds_read_b128 v[184:187], v142 offset:2048
	ds_read_b128 v[188:191], v143
	ds_read_b128 v[192:195], v143 offset:2048
	ds_read_b128 v[196:199], v142 offset:4096
	ds_read_b128 v[200:203], v142 offset:6144
	ds_read_b128 v[204:207], v143 offset:4096
	ds_read_b128 v[208:211], v143 offset:6144
	global_load_lds_dwordx4 v138, s[42:43]
	s_add_i32 m0, s34, 0xe000
	s_nop 0
	global_load_lds_dwordx4 v134, s[42:43]
	s_waitcnt vmcnt(8)
	s_waitcnt lgkmcnt(0)
	s_setprio 1
	s_barrier
	v_mfma_f32_16x16x32_bf16 v[128:131], v[144:147], v[176:179], v[128:131]
	v_mfma_f32_16x16x32_bf16 v[124:127], v[152:155], v[176:179], v[124:127]
	v_mfma_f32_16x16x32_bf16 v[112:115], v[144:147], v[184:187], v[112:115]
	v_mfma_f32_16x16x32_bf16 v[108:111], v[152:155], v[184:187], v[108:111]
	v_mfma_f32_16x16x32_bf16 v[96:99], v[144:147], v[196:199], v[96:99]
	v_mfma_f32_16x16x32_bf16 v[92:95], v[152:155], v[196:199], v[92:95]
	v_mfma_f32_16x16x32_bf16 v[80:83], v[144:147], v[200:203], v[80:83]
	v_mfma_f32_16x16x32_bf16 v[76:79], v[152:155], v[200:203], v[76:79]
	v_mfma_f32_16x16x32_bf16 v[128:131], v[148:151], v[188:191], v[128:131]
	v_mfma_f32_16x16x32_bf16 v[124:127], v[156:159], v[188:191], v[124:127]
	v_mfma_f32_16x16x32_bf16 v[112:115], v[148:151], v[192:195], v[112:115]
	v_mfma_f32_16x16x32_bf16 v[108:111], v[156:159], v[192:195], v[108:111]
	v_mfma_f32_16x16x32_bf16 v[96:99], v[148:151], v[204:207], v[96:99]
	v_mfma_f32_16x16x32_bf16 v[92:95], v[156:159], v[204:207], v[92:95]
	v_mfma_f32_16x16x32_bf16 v[80:83], v[148:151], v[208:211], v[80:83]
	v_mfma_f32_16x16x32_bf16 v[76:79], v[156:159], v[208:211], v[76:79]
	s_setprio 0
	s_setprio 1
	v_mfma_f32_16x16x32_bf16 v[120:123], v[160:163], v[176:179], v[120:123]
	v_mfma_f32_16x16x32_bf16 v[116:119], v[168:171], v[176:179], v[116:119]
	v_mfma_f32_16x16x32_bf16 v[104:107], v[160:163], v[184:187], v[104:107]
	v_mfma_f32_16x16x32_bf16 v[100:103], v[168:171], v[184:187], v[100:103]
	v_mfma_f32_16x16x32_bf16 v[88:91], v[160:163], v[196:199], v[88:91]
	v_mfma_f32_16x16x32_bf16 v[84:87], v[168:171], v[196:199], v[84:87]
	v_mfma_f32_16x16x32_bf16 v[72:75], v[160:163], v[200:203], v[72:75]
	v_mfma_f32_16x16x32_bf16 v[68:71], v[168:171], v[200:203], v[68:71]
	v_mfma_f32_16x16x32_bf16 v[120:123], v[164:167], v[188:191], v[120:123]
	v_mfma_f32_16x16x32_bf16 v[116:119], v[172:175], v[188:191], v[116:119]
	v_mfma_f32_16x16x32_bf16 v[104:107], v[164:167], v[192:195], v[104:107]
	v_mfma_f32_16x16x32_bf16 v[100:103], v[172:175], v[192:195], v[100:103]
	v_mfma_f32_16x16x32_bf16 v[88:91], v[164:167], v[204:207], v[88:91]
	v_mfma_f32_16x16x32_bf16 v[84:87], v[172:175], v[204:207], v[84:87]
	v_mfma_f32_16x16x32_bf16 v[72:75], v[164:167], v[208:211], v[72:75]
	v_mfma_f32_16x16x32_bf16 v[68:71], v[172:175], v[208:211], v[68:71]
	s_barrier
	s_setprio 0
	s_add_i32 s47, s47, s33
	s_mov_b32 m0, s47
	ds_read_b128 v[176:179], v142 offset:16384
	ds_read_b128 v[184:187], v142 offset:18432
	ds_read_b128 v[188:191], v143 offset:16384
	ds_read_b128 v[192:195], v143 offset:18432
	ds_read_b128 v[196:199], v142 offset:20480
	ds_read_b128 v[200:203], v142 offset:22528
	ds_read_b128 v[204:207], v143 offset:20480
	ds_read_b128 v[208:211], v143 offset:22528
	global_load_lds_dwordx4 v136, s[44:45]
	s_add_i32 m0, s47, 0x2000
	s_add_u32 s50, s44, 0x80000
	s_addc_u32 s51, s45, 0
	s_add_i32 s31, s31, s33
	global_load_lds_dwordx4 v132, s[44:45]
	s_mov_b32 m0, s31
	s_nop 0
	global_load_lds_dwordx4 v136, s[50:51]
	s_add_i32 m0, s31, 0x2000
	s_nop 0
	global_load_lds_dwordx4 v132, s[50:51]
	s_mov_b32 m0, s34
	s_nop 0
	global_load_lds_dwordx4 v138, s[48:49]
	s_mov_b32 m0, s35
	s_nop 0
	global_load_lds_dwordx4 v134, s[48:49]
	s_waitcnt vmcnt(8)
	s_waitcnt lgkmcnt(0)
	s_setprio 1
	s_barrier
	v_mfma_f32_16x16x32_bf16 v[64:67], v[144:147], v[176:179], v[64:67]
	v_mfma_f32_16x16x32_bf16 v[60:63], v[152:155], v[176:179], v[60:63]
	v_mfma_f32_16x16x32_bf16 v[48:51], v[144:147], v[184:187], v[48:51]
	v_mfma_f32_16x16x32_bf16 v[44:47], v[152:155], v[184:187], v[44:47]
	v_mfma_f32_16x16x32_bf16 v[30:33], v[144:147], v[196:199], v[30:33]
	v_mfma_f32_16x16x32_bf16 v[26:29], v[152:155], v[196:199], v[26:29]
	v_mfma_f32_16x16x32_bf16 v[14:17], v[144:147], v[200:203], v[14:17]
	v_mfma_f32_16x16x32_bf16 v[10:13], v[152:155], v[200:203], v[10:13]
	v_mfma_f32_16x16x32_bf16 v[64:67], v[148:151], v[188:191], v[64:67]
	v_mfma_f32_16x16x32_bf16 v[60:63], v[156:159], v[188:191], v[60:63]
	v_mfma_f32_16x16x32_bf16 v[48:51], v[148:151], v[192:195], v[48:51]
	v_mfma_f32_16x16x32_bf16 v[44:47], v[156:159], v[192:195], v[44:47]
	v_mfma_f32_16x16x32_bf16 v[30:33], v[148:151], v[204:207], v[30:33]
	v_mfma_f32_16x16x32_bf16 v[26:29], v[156:159], v[204:207], v[26:29]
	v_mfma_f32_16x16x32_bf16 v[14:17], v[148:151], v[208:211], v[14:17]
	v_mfma_f32_16x16x32_bf16 v[10:13], v[156:159], v[208:211], v[10:13]
	s_setprio 0
	s_setprio 1
	v_mfma_f32_16x16x32_bf16 v[56:59], v[160:163], v[176:179], v[56:59]
	v_mfma_f32_16x16x32_bf16 v[52:55], v[168:171], v[176:179], v[52:55]
	v_mfma_f32_16x16x32_bf16 v[40:43], v[160:163], v[184:187], v[40:43]
	v_mfma_f32_16x16x32_bf16 v[36:39], v[168:171], v[184:187], v[36:39]
	v_mfma_f32_16x16x32_bf16 v[22:25], v[160:163], v[196:199], v[22:25]
	v_mfma_f32_16x16x32_bf16 v[18:21], v[168:171], v[196:199], v[18:21]
	v_mfma_f32_16x16x32_bf16 v[6:9], v[160:163], v[200:203], v[6:9]
	v_mfma_f32_16x16x32_bf16 v[2:5], v[168:171], v[200:203], v[2:5]
	v_mfma_f32_16x16x32_bf16 v[56:59], v[164:167], v[188:191], v[56:59]
	v_mfma_f32_16x16x32_bf16 v[52:55], v[172:175], v[188:191], v[52:55]
	v_mfma_f32_16x16x32_bf16 v[40:43], v[164:167], v[192:195], v[40:43]
	v_mfma_f32_16x16x32_bf16 v[36:39], v[172:175], v[192:195], v[36:39]
	v_mfma_f32_16x16x32_bf16 v[22:25], v[164:167], v[204:207], v[22:25]
	v_mfma_f32_16x16x32_bf16 v[18:21], v[172:175], v[204:207], v[18:21]
	v_mfma_f32_16x16x32_bf16 v[6:9], v[164:167], v[208:211], v[6:9]
	v_mfma_f32_16x16x32_bf16 v[2:5], v[172:175], v[208:211], v[2:5]
	s_barrier
	s_setprio 0
	s_add_i32 s31, 0, 0x18000
	ds_read_b128 v[144:147], v1 offset:32768
	ds_read_b128 v[148:151], v141 offset:32768
	s_add_i32 s47, 0, 0x1c000
	ds_read_b128 v[152:155], v1 offset:34816
	ds_read_b128 v[156:159], v141 offset:34816
	ds_read_b128 v[160:163], v1 offset:49152
	ds_read_b128 v[164:167], v141 offset:49152
	ds_read_b128 v[168:171], v1 offset:51200
	ds_read_b128 v[172:175], v141 offset:51200
	s_mov_b64 s[100:101], s[48:49]
	s_add_u32 s48, s48, 0x80000
	s_addc_u32 s49, s49, 0
	s_mov_b32 m0, s54
	ds_read_b128 v[176:179], v142 offset:32768
	ds_read_b128 v[184:187], v142 offset:34816
	ds_read_b128 v[188:191], v143 offset:32768
	ds_read_b128 v[192:195], v143 offset:34816
	ds_read_b128 v[196:199], v142 offset:36864
	ds_read_b128 v[200:203], v142 offset:38912
	ds_read_b128 v[204:207], v143 offset:36864
	ds_read_b128 v[208:211], v143 offset:38912
	global_load_lds_dwordx4 v138, s[48:49]
	s_mov_b32 m0, s55
	s_nop 0
	global_load_lds_dwordx4 v134, s[48:49]
	s_waitcnt vmcnt(8)
	s_waitcnt lgkmcnt(0)
	s_setprio 1
	s_barrier
	v_mfma_f32_16x16x32_bf16 v[128:131], v[144:147], v[176:179], v[128:131]
	v_mfma_f32_16x16x32_bf16 v[124:127], v[152:155], v[176:179], v[124:127]
	v_mfma_f32_16x16x32_bf16 v[112:115], v[144:147], v[184:187], v[112:115]
	v_mfma_f32_16x16x32_bf16 v[108:111], v[152:155], v[184:187], v[108:111]
	v_mfma_f32_16x16x32_bf16 v[96:99], v[144:147], v[196:199], v[96:99]
	v_mfma_f32_16x16x32_bf16 v[92:95], v[152:155], v[196:199], v[92:95]
	v_mfma_f32_16x16x32_bf16 v[80:83], v[144:147], v[200:203], v[80:83]
	v_mfma_f32_16x16x32_bf16 v[76:79], v[152:155], v[200:203], v[76:79]
	v_mfma_f32_16x16x32_bf16 v[128:131], v[148:151], v[188:191], v[128:131]
	v_mfma_f32_16x16x32_bf16 v[124:127], v[156:159], v[188:191], v[124:127]
	v_mfma_f32_16x16x32_bf16 v[112:115], v[148:151], v[192:195], v[112:115]
	v_mfma_f32_16x16x32_bf16 v[108:111], v[156:159], v[192:195], v[108:111]
	v_mfma_f32_16x16x32_bf16 v[96:99], v[148:151], v[204:207], v[96:99]
	v_mfma_f32_16x16x32_bf16 v[92:95], v[156:159], v[204:207], v[92:95]
	v_mfma_f32_16x16x32_bf16 v[80:83], v[148:151], v[208:211], v[80:83]
	v_mfma_f32_16x16x32_bf16 v[76:79], v[156:159], v[208:211], v[76:79]
	s_setprio 0
	s_setprio 1
	v_mfma_f32_16x16x32_bf16 v[120:123], v[160:163], v[176:179], v[120:123]
	v_mfma_f32_16x16x32_bf16 v[116:119], v[168:171], v[176:179], v[116:119]
	v_mfma_f32_16x16x32_bf16 v[104:107], v[160:163], v[184:187], v[104:107]
	v_mfma_f32_16x16x32_bf16 v[100:103], v[168:171], v[184:187], v[100:103]
	v_mfma_f32_16x16x32_bf16 v[88:91], v[160:163], v[196:199], v[88:91]
	v_mfma_f32_16x16x32_bf16 v[84:87], v[168:171], v[196:199], v[84:87]
	v_mfma_f32_16x16x32_bf16 v[72:75], v[160:163], v[200:203], v[72:75]
	v_mfma_f32_16x16x32_bf16 v[68:71], v[168:171], v[200:203], v[68:71]
	v_mfma_f32_16x16x32_bf16 v[120:123], v[164:167], v[188:191], v[120:123]
	v_mfma_f32_16x16x32_bf16 v[116:119], v[172:175], v[188:191], v[116:119]
	v_mfma_f32_16x16x32_bf16 v[104:107], v[164:167], v[192:195], v[104:107]
	v_mfma_f32_16x16x32_bf16 v[100:103], v[172:175], v[192:195], v[100:103]
	v_mfma_f32_16x16x32_bf16 v[88:91], v[164:167], v[204:207], v[88:91]
	v_mfma_f32_16x16x32_bf16 v[84:87], v[172:175], v[204:207], v[84:87]
	v_mfma_f32_16x16x32_bf16 v[72:75], v[164:167], v[208:211], v[72:75]
	v_mfma_f32_16x16x32_bf16 v[68:71], v[172:175], v[208:211], v[68:71]
	s_barrier
	s_setprio 0
	s_add_i32 s31, s31, s33
	s_add_i32 m0, s31, 0xffffff80
	ds_read_b128 v[176:179], v142 offset:49152
	ds_read_b128 v[184:187], v142 offset:51200
	ds_read_b128 v[188:191], v143 offset:49152
	ds_read_b128 v[192:195], v143 offset:51200
	ds_read_b128 v[196:199], v142 offset:53248
	ds_read_b128 v[200:203], v142 offset:55296
	ds_read_b128 v[204:207], v143 offset:53248
	ds_read_b128 v[208:211], v143 offset:55296
	global_load_lds_dwordx4 v136, s[44:45] offset:128
	s_add_i32 m0, s31, 0x1f80
	s_mov_b64 s[98:99], s[44:45]
	s_add_u32 s44, s44, 0x80080
	s_addc_u32 s45, s45, 0
	s_add_i32 s31, s47, s33
	global_load_lds_dwordx4 v132, s[98:99] offset:128
	s_mov_b32 m0, s31
	s_nop 0
	global_load_lds_dwordx4 v136, s[44:45]
	s_add_i32 m0, s31, 0x2000
	s_nop 0
	global_load_lds_dwordx4 v132, s[44:45]
	s_add_i32 m0, s56, 0xffffff80
	s_nop 0
	global_load_lds_dwordx4 v138, s[100:101] offset:128
	s_add_i32 m0, s57, 0xffffff80
	s_nop 0
	global_load_lds_dwordx4 v134, s[100:101] offset:128
	s_waitcnt vmcnt(8)
	s_waitcnt lgkmcnt(0)
	s_setprio 1
	s_barrier
	v_mfma_f32_16x16x32_bf16 v[64:67], v[144:147], v[176:179], v[64:67]
	v_mfma_f32_16x16x32_bf16 v[60:63], v[152:155], v[176:179], v[60:63]
	v_mfma_f32_16x16x32_bf16 v[48:51], v[144:147], v[184:187], v[48:51]
	v_mfma_f32_16x16x32_bf16 v[44:47], v[152:155], v[184:187], v[44:47]
	v_mfma_f32_16x16x32_bf16 v[30:33], v[144:147], v[196:199], v[30:33]
	v_mfma_f32_16x16x32_bf16 v[26:29], v[152:155], v[196:199], v[26:29]
	v_mfma_f32_16x16x32_bf16 v[14:17], v[144:147], v[200:203], v[14:17]
	v_mfma_f32_16x16x32_bf16 v[10:13], v[152:155], v[200:203], v[10:13]
	v_mfma_f32_16x16x32_bf16 v[64:67], v[148:151], v[188:191], v[64:67]
	v_mfma_f32_16x16x32_bf16 v[60:63], v[156:159], v[188:191], v[60:63]
	v_mfma_f32_16x16x32_bf16 v[48:51], v[148:151], v[192:195], v[48:51]
	v_mfma_f32_16x16x32_bf16 v[44:47], v[156:159], v[192:195], v[44:47]
	v_mfma_f32_16x16x32_bf16 v[30:33], v[148:151], v[204:207], v[30:33]
	v_mfma_f32_16x16x32_bf16 v[26:29], v[156:159], v[204:207], v[26:29]
	v_mfma_f32_16x16x32_bf16 v[14:17], v[148:151], v[208:211], v[14:17]
	v_mfma_f32_16x16x32_bf16 v[10:13], v[156:159], v[208:211], v[10:13]
	s_setprio 0
	s_setprio 1
	v_mfma_f32_16x16x32_bf16 v[56:59], v[160:163], v[176:179], v[56:59]
	v_mfma_f32_16x16x32_bf16 v[52:55], v[168:171], v[176:179], v[52:55]
	v_mfma_f32_16x16x32_bf16 v[40:43], v[160:163], v[184:187], v[40:43]
	v_mfma_f32_16x16x32_bf16 v[36:39], v[168:171], v[184:187], v[36:39]
	v_mfma_f32_16x16x32_bf16 v[22:25], v[160:163], v[196:199], v[22:25]
	v_mfma_f32_16x16x32_bf16 v[18:21], v[168:171], v[196:199], v[18:21]
	v_mfma_f32_16x16x32_bf16 v[6:9], v[160:163], v[200:203], v[6:9]
	v_mfma_f32_16x16x32_bf16 v[2:5], v[168:171], v[200:203], v[2:5]
	v_mfma_f32_16x16x32_bf16 v[56:59], v[164:167], v[188:191], v[56:59]
	v_mfma_f32_16x16x32_bf16 v[52:55], v[172:175], v[188:191], v[52:55]
	v_mfma_f32_16x16x32_bf16 v[40:43], v[164:167], v[192:195], v[40:43]
	v_mfma_f32_16x16x32_bf16 v[36:39], v[172:175], v[192:195], v[36:39]
	v_mfma_f32_16x16x32_bf16 v[22:25], v[164:167], v[204:207], v[22:25]
	v_mfma_f32_16x16x32_bf16 v[18:21], v[172:175], v[204:207], v[18:21]
	v_mfma_f32_16x16x32_bf16 v[6:9], v[164:167], v[208:211], v[6:9]
	v_mfma_f32_16x16x32_bf16 v[2:5], v[172:175], v[208:211], v[2:5]
	s_barrier
	s_setprio 0
	s_add_i32 s30, s30, 2
	s_add_u32 s42, s42, 0x100
	s_addc_u32 s43, s43, 0
	s_add_u32 s23, s23, 0x100
	s_addc_u32 s25, s25, 0
	s_cmp_gt_u32 s30, 29
	s_cbranch_scc0 .LBB0_162

.LBB0_907:
	s_and_b32 s9, 1, s12
	s_cmp_gt_i32 s12, 1
	s_cselect_b32 s24, 10, 12
	s_cmp_eq_u32 s9, 1
	s_cselect_b64 s[18:19], -1, 0
	s_and_b64 s[20:21], s[18:19], exec
	s_cselect_b32 s9, s24, 32
	s_add_i32 s20, s9, -2
	s_add_u32 s22, s22, 0x80080
	s_addc_u32 s23, s23, 0
	s_add_u32 s21, s28, 0x100
	s_addc_u32 s24, s29, 0
	s_mov_b32 s25, 0
	s_waitcnt vmcnt(0)
	v_readlane_b32 s43, v255, 20
	v_readlane_b32 s45, v255, 21
	v_readlane_b32 s66, v255, 22
	v_readlane_b32 s67, v255, 23
	s_mov_b64 s[68:69], 0x80
	s_add_i32 s30, s25, 2
	s_add_u32 s28, s22, 0xfff80080
	s_addc_u32 s29, s23, -1
	s_add_i32 s31, 0, 0x10000
	s_cmp_eq_u32 s20, s25
	s_cselect_b32 s41, s47, s29
	s_cselect_b32 s40, s46, s28
	s_cselect_b32 s29, s49, s24
	s_cselect_b32 s28, s48, s21
	s_add_i32 s25, 0, 0x14000
	ds_read_b128 v[132:135], v1
	ds_read_b128 v[136:139], v204
	ds_read_b128 v[140:143], v1 offset:2048
	ds_read_b128 v[144:147], v204 offset:2048
	ds_read_b128 v[148:151], v1 offset:16384
	ds_read_b128 v[152:155], v204 offset:16384
	ds_read_b128 v[156:159], v1 offset:18432
	ds_read_b128 v[160:163], v204 offset:18432
	s_add_i32 m0, s50, 0xc000
	ds_read_b128 v[164:167], v205
	ds_read_b128 v[168:171], v205 offset:2048
	ds_read_b128 v[172:175], v206
	ds_read_b128 v[176:179], v206 offset:2048
	ds_read_b128 v[190:193], v205 offset:4096
	ds_read_b128 v[194:197], v205 offset:6144
	ds_read_b128 v[198:201], v206 offset:4096
	ds_read_b128 v[232:235], v206 offset:6144
	global_load_lds_dwordx4 v188, s[22:23]
	s_add_i32 m0, s50, 0xe000
	s_nop 0
	global_load_lds_dwordx4 v186, s[22:23]
	s_waitcnt vmcnt(8)
	s_waitcnt lgkmcnt(0)
	s_setprio 1
	s_barrier
	v_mfma_f32_16x16x32_bf16 v[68:71], v[132:135], v[164:167], 0
	v_mfma_f32_16x16x32_bf16 v[72:75], v[140:143], v[164:167], 0
	v_mfma_f32_16x16x32_bf16 v[84:87], v[132:135], v[168:171], 0
	v_mfma_f32_16x16x32_bf16 v[88:91], v[140:143], v[168:171], 0
	v_mfma_f32_16x16x32_bf16 v[100:103], v[132:135], v[190:193], 0
	v_mfma_f32_16x16x32_bf16 v[104:107], v[140:143], v[190:193], 0
	v_mfma_f32_16x16x32_bf16 v[116:119], v[132:135], v[194:197], 0
	v_mfma_f32_16x16x32_bf16 v[120:123], v[140:143], v[194:197], 0
	v_mfma_f32_16x16x32_bf16 v[68:71], v[136:139], v[172:175], v[68:71]
	v_mfma_f32_16x16x32_bf16 v[72:75], v[144:147], v[172:175], v[72:75]
	v_mfma_f32_16x16x32_bf16 v[84:87], v[136:139], v[176:179], v[84:87]
	v_mfma_f32_16x16x32_bf16 v[88:91], v[144:147], v[176:179], v[88:91]
	v_mfma_f32_16x16x32_bf16 v[100:103], v[136:139], v[198:201], v[100:103]
	v_mfma_f32_16x16x32_bf16 v[104:107], v[144:147], v[198:201], v[104:107]
	v_mfma_f32_16x16x32_bf16 v[116:119], v[136:139], v[232:235], v[116:119]
	v_mfma_f32_16x16x32_bf16 v[120:123], v[144:147], v[232:235], v[120:123]
	s_setprio 0
	s_setprio 1
	v_mfma_f32_16x16x32_bf16 v[76:79], v[148:151], v[164:167], 0
	v_mfma_f32_16x16x32_bf16 v[80:83], v[156:159], v[164:167], 0
	v_mfma_f32_16x16x32_bf16 v[92:95], v[148:151], v[168:171], 0
	v_mfma_f32_16x16x32_bf16 v[96:99], v[156:159], v[168:171], 0
	v_mfma_f32_16x16x32_bf16 v[108:111], v[148:151], v[190:193], 0
	v_mfma_f32_16x16x32_bf16 v[112:115], v[156:159], v[190:193], 0
	v_mfma_f32_16x16x32_bf16 v[124:127], v[148:151], v[194:197], 0
	v_mfma_f32_16x16x32_bf16 v[128:131], v[156:159], v[194:197], 0
	v_mfma_f32_16x16x32_bf16 v[76:79], v[152:155], v[172:175], v[76:79]
	v_mfma_f32_16x16x32_bf16 v[80:83], v[160:163], v[172:175], v[80:83]
	v_mfma_f32_16x16x32_bf16 v[92:95], v[152:155], v[176:179], v[92:95]
	v_mfma_f32_16x16x32_bf16 v[96:99], v[160:163], v[176:179], v[96:99]
	v_mfma_f32_16x16x32_bf16 v[108:111], v[152:155], v[198:201], v[108:111]
	v_mfma_f32_16x16x32_bf16 v[112:115], v[160:163], v[198:201], v[112:115]
	v_mfma_f32_16x16x32_bf16 v[124:127], v[152:155], v[232:235], v[124:127]
	v_mfma_f32_16x16x32_bf16 v[128:131], v[160:163], v[232:235], v[128:131]
	s_barrier
	s_setprio 0
	s_add_i32 s31, s31, s33
	s_mov_b32 m0, s31
	ds_read_b128 v[164:167], v205 offset:16384
	ds_read_b128 v[168:171], v205 offset:18432
	ds_read_b128 v[172:175], v206 offset:16384
	ds_read_b128 v[176:179], v206 offset:18432
	ds_read_b128 v[190:193], v205 offset:20480
	ds_read_b128 v[194:197], v205 offset:22528
	ds_read_b128 v[198:201], v206 offset:20480
	ds_read_b128 v[232:235], v206 offset:22528
	global_load_lds_dwordx4 v34, s[28:29]
	s_add_i32 m0, s31, 0x2000
	s_add_u32 s34, s28, 0x80000
	s_addc_u32 s35, s29, 0
	s_add_i32 s25, s25, s33
	global_load_lds_dwordx4 v184, s[28:29]
	s_mov_b32 m0, s25
	s_nop 0
	global_load_lds_dwordx4 v34, s[34:35]
	s_add_i32 m0, s25, 0x2000
	s_nop 0
	global_load_lds_dwordx4 v184, s[34:35]
	s_mov_b32 m0, s50
	s_nop 0
	global_load_lds_dwordx4 v188, s[40:41]
	s_mov_b32 m0, s51
	s_nop 0
	global_load_lds_dwordx4 v186, s[40:41]
	s_waitcnt vmcnt(8)
	s_waitcnt lgkmcnt(0)
	s_setprio 1
	s_barrier
	v_mfma_f32_16x16x32_bf16 v[2:5], v[132:135], v[164:167], 0
	v_mfma_f32_16x16x32_bf16 v[6:9], v[140:143], v[164:167], 0
	v_mfma_f32_16x16x32_bf16 v[18:21], v[132:135], v[168:171], 0
	v_mfma_f32_16x16x32_bf16 v[22:25], v[140:143], v[168:171], 0
	v_mfma_f32_16x16x32_bf16 v[36:39], v[132:135], v[190:193], 0
	v_mfma_f32_16x16x32_bf16 v[40:43], v[140:143], v[190:193], 0
	v_mfma_f32_16x16x32_bf16 v[52:55], v[132:135], v[194:197], 0
	v_mfma_f32_16x16x32_bf16 v[56:59], v[140:143], v[194:197], 0
	v_mfma_f32_16x16x32_bf16 v[2:5], v[136:139], v[172:175], v[2:5]
	v_mfma_f32_16x16x32_bf16 v[6:9], v[144:147], v[172:175], v[6:9]
	v_mfma_f32_16x16x32_bf16 v[18:21], v[136:139], v[176:179], v[18:21]
	v_mfma_f32_16x16x32_bf16 v[22:25], v[144:147], v[176:179], v[22:25]
	v_mfma_f32_16x16x32_bf16 v[36:39], v[136:139], v[198:201], v[36:39]
	v_mfma_f32_16x16x32_bf16 v[40:43], v[144:147], v[198:201], v[40:43]
	v_mfma_f32_16x16x32_bf16 v[52:55], v[136:139], v[232:235], v[52:55]
	v_mfma_f32_16x16x32_bf16 v[56:59], v[144:147], v[232:235], v[56:59]
	s_setprio 0
	s_setprio 1
	v_mfma_f32_16x16x32_bf16 v[10:13], v[148:151], v[164:167], 0
	v_mfma_f32_16x16x32_bf16 v[14:17], v[156:159], v[164:167], 0
	v_mfma_f32_16x16x32_bf16 v[26:29], v[148:151], v[168:171], 0
	v_mfma_f32_16x16x32_bf16 v[30:33], v[156:159], v[168:171], 0
	v_mfma_f32_16x16x32_bf16 v[44:47], v[148:151], v[190:193], 0
	v_mfma_f32_16x16x32_bf16 v[48:51], v[156:159], v[190:193], 0
	v_mfma_f32_16x16x32_bf16 v[60:63], v[148:151], v[194:197], 0
	v_mfma_f32_16x16x32_bf16 v[64:67], v[156:159], v[194:197], 0
	v_mfma_f32_16x16x32_bf16 v[10:13], v[152:155], v[172:175], v[10:13]
	v_mfma_f32_16x16x32_bf16 v[14:17], v[160:163], v[172:175], v[14:17]
	v_mfma_f32_16x16x32_bf16 v[26:29], v[152:155], v[176:179], v[26:29]
	v_mfma_f32_16x16x32_bf16 v[30:33], v[160:163], v[176:179], v[30:33]
	v_mfma_f32_16x16x32_bf16 v[44:47], v[152:155], v[198:201], v[44:47]
	v_mfma_f32_16x16x32_bf16 v[48:51], v[160:163], v[198:201], v[48:51]
	v_mfma_f32_16x16x32_bf16 v[60:63], v[152:155], v[232:235], v[60:63]
	v_mfma_f32_16x16x32_bf16 v[64:67], v[160:163], v[232:235], v[64:67]
	s_barrier
	s_setprio 0
	s_add_i32 s25, 0, 0x18000
	s_add_i32 s31, 0, 0x1c000
	ds_read_b128 v[132:135], v1 offset:32768
	ds_read_b128 v[136:139], v204 offset:32768
	ds_read_b128 v[140:143], v1 offset:34816
	ds_read_b128 v[144:147], v204 offset:34816
	ds_read_b128 v[148:151], v1 offset:49152
	ds_read_b128 v[152:155], v204 offset:49152
	ds_read_b128 v[156:159], v1 offset:51200
	ds_read_b128 v[160:163], v204 offset:51200
	s_add_u32 s34, s40, 0x80000
	s_addc_u32 s35, s41, 0
	s_mov_b32 m0, s52
	ds_read_b128 v[164:167], v205 offset:32768
	ds_read_b128 v[168:171], v205 offset:34816
	ds_read_b128 v[172:175], v206 offset:32768
	ds_read_b128 v[176:179], v206 offset:34816
	ds_read_b128 v[190:193], v205 offset:36864
	ds_read_b128 v[194:197], v205 offset:38912
	ds_read_b128 v[198:201], v206 offset:36864
	ds_read_b128 v[232:235], v206 offset:38912
	global_load_lds_dwordx4 v188, s[34:35]
	s_mov_b32 m0, s53
	s_nop 0
	global_load_lds_dwordx4 v186, s[34:35]
	s_waitcnt vmcnt(8)
	s_waitcnt lgkmcnt(0)
	s_setprio 1
	s_barrier
	v_mfma_f32_16x16x32_bf16 v[68:71], v[132:135], v[164:167], v[68:71]
	v_mfma_f32_16x16x32_bf16 v[72:75], v[140:143], v[164:167], v[72:75]
	v_mfma_f32_16x16x32_bf16 v[84:87], v[132:135], v[168:171], v[84:87]
	v_mfma_f32_16x16x32_bf16 v[88:91], v[140:143], v[168:171], v[88:91]
	v_mfma_f32_16x16x32_bf16 v[100:103], v[132:135], v[190:193], v[100:103]
	v_mfma_f32_16x16x32_bf16 v[104:107], v[140:143], v[190:193], v[104:107]
	v_mfma_f32_16x16x32_bf16 v[116:119], v[132:135], v[194:197], v[116:119]
	v_mfma_f32_16x16x32_bf16 v[120:123], v[140:143], v[194:197], v[120:123]
	v_mfma_f32_16x16x32_bf16 v[68:71], v[136:139], v[172:175], v[68:71]
	v_mfma_f32_16x16x32_bf16 v[72:75], v[144:147], v[172:175], v[72:75]
	v_mfma_f32_16x16x32_bf16 v[84:87], v[136:139], v[176:179], v[84:87]
	v_mfma_f32_16x16x32_bf16 v[88:91], v[144:147], v[176:179], v[88:91]
	v_mfma_f32_16x16x32_bf16 v[100:103], v[136:139], v[198:201], v[100:103]
	v_mfma_f32_16x16x32_bf16 v[104:107], v[144:147], v[198:201], v[104:107]
	v_mfma_f32_16x16x32_bf16 v[116:119], v[136:139], v[232:235], v[116:119]
	v_mfma_f32_16x16x32_bf16 v[120:123], v[144:147], v[232:235], v[120:123]
	s_setprio 0
	s_setprio 1
	v_mfma_f32_16x16x32_bf16 v[76:79], v[148:151], v[164:167], v[76:79]
	v_mfma_f32_16x16x32_bf16 v[80:83], v[156:159], v[164:167], v[80:83]
	v_mfma_f32_16x16x32_bf16 v[92:95], v[148:151], v[168:171], v[92:95]
	v_mfma_f32_16x16x32_bf16 v[96:99], v[156:159], v[168:171], v[96:99]
	v_mfma_f32_16x16x32_bf16 v[108:111], v[148:151], v[190:193], v[108:111]
	v_mfma_f32_16x16x32_bf16 v[112:115], v[156:159], v[190:193], v[112:115]
	v_mfma_f32_16x16x32_bf16 v[124:127], v[148:151], v[194:197], v[124:127]
	v_mfma_f32_16x16x32_bf16 v[128:131], v[156:159], v[194:197], v[128:131]
	v_mfma_f32_16x16x32_bf16 v[76:79], v[152:155], v[172:175], v[76:79]
	v_mfma_f32_16x16x32_bf16 v[80:83], v[160:163], v[172:175], v[80:83]
	v_mfma_f32_16x16x32_bf16 v[92:95], v[152:155], v[176:179], v[92:95]
	v_mfma_f32_16x16x32_bf16 v[96:99], v[160:163], v[176:179], v[96:99]
	v_mfma_f32_16x16x32_bf16 v[108:111], v[152:155], v[198:201], v[108:111]
	v_mfma_f32_16x16x32_bf16 v[112:115], v[160:163], v[198:201], v[112:115]
	v_mfma_f32_16x16x32_bf16 v[124:127], v[152:155], v[232:235], v[124:127]
	v_mfma_f32_16x16x32_bf16 v[128:131], v[160:163], v[232:235], v[128:131]
	s_barrier
	s_setprio 0
	s_add_i32 s25, s25, s33
	s_add_i32 m0, s25, 0xffffff80
	ds_read_b128 v[164:167], v205 offset:49152
	ds_read_b128 v[168:171], v205 offset:51200
	ds_read_b128 v[172:175], v206 offset:49152
	ds_read_b128 v[176:179], v206 offset:51200
	ds_read_b128 v[190:193], v205 offset:53248
	ds_read_b128 v[194:197], v205 offset:55296
	ds_read_b128 v[198:201], v206 offset:53248
	ds_read_b128 v[232:235], v206 offset:55296
	global_load_lds_dwordx4 v34, s[28:29] offset:128
	s_add_i32 m0, s25, 0x1f80
	s_mov_b64 s[98:99], s[28:29]
	s_add_u32 s28, s28, 0x80080
	s_addc_u32 s29, s29, 0
	s_add_i32 s25, s31, s33
	global_load_lds_dwordx4 v184, s[98:99] offset:128
	s_mov_b32 m0, s25
	s_nop 0
	global_load_lds_dwordx4 v34, s[28:29]
	s_add_i32 m0, s25, 0x2000
	s_nop 0
	global_load_lds_dwordx4 v184, s[28:29]
	s_add_i32 m0, s54, 0xffffff80
	s_nop 0
	global_load_lds_dwordx4 v188, s[40:41] offset:128
	s_add_i32 m0, s55, 0xffffff80
	s_nop 0
	global_load_lds_dwordx4 v186, s[40:41] offset:128
	s_waitcnt vmcnt(8)
	s_waitcnt lgkmcnt(0)
	s_setprio 1
	s_barrier
	v_mfma_f32_16x16x32_bf16 v[2:5], v[132:135], v[164:167], v[2:5]
	v_mfma_f32_16x16x32_bf16 v[6:9], v[140:143], v[164:167], v[6:9]
	v_mfma_f32_16x16x32_bf16 v[18:21], v[132:135], v[168:171], v[18:21]
	v_mfma_f32_16x16x32_bf16 v[22:25], v[140:143], v[168:171], v[22:25]
	v_mfma_f32_16x16x32_bf16 v[36:39], v[132:135], v[190:193], v[36:39]
	v_mfma_f32_16x16x32_bf16 v[40:43], v[140:143], v[190:193], v[40:43]
	v_mfma_f32_16x16x32_bf16 v[52:55], v[132:135], v[194:197], v[52:55]
	v_mfma_f32_16x16x32_bf16 v[56:59], v[140:143], v[194:197], v[56:59]
	v_mfma_f32_16x16x32_bf16 v[2:5], v[136:139], v[172:175], v[2:5]
	v_mfma_f32_16x16x32_bf16 v[6:9], v[144:147], v[172:175], v[6:9]
	v_mfma_f32_16x16x32_bf16 v[18:21], v[136:139], v[176:179], v[18:21]
	v_mfma_f32_16x16x32_bf16 v[22:25], v[144:147], v[176:179], v[22:25]
	v_mfma_f32_16x16x32_bf16 v[36:39], v[136:139], v[198:201], v[36:39]
	v_mfma_f32_16x16x32_bf16 v[40:43], v[144:147], v[198:201], v[40:43]
	v_mfma_f32_16x16x32_bf16 v[52:55], v[136:139], v[232:235], v[52:55]
	v_mfma_f32_16x16x32_bf16 v[56:59], v[144:147], v[232:235], v[56:59]
	s_setprio 0
	s_setprio 1
	v_mfma_f32_16x16x32_bf16 v[10:13], v[148:151], v[164:167], v[10:13]
	v_mfma_f32_16x16x32_bf16 v[14:17], v[156:159], v[164:167], v[14:17]
	v_mfma_f32_16x16x32_bf16 v[26:29], v[148:151], v[168:171], v[26:29]
	v_mfma_f32_16x16x32_bf16 v[30:33], v[156:159], v[168:171], v[30:33]
	v_mfma_f32_16x16x32_bf16 v[44:47], v[148:151], v[190:193], v[44:47]
	v_mfma_f32_16x16x32_bf16 v[48:51], v[156:159], v[190:193], v[48:51]
	v_mfma_f32_16x16x32_bf16 v[60:63], v[148:151], v[194:197], v[60:63]
	v_mfma_f32_16x16x32_bf16 v[64:67], v[156:159], v[194:197], v[64:67]
	v_mfma_f32_16x16x32_bf16 v[10:13], v[152:155], v[172:175], v[10:13]
	v_mfma_f32_16x16x32_bf16 v[14:17], v[160:163], v[172:175], v[14:17]
	v_mfma_f32_16x16x32_bf16 v[26:29], v[152:155], v[176:179], v[26:29]
	v_mfma_f32_16x16x32_bf16 v[30:33], v[160:163], v[176:179], v[30:33]
	v_mfma_f32_16x16x32_bf16 v[44:47], v[152:155], v[198:201], v[44:47]
	v_mfma_f32_16x16x32_bf16 v[48:51], v[160:163], v[198:201], v[48:51]
	v_mfma_f32_16x16x32_bf16 v[60:63], v[152:155], v[232:235], v[60:63]
	v_mfma_f32_16x16x32_bf16 v[64:67], v[160:163], v[232:235], v[64:67]
	s_barrier
	s_setprio 0
	s_add_u32 s22, s22, 0x100
	s_addc_u32 s23, s23, 0
	s_add_u32 s21, s21, 0x100
	s_addc_u32 s24, s24, 0
	s_cmp_ge_u32 s30, s9
	s_mov_b32 s25, s30
	s_cbranch_scc1 .Lpeel_done_P3
.LBB0_908:
	s_add_i32 s30, s25, 2
	s_add_u32 s28, s22, 0xfff80080
	s_addc_u32 s29, s23, -1
	s_add_i32 s31, 0, 0x10000
	s_cmp_eq_u32 s20, s25
	s_cselect_b32 s41, s47, s29
	s_cselect_b32 s40, s46, s28
	s_cselect_b32 s29, s49, s24
	s_cselect_b32 s28, s48, s21
	s_add_i32 s25, 0, 0x14000
	ds_read_b128 v[132:135], v1
	ds_read_b128 v[136:139], v204
	ds_read_b128 v[140:143], v1 offset:2048
	ds_read_b128 v[144:147], v204 offset:2048
	ds_read_b128 v[148:151], v1 offset:16384
	ds_read_b128 v[152:155], v204 offset:16384
	ds_read_b128 v[156:159], v1 offset:18432
	ds_read_b128 v[160:163], v204 offset:18432
	s_add_i32 m0, s50, 0xc000
	ds_read_b128 v[164:167], v205
	ds_read_b128 v[168:171], v205 offset:2048
	ds_read_b128 v[172:175], v206
	ds_read_b128 v[176:179], v206 offset:2048
	ds_read_b128 v[190:193], v205 offset:4096
	ds_read_b128 v[194:197], v205 offset:6144
	ds_read_b128 v[198:201], v206 offset:4096
	ds_read_b128 v[232:235], v206 offset:6144
	global_load_lds_dwordx4 v188, s[22:23]
	s_add_i32 m0, s50, 0xe000
	s_nop 0
	global_load_lds_dwordx4 v186, s[22:23]
	s_waitcnt vmcnt(8)
	s_waitcnt lgkmcnt(0)
	s_setprio 1
	s_barrier
	v_mfma_f32_16x16x32_bf16 v[68:71], v[132:135], v[164:167], v[68:71]
	v_mfma_f32_16x16x32_bf16 v[72:75], v[140:143], v[164:167], v[72:75]
	v_mfma_f32_16x16x32_bf16 v[84:87], v[132:135], v[168:171], v[84:87]
	v_mfma_f32_16x16x32_bf16 v[88:91], v[140:143], v[168:171], v[88:91]
	v_mfma_f32_16x16x32_bf16 v[100:103], v[132:135], v[190:193], v[100:103]
	v_mfma_f32_16x16x32_bf16 v[104:107], v[140:143], v[190:193], v[104:107]
	v_mfma_f32_16x16x32_bf16 v[116:119], v[132:135], v[194:197], v[116:119]
	v_mfma_f32_16x16x32_bf16 v[120:123], v[140:143], v[194:197], v[120:123]
	v_mfma_f32_16x16x32_bf16 v[68:71], v[136:139], v[172:175], v[68:71]
	v_mfma_f32_16x16x32_bf16 v[72:75], v[144:147], v[172:175], v[72:75]
	v_mfma_f32_16x16x32_bf16 v[84:87], v[136:139], v[176:179], v[84:87]
	v_mfma_f32_16x16x32_bf16 v[88:91], v[144:147], v[176:179], v[88:91]
	v_mfma_f32_16x16x32_bf16 v[100:103], v[136:139], v[198:201], v[100:103]
	v_mfma_f32_16x16x32_bf16 v[104:107], v[144:147], v[198:201], v[104:107]
	v_mfma_f32_16x16x32_bf16 v[116:119], v[136:139], v[232:235], v[116:119]
	v_mfma_f32_16x16x32_bf16 v[120:123], v[144:147], v[232:235], v[120:123]
	s_setprio 0
	s_setprio 1
	v_mfma_f32_16x16x32_bf16 v[76:79], v[148:151], v[164:167], v[76:79]
	v_mfma_f32_16x16x32_bf16 v[80:83], v[156:159], v[164:167], v[80:83]
	v_mfma_f32_16x16x32_bf16 v[92:95], v[148:151], v[168:171], v[92:95]
	v_mfma_f32_16x16x32_bf16 v[96:99], v[156:159], v[168:171], v[96:99]
	v_mfma_f32_16x16x32_bf16 v[108:111], v[148:151], v[190:193], v[108:111]
	v_mfma_f32_16x16x32_bf16 v[112:115], v[156:159], v[190:193], v[112:115]
	v_mfma_f32_16x16x32_bf16 v[124:127], v[148:151], v[194:197], v[124:127]
	v_mfma_f32_16x16x32_bf16 v[128:131], v[156:159], v[194:197], v[128:131]
	v_mfma_f32_16x16x32_bf16 v[76:79], v[152:155], v[172:175], v[76:79]
	v_mfma_f32_16x16x32_bf16 v[80:83], v[160:163], v[172:175], v[80:83]
	v_mfma_f32_16x16x32_bf16 v[92:95], v[152:155], v[176:179], v[92:95]
	v_mfma_f32_16x16x32_bf16 v[96:99], v[160:163], v[176:179], v[96:99]
	v_mfma_f32_16x16x32_bf16 v[108:111], v[152:155], v[198:201], v[108:111]
	v_mfma_f32_16x16x32_bf16 v[112:115], v[160:163], v[198:201], v[112:115]
	v_mfma_f32_16x16x32_bf16 v[124:127], v[152:155], v[232:235], v[124:127]
	v_mfma_f32_16x16x32_bf16 v[128:131], v[160:163], v[232:235], v[128:131]
	s_barrier
	s_setprio 0
	s_add_i32 s31, s31, s33
	s_mov_b32 m0, s31
	ds_read_b128 v[164:167], v205 offset:16384
	ds_read_b128 v[168:171], v205 offset:18432
	ds_read_b128 v[172:175], v206 offset:16384
	ds_read_b128 v[176:179], v206 offset:18432
	ds_read_b128 v[190:193], v205 offset:20480
	ds_read_b128 v[194:197], v205 offset:22528
	ds_read_b128 v[198:201], v206 offset:20480
	ds_read_b128 v[232:235], v206 offset:22528
	global_load_lds_dwordx4 v34, s[28:29]
	s_add_i32 m0, s31, 0x2000
	s_add_u32 s34, s28, 0x80000
	s_addc_u32 s35, s29, 0
	s_add_i32 s25, s25, s33
	global_load_lds_dwordx4 v184, s[28:29]
	s_mov_b32 m0, s25
	s_nop 0
	global_load_lds_dwordx4 v34, s[34:35]
	s_add_i32 m0, s25, 0x2000
	s_nop 0
	global_load_lds_dwordx4 v184, s[34:35]
	s_mov_b32 m0, s50
	s_nop 0
	global_load_lds_dwordx4 v188, s[40:41]
	s_mov_b32 m0, s51
	s_nop 0
	global_load_lds_dwordx4 v186, s[40:41]
	s_waitcnt vmcnt(8)
	s_waitcnt lgkmcnt(0)
	s_setprio 1
	s_barrier
	v_mfma_f32_16x16x32_bf16 v[2:5], v[132:135], v[164:167], v[2:5]
	v_mfma_f32_16x16x32_bf16 v[6:9], v[140:143], v[164:167], v[6:9]
	v_mfma_f32_16x16x32_bf16 v[18:21], v[132:135], v[168:171], v[18:21]
	v_mfma_f32_16x16x32_bf16 v[22:25], v[140:143], v[168:171], v[22:25]
	v_mfma_f32_16x16x32_bf16 v[36:39], v[132:135], v[190:193], v[36:39]
	v_mfma_f32_16x16x32_bf16 v[40:43], v[140:143], v[190:193], v[40:43]
	v_mfma_f32_16x16x32_bf16 v[52:55], v[132:135], v[194:197], v[52:55]
	v_mfma_f32_16x16x32_bf16 v[56:59], v[140:143], v[194:197], v[56:59]
	v_mfma_f32_16x16x32_bf16 v[2:5], v[136:139], v[172:175], v[2:5]
	v_mfma_f32_16x16x32_bf16 v[6:9], v[144:147], v[172:175], v[6:9]
	v_mfma_f32_16x16x32_bf16 v[18:21], v[136:139], v[176:179], v[18:21]
	v_mfma_f32_16x16x32_bf16 v[22:25], v[144:147], v[176:179], v[22:25]
	v_mfma_f32_16x16x32_bf16 v[36:39], v[136:139], v[198:201], v[36:39]
	v_mfma_f32_16x16x32_bf16 v[40:43], v[144:147], v[198:201], v[40:43]
	v_mfma_f32_16x16x32_bf16 v[52:55], v[136:139], v[232:235], v[52:55]
	v_mfma_f32_16x16x32_bf16 v[56:59], v[144:147], v[232:235], v[56:59]
	s_setprio 0
	s_setprio 1
	v_mfma_f32_16x16x32_bf16 v[10:13], v[148:151], v[164:167], v[10:13]
	v_mfma_f32_16x16x32_bf16 v[14:17], v[156:159], v[164:167], v[14:17]
	v_mfma_f32_16x16x32_bf16 v[26:29], v[148:151], v[168:171], v[26:29]
	v_mfma_f32_16x16x32_bf16 v[30:33], v[156:159], v[168:171], v[30:33]
	v_mfma_f32_16x16x32_bf16 v[44:47], v[148:151], v[190:193], v[44:47]
	v_mfma_f32_16x16x32_bf16 v[48:51], v[156:159], v[190:193], v[48:51]
	v_mfma_f32_16x16x32_bf16 v[60:63], v[148:151], v[194:197], v[60:63]
	v_mfma_f32_16x16x32_bf16 v[64:67], v[156:159], v[194:197], v[64:67]
	v_mfma_f32_16x16x32_bf16 v[10:13], v[152:155], v[172:175], v[10:13]
	v_mfma_f32_16x16x32_bf16 v[14:17], v[160:163], v[172:175], v[14:17]
	v_mfma_f32_16x16x32_bf16 v[26:29], v[152:155], v[176:179], v[26:29]
	v_mfma_f32_16x16x32_bf16 v[30:33], v[160:163], v[176:179], v[30:33]
	v_mfma_f32_16x16x32_bf16 v[44:47], v[152:155], v[198:201], v[44:47]
	v_mfma_f32_16x16x32_bf16 v[48:51], v[160:163], v[198:201], v[48:51]
	v_mfma_f32_16x16x32_bf16 v[60:63], v[152:155], v[232:235], v[60:63]
	v_mfma_f32_16x16x32_bf16 v[64:67], v[160:163], v[232:235], v[64:67]
	s_barrier
	s_setprio 0
	s_add_i32 s25, 0, 0x18000
	s_add_i32 s31, 0, 0x1c000
	ds_read_b128 v[132:135], v1 offset:32768
	ds_read_b128 v[136:139], v204 offset:32768
	ds_read_b128 v[140:143], v1 offset:34816
	ds_read_b128 v[144:147], v204 offset:34816
	ds_read_b128 v[148:151], v1 offset:49152
	ds_read_b128 v[152:155], v204 offset:49152
	ds_read_b128 v[156:159], v1 offset:51200
	ds_read_b128 v[160:163], v204 offset:51200
	s_add_u32 s34, s40, 0x80000
	s_addc_u32 s35, s41, 0
	s_mov_b32 m0, s52
	ds_read_b128 v[164:167], v205 offset:32768
	ds_read_b128 v[168:171], v205 offset:34816
	ds_read_b128 v[172:175], v206 offset:32768
	ds_read_b128 v[176:179], v206 offset:34816
	ds_read_b128 v[190:193], v205 offset:36864
	ds_read_b128 v[194:197], v205 offset:38912
	ds_read_b128 v[198:201], v206 offset:36864
	ds_read_b128 v[232:235], v206 offset:38912
	global_load_lds_dwordx4 v188, s[34:35]
	s_mov_b32 m0, s53
	s_nop 0
	global_load_lds_dwordx4 v186, s[34:35]
	s_waitcnt vmcnt(8)
	s_waitcnt lgkmcnt(0)
	s_setprio 1
	s_barrier
	v_mfma_f32_16x16x32_bf16 v[68:71], v[132:135], v[164:167], v[68:71]
	v_mfma_f32_16x16x32_bf16 v[72:75], v[140:143], v[164:167], v[72:75]
	v_mfma_f32_16x16x32_bf16 v[84:87], v[132:135], v[168:171], v[84:87]
	v_mfma_f32_16x16x32_bf16 v[88:91], v[140:143], v[168:171], v[88:91]
	v_mfma_f32_16x16x32_bf16 v[100:103], v[132:135], v[190:193], v[100:103]
	v_mfma_f32_16x16x32_bf16 v[104:107], v[140:143], v[190:193], v[104:107]
	v_mfma_f32_16x16x32_bf16 v[116:119], v[132:135], v[194:197], v[116:119]
	v_mfma_f32_16x16x32_bf16 v[120:123], v[140:143], v[194:197], v[120:123]
	v_mfma_f32_16x16x32_bf16 v[68:71], v[136:139], v[172:175], v[68:71]
	v_mfma_f32_16x16x32_bf16 v[72:75], v[144:147], v[172:175], v[72:75]
	v_mfma_f32_16x16x32_bf16 v[84:87], v[136:139], v[176:179], v[84:87]
	v_mfma_f32_16x16x32_bf16 v[88:91], v[144:147], v[176:179], v[88:91]
	v_mfma_f32_16x16x32_bf16 v[100:103], v[136:139], v[198:201], v[100:103]
	v_mfma_f32_16x16x32_bf16 v[104:107], v[144:147], v[198:201], v[104:107]
	v_mfma_f32_16x16x32_bf16 v[116:119], v[136:139], v[232:235], v[116:119]
	v_mfma_f32_16x16x32_bf16 v[120:123], v[144:147], v[232:235], v[120:123]
	s_setprio 0
	s_setprio 1
	v_mfma_f32_16x16x32_bf16 v[76:79], v[148:151], v[164:167], v[76:79]
	v_mfma_f32_16x16x32_bf16 v[80:83], v[156:159], v[164:167], v[80:83]
	v_mfma_f32_16x16x32_bf16 v[92:95], v[148:151], v[168:171], v[92:95]
	v_mfma_f32_16x16x32_bf16 v[96:99], v[156:159], v[168:171], v[96:99]
	v_mfma_f32_16x16x32_bf16 v[108:111], v[148:151], v[190:193], v[108:111]
	v_mfma_f32_16x16x32_bf16 v[112:115], v[156:159], v[190:193], v[112:115]
	v_mfma_f32_16x16x32_bf16 v[124:127], v[148:151], v[194:197], v[124:127]
	v_mfma_f32_16x16x32_bf16 v[128:131], v[156:159], v[194:197], v[128:131]
	v_mfma_f32_16x16x32_bf16 v[76:79], v[152:155], v[172:175], v[76:79]
	v_mfma_f32_16x16x32_bf16 v[80:83], v[160:163], v[172:175], v[80:83]
	v_mfma_f32_16x16x32_bf16 v[92:95], v[152:155], v[176:179], v[92:95]
	v_mfma_f32_16x16x32_bf16 v[96:99], v[160:163], v[176:179], v[96:99]
	v_mfma_f32_16x16x32_bf16 v[108:111], v[152:155], v[198:201], v[108:111]
	v_mfma_f32_16x16x32_bf16 v[112:115], v[160:163], v[198:201], v[112:115]
	v_mfma_f32_16x16x32_bf16 v[124:127], v[152:155], v[232:235], v[124:127]
	v_mfma_f32_16x16x32_bf16 v[128:131], v[160:163], v[232:235], v[128:131]
	s_barrier
	s_setprio 0
	s_add_i32 s25, s25, s33
	s_add_i32 m0, s25, 0xffffff80
	ds_read_b128 v[164:167], v205 offset:49152
	ds_read_b128 v[168:171], v205 offset:51200
	ds_read_b128 v[172:175], v206 offset:49152
	ds_read_b128 v[176:179], v206 offset:51200
	ds_read_b128 v[190:193], v205 offset:53248
	ds_read_b128 v[194:197], v205 offset:55296
	ds_read_b128 v[198:201], v206 offset:53248
	ds_read_b128 v[232:235], v206 offset:55296
	global_load_lds_dwordx4 v34, s[28:29] offset:128
	s_add_i32 m0, s25, 0x1f80
	s_mov_b64 s[98:99], s[28:29]
	s_add_u32 s28, s28, 0x80080
	s_addc_u32 s29, s29, 0
	s_add_i32 s25, s31, s33
	global_load_lds_dwordx4 v184, s[98:99] offset:128
	s_mov_b32 m0, s25
	s_nop 0
	global_load_lds_dwordx4 v34, s[28:29]
	s_add_i32 m0, s25, 0x2000
	s_nop 0
	global_load_lds_dwordx4 v184, s[28:29]
	s_add_i32 m0, s54, 0xffffff80
	s_nop 0
	global_load_lds_dwordx4 v188, s[40:41] offset:128
	s_add_i32 m0, s55, 0xffffff80
	s_nop 0
	global_load_lds_dwordx4 v186, s[40:41] offset:128
	s_waitcnt vmcnt(8)
	s_waitcnt lgkmcnt(0)
	s_setprio 1
	s_barrier
	v_mfma_f32_16x16x32_bf16 v[2:5], v[132:135], v[164:167], v[2:5]
	v_mfma_f32_16x16x32_bf16 v[6:9], v[140:143], v[164:167], v[6:9]
	v_mfma_f32_16x16x32_bf16 v[18:21], v[132:135], v[168:171], v[18:21]
	v_mfma_f32_16x16x32_bf16 v[22:25], v[140:143], v[168:171], v[22:25]
	v_mfma_f32_16x16x32_bf16 v[36:39], v[132:135], v[190:193], v[36:39]
	v_mfma_f32_16x16x32_bf16 v[40:43], v[140:143], v[190:193], v[40:43]
	v_mfma_f32_16x16x32_bf16 v[52:55], v[132:135], v[194:197], v[52:55]
	v_mfma_f32_16x16x32_bf16 v[56:59], v[140:143], v[194:197], v[56:59]
	v_mfma_f32_16x16x32_bf16 v[2:5], v[136:139], v[172:175], v[2:5]
	v_mfma_f32_16x16x32_bf16 v[6:9], v[144:147], v[172:175], v[6:9]
	v_mfma_f32_16x16x32_bf16 v[18:21], v[136:139], v[176:179], v[18:21]
	v_mfma_f32_16x16x32_bf16 v[22:25], v[144:147], v[176:179], v[22:25]
	v_mfma_f32_16x16x32_bf16 v[36:39], v[136:139], v[198:201], v[36:39]
	v_mfma_f32_16x16x32_bf16 v[40:43], v[144:147], v[198:201], v[40:43]
	v_mfma_f32_16x16x32_bf16 v[52:55], v[136:139], v[232:235], v[52:55]
	v_mfma_f32_16x16x32_bf16 v[56:59], v[144:147], v[232:235], v[56:59]
	s_setprio 0
	s_setprio 1
	v_mfma_f32_16x16x32_bf16 v[10:13], v[148:151], v[164:167], v[10:13]
	v_mfma_f32_16x16x32_bf16 v[14:17], v[156:159], v[164:167], v[14:17]
	v_mfma_f32_16x16x32_bf16 v[26:29], v[148:151], v[168:171], v[26:29]
	v_mfma_f32_16x16x32_bf16 v[30:33], v[156:159], v[168:171], v[30:33]
	v_mfma_f32_16x16x32_bf16 v[44:47], v[148:151], v[190:193], v[44:47]
	v_mfma_f32_16x16x32_bf16 v[48:51], v[156:159], v[190:193], v[48:51]
	v_mfma_f32_16x16x32_bf16 v[60:63], v[148:151], v[194:197], v[60:63]
	v_mfma_f32_16x16x32_bf16 v[64:67], v[156:159], v[194:197], v[64:67]
	v_mfma_f32_16x16x32_bf16 v[10:13], v[152:155], v[172:175], v[10:13]
	v_mfma_f32_16x16x32_bf16 v[14:17], v[160:163], v[172:175], v[14:17]
	v_mfma_f32_16x16x32_bf16 v[26:29], v[152:155], v[176:179], v[26:29]
	v_mfma_f32_16x16x32_bf16 v[30:33], v[160:163], v[176:179], v[30:33]
	v_mfma_f32_16x16x32_bf16 v[44:47], v[152:155], v[198:201], v[44:47]
	v_mfma_f32_16x16x32_bf16 v[48:51], v[160:163], v[198:201], v[48:51]
	v_mfma_f32_16x16x32_bf16 v[60:63], v[152:155], v[232:235], v[60:63]
	v_mfma_f32_16x16x32_bf16 v[64:67], v[160:163], v[232:235], v[64:67]
	s_barrier
	s_setprio 0
	s_add_u32 s22, s22, 0x100
	s_addc_u32 s23, s23, 0
	s_add_u32 s21, s21, 0x100
	s_addc_u32 s24, s24, 0
	s_cmp_ge_u32 s30, s9
	s_mov_b32 s25, s30
	s_cbranch_scc0 .LBB0_908

.LBB0_1022:
	s_ashr_i32 s23, s22, 31
	s_lshl_b64 s[12:13], s[22:23], 20
	v_readlane_b32 s20, v254, 52
	v_readlane_b32 s21, v254, 53
	s_add_u32 s40, s20, s12
	s_addc_u32 s41, s21, s13
	s_and_b64 s[12:13], s[38:39], exec
	s_cselect_b32 s12, s41, s9
	s_cselect_b32 s13, s40, s8
	s_ashr_i32 s19, s18, 31
	s_lshl_b64 s[20:21], s[18:19], 20
	v_readlane_b32 s24, v254, 48
	v_readlane_b32 s25, v254, 49
	s_add_u32 s42, s24, s20
	s_addc_u32 s43, s25, s21
	s_and_b64 s[20:21], s[38:39], exec
	s_cselect_b32 s19, s43, s29
	s_cselect_b32 s20, s42, s28
	s_add_u32 s8, s8, 0x80080
	s_addc_u32 s9, s9, 0
	s_add_u32 s21, s28, 0x100
	s_addc_u32 s23, s29, 0
	s_mov_b32 s24, -2
	v_readlane_b32 s35, v255, 20
	v_readlane_b32 s57, v255, 21
	v_readlane_b32 s58, v255, 22
	v_readlane_b32 s59, v255, 23
	s_mov_b64 s[60:61], 0x80
	s_add_u32 s25, s8, 0xfff80080
	s_addc_u32 s28, s9, -1
	s_add_i32 s30, 0, 0x10000
	s_cmp_eq_u32 s24, 28
	s_cselect_b32 s45, s12, s28
	s_cselect_b32 s44, s13, s25
	s_cselect_b32 s29, s19, s23
	s_cselect_b32 s28, s20, s21
	s_add_i32 s25, 0, 0x14000
	ds_read_b128 v[138:141], v1
	ds_read_b128 v[142:145], v150
	ds_read_b128 v[146:149], v1 offset:2048
	ds_read_b128 v[154:157], v150 offset:2048
	ds_read_b128 v[158:161], v1 offset:16384
	ds_read_b128 v[162:165], v150 offset:16384
	ds_read_b128 v[166:169], v1 offset:18432
	ds_read_b128 v[170:173], v150 offset:18432
	s_add_i32 m0, s46, 0xc000
	ds_read_b128 v[174:177], v151
	ds_read_b128 v[184:187], v151 offset:2048
	ds_read_b128 v[188:191], v152
	ds_read_b128 v[192:195], v152 offset:2048
	ds_read_b128 v[196:199], v151 offset:4096
	ds_read_b128 v[200:203], v151 offset:6144
	ds_read_b128 v[204:207], v152 offset:4096
	ds_read_b128 v[208:211], v152 offset:6144
	global_load_lds_dwordx4 v136, s[8:9]
	s_add_i32 m0, s46, 0xe000
	s_nop 0
	global_load_lds_dwordx4 v134, s[8:9]
	s_waitcnt vmcnt(8)
	s_waitcnt lgkmcnt(0)
	s_setprio 1
	s_barrier
	v_mfma_f32_16x16x32_bf16 v[128:131], v[138:141], v[174:177], 0
	v_mfma_f32_16x16x32_bf16 v[124:127], v[146:149], v[174:177], 0
	v_mfma_f32_16x16x32_bf16 v[112:115], v[138:141], v[184:187], 0
	v_mfma_f32_16x16x32_bf16 v[108:111], v[146:149], v[184:187], 0
	v_mfma_f32_16x16x32_bf16 v[96:99], v[138:141], v[196:199], 0
	v_mfma_f32_16x16x32_bf16 v[92:95], v[146:149], v[196:199], 0
	v_mfma_f32_16x16x32_bf16 v[80:83], v[138:141], v[200:203], 0
	v_mfma_f32_16x16x32_bf16 v[76:79], v[146:149], v[200:203], 0
	v_mfma_f32_16x16x32_bf16 v[128:131], v[142:145], v[188:191], v[128:131]
	v_mfma_f32_16x16x32_bf16 v[124:127], v[154:157], v[188:191], v[124:127]
	v_mfma_f32_16x16x32_bf16 v[112:115], v[142:145], v[192:195], v[112:115]
	v_mfma_f32_16x16x32_bf16 v[108:111], v[154:157], v[192:195], v[108:111]
	v_mfma_f32_16x16x32_bf16 v[96:99], v[142:145], v[204:207], v[96:99]
	v_mfma_f32_16x16x32_bf16 v[92:95], v[154:157], v[204:207], v[92:95]
	v_mfma_f32_16x16x32_bf16 v[80:83], v[142:145], v[208:211], v[80:83]
	v_mfma_f32_16x16x32_bf16 v[76:79], v[154:157], v[208:211], v[76:79]
	s_setprio 0
	s_setprio 1
	v_mfma_f32_16x16x32_bf16 v[120:123], v[158:161], v[174:177], 0
	v_mfma_f32_16x16x32_bf16 v[116:119], v[166:169], v[174:177], 0
	v_mfma_f32_16x16x32_bf16 v[104:107], v[158:161], v[184:187], 0
	v_mfma_f32_16x16x32_bf16 v[100:103], v[166:169], v[184:187], 0
	v_mfma_f32_16x16x32_bf16 v[88:91], v[158:161], v[196:199], 0
	v_mfma_f32_16x16x32_bf16 v[84:87], v[166:169], v[196:199], 0
	v_mfma_f32_16x16x32_bf16 v[72:75], v[158:161], v[200:203], 0
	v_mfma_f32_16x16x32_bf16 v[68:71], v[166:169], v[200:203], 0
	v_mfma_f32_16x16x32_bf16 v[120:123], v[162:165], v[188:191], v[120:123]
	v_mfma_f32_16x16x32_bf16 v[116:119], v[170:173], v[188:191], v[116:119]
	v_mfma_f32_16x16x32_bf16 v[104:107], v[162:165], v[192:195], v[104:107]
	v_mfma_f32_16x16x32_bf16 v[100:103], v[170:173], v[192:195], v[100:103]
	v_mfma_f32_16x16x32_bf16 v[88:91], v[162:165], v[204:207], v[88:91]
	v_mfma_f32_16x16x32_bf16 v[84:87], v[170:173], v[204:207], v[84:87]
	v_mfma_f32_16x16x32_bf16 v[72:75], v[162:165], v[208:211], v[72:75]
	v_mfma_f32_16x16x32_bf16 v[68:71], v[170:173], v[208:211], v[68:71]
	s_barrier
	s_setprio 0
	s_add_i32 s30, s30, s33
	s_mov_b32 m0, s30
	ds_read_b128 v[174:177], v151 offset:16384
	ds_read_b128 v[184:187], v151 offset:18432
	ds_read_b128 v[188:191], v152 offset:16384
	ds_read_b128 v[192:195], v152 offset:18432
	ds_read_b128 v[196:199], v151 offset:20480
	ds_read_b128 v[200:203], v151 offset:22528
	ds_read_b128 v[204:207], v152 offset:20480
	ds_read_b128 v[208:211], v152 offset:22528
	global_load_lds_dwordx4 v34, s[28:29]
	s_add_i32 m0, s30, 0x2000
	s_add_u32 s30, s28, 0x80000
	s_addc_u32 s31, s29, 0
	s_add_i32 s25, s25, s33
	global_load_lds_dwordx4 v132, s[28:29]
	s_mov_b32 m0, s25
	s_nop 0
	global_load_lds_dwordx4 v34, s[30:31]
	s_add_i32 m0, s25, 0x2000
	s_nop 0
	global_load_lds_dwordx4 v132, s[30:31]
	s_mov_b32 m0, s46
	s_nop 0
	global_load_lds_dwordx4 v136, s[44:45]
	s_mov_b32 m0, s47
	s_nop 0
	global_load_lds_dwordx4 v134, s[44:45]
	s_waitcnt vmcnt(8)
	s_waitcnt lgkmcnt(0)
	s_setprio 1
	s_barrier
	v_mfma_f32_16x16x32_bf16 v[64:67], v[138:141], v[174:177], 0
	v_mfma_f32_16x16x32_bf16 v[60:63], v[146:149], v[174:177], 0
	v_mfma_f32_16x16x32_bf16 v[48:51], v[138:141], v[184:187], 0
	v_mfma_f32_16x16x32_bf16 v[44:47], v[146:149], v[184:187], 0
	v_mfma_f32_16x16x32_bf16 v[30:33], v[138:141], v[196:199], 0
	v_mfma_f32_16x16x32_bf16 v[26:29], v[146:149], v[196:199], 0
	v_mfma_f32_16x16x32_bf16 v[14:17], v[138:141], v[200:203], 0
	v_mfma_f32_16x16x32_bf16 v[10:13], v[146:149], v[200:203], 0
	v_mfma_f32_16x16x32_bf16 v[64:67], v[142:145], v[188:191], v[64:67]
	v_mfma_f32_16x16x32_bf16 v[60:63], v[154:157], v[188:191], v[60:63]
	v_mfma_f32_16x16x32_bf16 v[48:51], v[142:145], v[192:195], v[48:51]
	v_mfma_f32_16x16x32_bf16 v[44:47], v[154:157], v[192:195], v[44:47]
	v_mfma_f32_16x16x32_bf16 v[30:33], v[142:145], v[204:207], v[30:33]
	v_mfma_f32_16x16x32_bf16 v[26:29], v[154:157], v[204:207], v[26:29]
	v_mfma_f32_16x16x32_bf16 v[14:17], v[142:145], v[208:211], v[14:17]
	v_mfma_f32_16x16x32_bf16 v[10:13], v[154:157], v[208:211], v[10:13]
	s_setprio 0
	s_setprio 1
	v_mfma_f32_16x16x32_bf16 v[56:59], v[158:161], v[174:177], 0
	v_mfma_f32_16x16x32_bf16 v[52:55], v[166:169], v[174:177], 0
	v_mfma_f32_16x16x32_bf16 v[40:43], v[158:161], v[184:187], 0
	v_mfma_f32_16x16x32_bf16 v[36:39], v[166:169], v[184:187], 0
	v_mfma_f32_16x16x32_bf16 v[22:25], v[158:161], v[196:199], 0
	v_mfma_f32_16x16x32_bf16 v[18:21], v[166:169], v[196:199], 0
	v_mfma_f32_16x16x32_bf16 v[6:9], v[158:161], v[200:203], 0
	v_mfma_f32_16x16x32_bf16 v[2:5], v[166:169], v[200:203], 0
	v_mfma_f32_16x16x32_bf16 v[56:59], v[162:165], v[188:191], v[56:59]
	v_mfma_f32_16x16x32_bf16 v[52:55], v[170:173], v[188:191], v[52:55]
	v_mfma_f32_16x16x32_bf16 v[40:43], v[162:165], v[192:195], v[40:43]
	v_mfma_f32_16x16x32_bf16 v[36:39], v[170:173], v[192:195], v[36:39]
	v_mfma_f32_16x16x32_bf16 v[22:25], v[162:165], v[204:207], v[22:25]
	v_mfma_f32_16x16x32_bf16 v[18:21], v[170:173], v[204:207], v[18:21]
	v_mfma_f32_16x16x32_bf16 v[6:9], v[162:165], v[208:211], v[6:9]
	v_mfma_f32_16x16x32_bf16 v[2:5], v[170:173], v[208:211], v[2:5]
	s_barrier
	s_setprio 0
	s_add_i32 s25, 0, 0x18000
	s_add_i32 s34, 0, 0x1c000
	ds_read_b128 v[138:141], v1 offset:32768
	ds_read_b128 v[142:145], v150 offset:32768
	ds_read_b128 v[146:149], v1 offset:34816
	ds_read_b128 v[154:157], v150 offset:34816
	ds_read_b128 v[158:161], v1 offset:49152
	ds_read_b128 v[162:165], v150 offset:49152
	ds_read_b128 v[166:169], v1 offset:51200
	ds_read_b128 v[170:173], v150 offset:51200
	s_add_u32 s30, s44, 0x80000
	s_addc_u32 s31, s45, 0
	s_mov_b32 m0, s48
	ds_read_b128 v[174:177], v151 offset:32768
	ds_read_b128 v[184:187], v151 offset:34816
	ds_read_b128 v[188:191], v152 offset:32768
	ds_read_b128 v[192:195], v152 offset:34816
	ds_read_b128 v[196:199], v151 offset:36864
	ds_read_b128 v[200:203], v151 offset:38912
	ds_read_b128 v[204:207], v152 offset:36864
	ds_read_b128 v[208:211], v152 offset:38912
	global_load_lds_dwordx4 v136, s[30:31]
	s_mov_b32 m0, s49
	s_nop 0
	global_load_lds_dwordx4 v134, s[30:31]
	s_waitcnt vmcnt(8)
	s_waitcnt lgkmcnt(0)
	s_setprio 1
	s_barrier
	v_mfma_f32_16x16x32_bf16 v[128:131], v[138:141], v[174:177], v[128:131]
	v_mfma_f32_16x16x32_bf16 v[124:127], v[146:149], v[174:177], v[124:127]
	v_mfma_f32_16x16x32_bf16 v[112:115], v[138:141], v[184:187], v[112:115]
	v_mfma_f32_16x16x32_bf16 v[108:111], v[146:149], v[184:187], v[108:111]
	v_mfma_f32_16x16x32_bf16 v[96:99], v[138:141], v[196:199], v[96:99]
	v_mfma_f32_16x16x32_bf16 v[92:95], v[146:149], v[196:199], v[92:95]
	v_mfma_f32_16x16x32_bf16 v[80:83], v[138:141], v[200:203], v[80:83]
	v_mfma_f32_16x16x32_bf16 v[76:79], v[146:149], v[200:203], v[76:79]
	v_mfma_f32_16x16x32_bf16 v[128:131], v[142:145], v[188:191], v[128:131]
	v_mfma_f32_16x16x32_bf16 v[124:127], v[154:157], v[188:191], v[124:127]
	v_mfma_f32_16x16x32_bf16 v[112:115], v[142:145], v[192:195], v[112:115]
	v_mfma_f32_16x16x32_bf16 v[108:111], v[154:157], v[192:195], v[108:111]
	v_mfma_f32_16x16x32_bf16 v[96:99], v[142:145], v[204:207], v[96:99]
	v_mfma_f32_16x16x32_bf16 v[92:95], v[154:157], v[204:207], v[92:95]
	v_mfma_f32_16x16x32_bf16 v[80:83], v[142:145], v[208:211], v[80:83]
	v_mfma_f32_16x16x32_bf16 v[76:79], v[154:157], v[208:211], v[76:79]
	s_setprio 0
	s_setprio 1
	v_mfma_f32_16x16x32_bf16 v[120:123], v[158:161], v[174:177], v[120:123]
	v_mfma_f32_16x16x32_bf16 v[116:119], v[166:169], v[174:177], v[116:119]
	v_mfma_f32_16x16x32_bf16 v[104:107], v[158:161], v[184:187], v[104:107]
	v_mfma_f32_16x16x32_bf16 v[100:103], v[166:169], v[184:187], v[100:103]
	v_mfma_f32_16x16x32_bf16 v[88:91], v[158:161], v[196:199], v[88:91]
	v_mfma_f32_16x16x32_bf16 v[84:87], v[166:169], v[196:199], v[84:87]
	v_mfma_f32_16x16x32_bf16 v[72:75], v[158:161], v[200:203], v[72:75]
	v_mfma_f32_16x16x32_bf16 v[68:71], v[166:169], v[200:203], v[68:71]
	v_mfma_f32_16x16x32_bf16 v[120:123], v[162:165], v[188:191], v[120:123]
	v_mfma_f32_16x16x32_bf16 v[116:119], v[170:173], v[188:191], v[116:119]
	v_mfma_f32_16x16x32_bf16 v[104:107], v[162:165], v[192:195], v[104:107]
	v_mfma_f32_16x16x32_bf16 v[100:103], v[170:173], v[192:195], v[100:103]
	v_mfma_f32_16x16x32_bf16 v[88:91], v[162:165], v[204:207], v[88:91]
	v_mfma_f32_16x16x32_bf16 v[84:87], v[170:173], v[204:207], v[84:87]
	v_mfma_f32_16x16x32_bf16 v[72:75], v[162:165], v[208:211], v[72:75]
	v_mfma_f32_16x16x32_bf16 v[68:71], v[170:173], v[208:211], v[68:71]
	s_barrier
	s_setprio 0
	s_add_i32 s25, s25, s33
	s_add_i32 m0, s25, 0xffffff80
	ds_read_b128 v[174:177], v151 offset:49152
	ds_read_b128 v[184:187], v151 offset:51200
	ds_read_b128 v[188:191], v152 offset:49152
	ds_read_b128 v[192:195], v152 offset:51200
	ds_read_b128 v[196:199], v151 offset:53248
	ds_read_b128 v[200:203], v151 offset:55296
	ds_read_b128 v[204:207], v152 offset:53248
	ds_read_b128 v[208:211], v152 offset:55296
	global_load_lds_dwordx4 v34, s[28:29] offset:128
	s_add_i32 m0, s25, 0x1f80
	s_mov_b64 s[98:99], s[28:29]
	s_add_u32 s28, s28, 0x80080
	s_addc_u32 s29, s29, 0
	s_add_i32 s25, s34, s33
	global_load_lds_dwordx4 v132, s[98:99] offset:128
	s_mov_b32 m0, s25
	s_nop 0
	global_load_lds_dwordx4 v34, s[28:29]
	s_add_i32 m0, s25, 0x2000
	s_nop 0
	global_load_lds_dwordx4 v132, s[28:29]
	s_add_i32 m0, s52, 0xffffff80
	s_nop 0
	global_load_lds_dwordx4 v136, s[44:45] offset:128
	s_add_i32 m0, s53, 0xffffff80
	s_nop 0
	global_load_lds_dwordx4 v134, s[44:45] offset:128
	s_waitcnt vmcnt(8)
	s_waitcnt lgkmcnt(0)
	s_setprio 1
	s_barrier
	v_mfma_f32_16x16x32_bf16 v[64:67], v[138:141], v[174:177], v[64:67]
	v_mfma_f32_16x16x32_bf16 v[60:63], v[146:149], v[174:177], v[60:63]
	v_mfma_f32_16x16x32_bf16 v[48:51], v[138:141], v[184:187], v[48:51]
	v_mfma_f32_16x16x32_bf16 v[44:47], v[146:149], v[184:187], v[44:47]
	v_mfma_f32_16x16x32_bf16 v[30:33], v[138:141], v[196:199], v[30:33]
	v_mfma_f32_16x16x32_bf16 v[26:29], v[146:149], v[196:199], v[26:29]
	v_mfma_f32_16x16x32_bf16 v[14:17], v[138:141], v[200:203], v[14:17]
	v_mfma_f32_16x16x32_bf16 v[10:13], v[146:149], v[200:203], v[10:13]
	v_mfma_f32_16x16x32_bf16 v[64:67], v[142:145], v[188:191], v[64:67]
	v_mfma_f32_16x16x32_bf16 v[60:63], v[154:157], v[188:191], v[60:63]
	v_mfma_f32_16x16x32_bf16 v[48:51], v[142:145], v[192:195], v[48:51]
	v_mfma_f32_16x16x32_bf16 v[44:47], v[154:157], v[192:195], v[44:47]
	v_mfma_f32_16x16x32_bf16 v[30:33], v[142:145], v[204:207], v[30:33]
	v_mfma_f32_16x16x32_bf16 v[26:29], v[154:157], v[204:207], v[26:29]
	v_mfma_f32_16x16x32_bf16 v[14:17], v[142:145], v[208:211], v[14:17]
	v_mfma_f32_16x16x32_bf16 v[10:13], v[154:157], v[208:211], v[10:13]
	s_setprio 0
	s_setprio 1
	v_mfma_f32_16x16x32_bf16 v[56:59], v[158:161], v[174:177], v[56:59]
	v_mfma_f32_16x16x32_bf16 v[52:55], v[166:169], v[174:177], v[52:55]
	v_mfma_f32_16x16x32_bf16 v[40:43], v[158:161], v[184:187], v[40:43]
	v_mfma_f32_16x16x32_bf16 v[36:39], v[166:169], v[184:187], v[36:39]
	v_mfma_f32_16x16x32_bf16 v[22:25], v[158:161], v[196:199], v[22:25]
	v_mfma_f32_16x16x32_bf16 v[18:21], v[166:169], v[196:199], v[18:21]
	v_mfma_f32_16x16x32_bf16 v[6:9], v[158:161], v[200:203], v[6:9]
	v_mfma_f32_16x16x32_bf16 v[2:5], v[166:169], v[200:203], v[2:5]
	v_mfma_f32_16x16x32_bf16 v[56:59], v[162:165], v[188:191], v[56:59]
	v_mfma_f32_16x16x32_bf16 v[52:55], v[170:173], v[188:191], v[52:55]
	v_mfma_f32_16x16x32_bf16 v[40:43], v[162:165], v[192:195], v[40:43]
	v_mfma_f32_16x16x32_bf16 v[36:39], v[170:173], v[192:195], v[36:39]
	v_mfma_f32_16x16x32_bf16 v[22:25], v[162:165], v[204:207], v[22:25]
	v_mfma_f32_16x16x32_bf16 v[18:21], v[170:173], v[204:207], v[18:21]
	v_mfma_f32_16x16x32_bf16 v[6:9], v[162:165], v[208:211], v[6:9]
	v_mfma_f32_16x16x32_bf16 v[2:5], v[170:173], v[208:211], v[2:5]
	s_barrier
	s_setprio 0
	s_add_i32 s24, s24, 2
	s_add_u32 s8, s8, 0x100
	s_addc_u32 s9, s9, 0
	s_add_u32 s21, s21, 0x100
	s_addc_u32 s23, s23, 0
	s_cmp_gt_u32 s24, 29
	s_cbranch_scc1 .Lpeel_done_P4
.LBB0_1023:
	s_add_u32 s25, s8, 0xfff80080
	s_addc_u32 s28, s9, -1
	s_add_i32 s30, 0, 0x10000
	s_cmp_eq_u32 s24, 28
	s_cselect_b32 s45, s12, s28
	s_cselect_b32 s44, s13, s25
	s_cselect_b32 s29, s19, s23
	s_cselect_b32 s28, s20, s21
	s_add_i32 s25, 0, 0x14000
	ds_read_b128 v[138:141], v1
	ds_read_b128 v[142:145], v150
	ds_read_b128 v[146:149], v1 offset:2048
	ds_read_b128 v[154:157], v150 offset:2048
	ds_read_b128 v[158:161], v1 offset:16384
	ds_read_b128 v[162:165], v150 offset:16384
	ds_read_b128 v[166:169], v1 offset:18432
	ds_read_b128 v[170:173], v150 offset:18432
	s_add_i32 m0, s46, 0xc000
	ds_read_b128 v[174:177], v151
	ds_read_b128 v[184:187], v151 offset:2048
	ds_read_b128 v[188:191], v152
	ds_read_b128 v[192:195], v152 offset:2048
	ds_read_b128 v[196:199], v151 offset:4096
	ds_read_b128 v[200:203], v151 offset:6144
	ds_read_b128 v[204:207], v152 offset:4096
	ds_read_b128 v[208:211], v152 offset:6144
	global_load_lds_dwordx4 v136, s[8:9]
	s_add_i32 m0, s46, 0xe000
	s_nop 0
	global_load_lds_dwordx4 v134, s[8:9]
	s_waitcnt vmcnt(8)
	s_waitcnt lgkmcnt(0)
	s_setprio 1
	s_barrier
	v_mfma_f32_16x16x32_bf16 v[128:131], v[138:141], v[174:177], v[128:131]
	v_mfma_f32_16x16x32_bf16 v[124:127], v[146:149], v[174:177], v[124:127]
	v_mfma_f32_16x16x32_bf16 v[112:115], v[138:141], v[184:187], v[112:115]
	v_mfma_f32_16x16x32_bf16 v[108:111], v[146:149], v[184:187], v[108:111]
	v_mfma_f32_16x16x32_bf16 v[96:99], v[138:141], v[196:199], v[96:99]
	v_mfma_f32_16x16x32_bf16 v[92:95], v[146:149], v[196:199], v[92:95]
	v_mfma_f32_16x16x32_bf16 v[80:83], v[138:141], v[200:203], v[80:83]
	v_mfma_f32_16x16x32_bf16 v[76:79], v[146:149], v[200:203], v[76:79]
	v_mfma_f32_16x16x32_bf16 v[128:131], v[142:145], v[188:191], v[128:131]
	v_mfma_f32_16x16x32_bf16 v[124:127], v[154:157], v[188:191], v[124:127]
	v_mfma_f32_16x16x32_bf16 v[112:115], v[142:145], v[192:195], v[112:115]
	v_mfma_f32_16x16x32_bf16 v[108:111], v[154:157], v[192:195], v[108:111]
	v_mfma_f32_16x16x32_bf16 v[96:99], v[142:145], v[204:207], v[96:99]
	v_mfma_f32_16x16x32_bf16 v[92:95], v[154:157], v[204:207], v[92:95]
	v_mfma_f32_16x16x32_bf16 v[80:83], v[142:145], v[208:211], v[80:83]
	v_mfma_f32_16x16x32_bf16 v[76:79], v[154:157], v[208:211], v[76:79]
	s_setprio 0
	s_setprio 1
	v_mfma_f32_16x16x32_bf16 v[120:123], v[158:161], v[174:177], v[120:123]
	v_mfma_f32_16x16x32_bf16 v[116:119], v[166:169], v[174:177], v[116:119]
	v_mfma_f32_16x16x32_bf16 v[104:107], v[158:161], v[184:187], v[104:107]
	v_mfma_f32_16x16x32_bf16 v[100:103], v[166:169], v[184:187], v[100:103]
	v_mfma_f32_16x16x32_bf16 v[88:91], v[158:161], v[196:199], v[88:91]
	v_mfma_f32_16x16x32_bf16 v[84:87], v[166:169], v[196:199], v[84:87]
	v_mfma_f32_16x16x32_bf16 v[72:75], v[158:161], v[200:203], v[72:75]
	v_mfma_f32_16x16x32_bf16 v[68:71], v[166:169], v[200:203], v[68:71]
	v_mfma_f32_16x16x32_bf16 v[120:123], v[162:165], v[188:191], v[120:123]
	v_mfma_f32_16x16x32_bf16 v[116:119], v[170:173], v[188:191], v[116:119]
	v_mfma_f32_16x16x32_bf16 v[104:107], v[162:165], v[192:195], v[104:107]
	v_mfma_f32_16x16x32_bf16 v[100:103], v[170:173], v[192:195], v[100:103]
	v_mfma_f32_16x16x32_bf16 v[88:91], v[162:165], v[204:207], v[88:91]
	v_mfma_f32_16x16x32_bf16 v[84:87], v[170:173], v[204:207], v[84:87]
	v_mfma_f32_16x16x32_bf16 v[72:75], v[162:165], v[208:211], v[72:75]
	v_mfma_f32_16x16x32_bf16 v[68:71], v[170:173], v[208:211], v[68:71]
	s_barrier
	s_setprio 0
	s_add_i32 s30, s30, s33
	s_mov_b32 m0, s30
	ds_read_b128 v[174:177], v151 offset:16384
	ds_read_b128 v[184:187], v151 offset:18432
	ds_read_b128 v[188:191], v152 offset:16384
	ds_read_b128 v[192:195], v152 offset:18432
	ds_read_b128 v[196:199], v151 offset:20480
	ds_read_b128 v[200:203], v151 offset:22528
	ds_read_b128 v[204:207], v152 offset:20480
	ds_read_b128 v[208:211], v152 offset:22528
	global_load_lds_dwordx4 v34, s[28:29]
	s_add_i32 m0, s30, 0x2000
	s_add_u32 s30, s28, 0x80000
	s_addc_u32 s31, s29, 0
	s_add_i32 s25, s25, s33
	global_load_lds_dwordx4 v132, s[28:29]
	s_mov_b32 m0, s25
	s_nop 0
	global_load_lds_dwordx4 v34, s[30:31]
	s_add_i32 m0, s25, 0x2000
	s_nop 0
	global_load_lds_dwordx4 v132, s[30:31]
	s_mov_b32 m0, s46
	s_nop 0
	global_load_lds_dwordx4 v136, s[44:45]
	s_mov_b32 m0, s47
	s_nop 0
	global_load_lds_dwordx4 v134, s[44:45]
	s_waitcnt vmcnt(8)
	s_waitcnt lgkmcnt(0)
	s_setprio 1
	s_barrier
	v_mfma_f32_16x16x32_bf16 v[64:67], v[138:141], v[174:177], v[64:67]
	v_mfma_f32_16x16x32_bf16 v[60:63], v[146:149], v[174:177], v[60:63]
	v_mfma_f32_16x16x32_bf16 v[48:51], v[138:141], v[184:187], v[48:51]
	v_mfma_f32_16x16x32_bf16 v[44:47], v[146:149], v[184:187], v[44:47]
	v_mfma_f32_16x16x32_bf16 v[30:33], v[138:141], v[196:199], v[30:33]
	v_mfma_f32_16x16x32_bf16 v[26:29], v[146:149], v[196:199], v[26:29]
	v_mfma_f32_16x16x32_bf16 v[14:17], v[138:141], v[200:203], v[14:17]
	v_mfma_f32_16x16x32_bf16 v[10:13], v[146:149], v[200:203], v[10:13]
	v_mfma_f32_16x16x32_bf16 v[64:67], v[142:145], v[188:191], v[64:67]
	v_mfma_f32_16x16x32_bf16 v[60:63], v[154:157], v[188:191], v[60:63]
	v_mfma_f32_16x16x32_bf16 v[48:51], v[142:145], v[192:195], v[48:51]
	v_mfma_f32_16x16x32_bf16 v[44:47], v[154:157], v[192:195], v[44:47]
	v_mfma_f32_16x16x32_bf16 v[30:33], v[142:145], v[204:207], v[30:33]
	v_mfma_f32_16x16x32_bf16 v[26:29], v[154:157], v[204:207], v[26:29]
	v_mfma_f32_16x16x32_bf16 v[14:17], v[142:145], v[208:211], v[14:17]
	v_mfma_f32_16x16x32_bf16 v[10:13], v[154:157], v[208:211], v[10:13]
	s_setprio 0
	s_setprio 1
	v_mfma_f32_16x16x32_bf16 v[56:59], v[158:161], v[174:177], v[56:59]
	v_mfma_f32_16x16x32_bf16 v[52:55], v[166:169], v[174:177], v[52:55]
	v_mfma_f32_16x16x32_bf16 v[40:43], v[158:161], v[184:187], v[40:43]
	v_mfma_f32_16x16x32_bf16 v[36:39], v[166:169], v[184:187], v[36:39]
	v_mfma_f32_16x16x32_bf16 v[22:25], v[158:161], v[196:199], v[22:25]
	v_mfma_f32_16x16x32_bf16 v[18:21], v[166:169], v[196:199], v[18:21]
	v_mfma_f32_16x16x32_bf16 v[6:9], v[158:161], v[200:203], v[6:9]
	v_mfma_f32_16x16x32_bf16 v[2:5], v[166:169], v[200:203], v[2:5]
	v_mfma_f32_16x16x32_bf16 v[56:59], v[162:165], v[188:191], v[56:59]
	v_mfma_f32_16x16x32_bf16 v[52:55], v[170:173], v[188:191], v[52:55]
	v_mfma_f32_16x16x32_bf16 v[40:43], v[162:165], v[192:195], v[40:43]
	v_mfma_f32_16x16x32_bf16 v[36:39], v[170:173], v[192:195], v[36:39]
	v_mfma_f32_16x16x32_bf16 v[22:25], v[162:165], v[204:207], v[22:25]
	v_mfma_f32_16x16x32_bf16 v[18:21], v[170:173], v[204:207], v[18:21]
	v_mfma_f32_16x16x32_bf16 v[6:9], v[162:165], v[208:211], v[6:9]
	v_mfma_f32_16x16x32_bf16 v[2:5], v[170:173], v[208:211], v[2:5]
	s_barrier
	s_setprio 0
	s_add_i32 s25, 0, 0x18000
	s_add_i32 s34, 0, 0x1c000
	ds_read_b128 v[138:141], v1 offset:32768
	ds_read_b128 v[142:145], v150 offset:32768
	ds_read_b128 v[146:149], v1 offset:34816
	ds_read_b128 v[154:157], v150 offset:34816
	ds_read_b128 v[158:161], v1 offset:49152
	ds_read_b128 v[162:165], v150 offset:49152
	ds_read_b128 v[166:169], v1 offset:51200
	ds_read_b128 v[170:173], v150 offset:51200
	s_add_u32 s30, s44, 0x80000
	s_addc_u32 s31, s45, 0
	s_mov_b32 m0, s48
	ds_read_b128 v[174:177], v151 offset:32768
	ds_read_b128 v[184:187], v151 offset:34816
	ds_read_b128 v[188:191], v152 offset:32768
	ds_read_b128 v[192:195], v152 offset:34816
	ds_read_b128 v[196:199], v151 offset:36864
	ds_read_b128 v[200:203], v151 offset:38912
	ds_read_b128 v[204:207], v152 offset:36864
	ds_read_b128 v[208:211], v152 offset:38912
	global_load_lds_dwordx4 v136, s[30:31]
	s_mov_b32 m0, s49
	s_nop 0
	global_load_lds_dwordx4 v134, s[30:31]
	s_waitcnt vmcnt(8)
	s_waitcnt lgkmcnt(0)
	s_setprio 1
	s_barrier
	v_mfma_f32_16x16x32_bf16 v[128:131], v[138:141], v[174:177], v[128:131]
	v_mfma_f32_16x16x32_bf16 v[124:127], v[146:149], v[174:177], v[124:127]
	v_mfma_f32_16x16x32_bf16 v[112:115], v[138:141], v[184:187], v[112:115]
	v_mfma_f32_16x16x32_bf16 v[108:111], v[146:149], v[184:187], v[108:111]
	v_mfma_f32_16x16x32_bf16 v[96:99], v[138:141], v[196:199], v[96:99]
	v_mfma_f32_16x16x32_bf16 v[92:95], v[146:149], v[196:199], v[92:95]
	v_mfma_f32_16x16x32_bf16 v[80:83], v[138:141], v[200:203], v[80:83]
	v_mfma_f32_16x16x32_bf16 v[76:79], v[146:149], v[200:203], v[76:79]
	v_mfma_f32_16x16x32_bf16 v[128:131], v[142:145], v[188:191], v[128:131]
	v_mfma_f32_16x16x32_bf16 v[124:127], v[154:157], v[188:191], v[124:127]
	v_mfma_f32_16x16x32_bf16 v[112:115], v[142:145], v[192:195], v[112:115]
	v_mfma_f32_16x16x32_bf16 v[108:111], v[154:157], v[192:195], v[108:111]
	v_mfma_f32_16x16x32_bf16 v[96:99], v[142:145], v[204:207], v[96:99]
	v_mfma_f32_16x16x32_bf16 v[92:95], v[154:157], v[204:207], v[92:95]
	v_mfma_f32_16x16x32_bf16 v[80:83], v[142:145], v[208:211], v[80:83]
	v_mfma_f32_16x16x32_bf16 v[76:79], v[154:157], v[208:211], v[76:79]
	s_setprio 0
	s_setprio 1
	v_mfma_f32_16x16x32_bf16 v[120:123], v[158:161], v[174:177], v[120:123]
	v_mfma_f32_16x16x32_bf16 v[116:119], v[166:169], v[174:177], v[116:119]
	v_mfma_f32_16x16x32_bf16 v[104:107], v[158:161], v[184:187], v[104:107]
	v_mfma_f32_16x16x32_bf16 v[100:103], v[166:169], v[184:187], v[100:103]
	v_mfma_f32_16x16x32_bf16 v[88:91], v[158:161], v[196:199], v[88:91]
	v_mfma_f32_16x16x32_bf16 v[84:87], v[166:169], v[196:199], v[84:87]
	v_mfma_f32_16x16x32_bf16 v[72:75], v[158:161], v[200:203], v[72:75]
	v_mfma_f32_16x16x32_bf16 v[68:71], v[166:169], v[200:203], v[68:71]
	v_mfma_f32_16x16x32_bf16 v[120:123], v[162:165], v[188:191], v[120:123]
	v_mfma_f32_16x16x32_bf16 v[116:119], v[170:173], v[188:191], v[116:119]
	v_mfma_f32_16x16x32_bf16 v[104:107], v[162:165], v[192:195], v[104:107]
	v_mfma_f32_16x16x32_bf16 v[100:103], v[170:173], v[192:195], v[100:103]
	v_mfma_f32_16x16x32_bf16 v[88:91], v[162:165], v[204:207], v[88:91]
	v_mfma_f32_16x16x32_bf16 v[84:87], v[170:173], v[204:207], v[84:87]
	v_mfma_f32_16x16x32_bf16 v[72:75], v[162:165], v[208:211], v[72:75]
	v_mfma_f32_16x16x32_bf16 v[68:71], v[170:173], v[208:211], v[68:71]
	s_barrier
	s_setprio 0
	s_add_i32 s25, s25, s33
	s_add_i32 m0, s25, 0xffffff80
	ds_read_b128 v[174:177], v151 offset:49152
	ds_read_b128 v[184:187], v151 offset:51200
	ds_read_b128 v[188:191], v152 offset:49152
	ds_read_b128 v[192:195], v152 offset:51200
	ds_read_b128 v[196:199], v151 offset:53248
	ds_read_b128 v[200:203], v151 offset:55296
	ds_read_b128 v[204:207], v152 offset:53248
	ds_read_b128 v[208:211], v152 offset:55296
	global_load_lds_dwordx4 v34, s[28:29] offset:128
	s_add_i32 m0, s25, 0x1f80
	s_mov_b64 s[98:99], s[28:29]
	s_add_u32 s28, s28, 0x80080
	s_addc_u32 s29, s29, 0
	s_add_i32 s25, s34, s33
	global_load_lds_dwordx4 v132, s[98:99] offset:128
	s_mov_b32 m0, s25
	s_nop 0
	global_load_lds_dwordx4 v34, s[28:29]
	s_add_i32 m0, s25, 0x2000
	s_nop 0
	global_load_lds_dwordx4 v132, s[28:29]
	s_add_i32 m0, s52, 0xffffff80
	s_nop 0
	global_load_lds_dwordx4 v136, s[44:45] offset:128
	s_add_i32 m0, s53, 0xffffff80
	s_nop 0
	global_load_lds_dwordx4 v134, s[44:45] offset:128
	s_waitcnt vmcnt(8)
	s_waitcnt lgkmcnt(0)
	s_setprio 1
	s_barrier
	v_mfma_f32_16x16x32_bf16 v[64:67], v[138:141], v[174:177], v[64:67]
	v_mfma_f32_16x16x32_bf16 v[60:63], v[146:149], v[174:177], v[60:63]
	v_mfma_f32_16x16x32_bf16 v[48:51], v[138:141], v[184:187], v[48:51]
	v_mfma_f32_16x16x32_bf16 v[44:47], v[146:149], v[184:187], v[44:47]
	v_mfma_f32_16x16x32_bf16 v[30:33], v[138:141], v[196:199], v[30:33]
	v_mfma_f32_16x16x32_bf16 v[26:29], v[146:149], v[196:199], v[26:29]
	v_mfma_f32_16x16x32_bf16 v[14:17], v[138:141], v[200:203], v[14:17]
	v_mfma_f32_16x16x32_bf16 v[10:13], v[146:149], v[200:203], v[10:13]
	v_mfma_f32_16x16x32_bf16 v[64:67], v[142:145], v[188:191], v[64:67]
	v_mfma_f32_16x16x32_bf16 v[60:63], v[154:157], v[188:191], v[60:63]
	v_mfma_f32_16x16x32_bf16 v[48:51], v[142:145], v[192:195], v[48:51]
	v_mfma_f32_16x16x32_bf16 v[44:47], v[154:157], v[192:195], v[44:47]
	v_mfma_f32_16x16x32_bf16 v[30:33], v[142:145], v[204:207], v[30:33]
	v_mfma_f32_16x16x32_bf16 v[26:29], v[154:157], v[204:207], v[26:29]
	v_mfma_f32_16x16x32_bf16 v[14:17], v[142:145], v[208:211], v[14:17]
	v_mfma_f32_16x16x32_bf16 v[10:13], v[154:157], v[208:211], v[10:13]
	s_setprio 0
	s_setprio 1
	v_mfma_f32_16x16x32_bf16 v[56:59], v[158:161], v[174:177], v[56:59]
	v_mfma_f32_16x16x32_bf16 v[52:55], v[166:169], v[174:177], v[52:55]
	v_mfma_f32_16x16x32_bf16 v[40:43], v[158:161], v[184:187], v[40:43]
	v_mfma_f32_16x16x32_bf16 v[36:39], v[166:169], v[184:187], v[36:39]
	v_mfma_f32_16x16x32_bf16 v[22:25], v[158:161], v[196:199], v[22:25]
	v_mfma_f32_16x16x32_bf16 v[18:21], v[166:169], v[196:199], v[18:21]
	v_mfma_f32_16x16x32_bf16 v[6:9], v[158:161], v[200:203], v[6:9]
	v_mfma_f32_16x16x32_bf16 v[2:5], v[166:169], v[200:203], v[2:5]
	v_mfma_f32_16x16x32_bf16 v[56:59], v[162:165], v[188:191], v[56:59]
	v_mfma_f32_16x16x32_bf16 v[52:55], v[170:173], v[188:191], v[52:55]
	v_mfma_f32_16x16x32_bf16 v[40:43], v[162:165], v[192:195], v[40:43]
	v_mfma_f32_16x16x32_bf16 v[36:39], v[170:173], v[192:195], v[36:39]
	v_mfma_f32_16x16x32_bf16 v[22:25], v[162:165], v[204:207], v[22:25]
	v_mfma_f32_16x16x32_bf16 v[18:21], v[170:173], v[204:207], v[18:21]
	v_mfma_f32_16x16x32_bf16 v[6:9], v[162:165], v[208:211], v[6:9]
	v_mfma_f32_16x16x32_bf16 v[2:5], v[170:173], v[208:211], v[2:5]
	s_barrier
	s_setprio 0
	s_add_i32 s24, s24, 2
	s_add_u32 s8, s8, 0x100
	s_addc_u32 s9, s9, 0
	s_add_u32 s21, s21, 0x100
	s_addc_u32 s23, s23, 0
	s_cmp_gt_u32 s24, 29
	s_cbranch_scc0 .LBB0_1023

.LBB0_1113:
	s_ashr_i32 s19, s18, 31
	s_lshl_b64 s[20:21], s[18:19], 20
	v_readlane_b32 s22, v254, 38
	v_readlane_b32 s23, v254, 39
	s_add_u32 s22, s22, s20
	s_addc_u32 s23, s23, s21
	s_and_b64 s[20:21], s[38:39], exec
	s_cselect_b32 s13, s23, s9
	s_cselect_b32 s19, s22, s8
	s_ashr_i32 s11, s10, 31
	s_lshl_b64 s[20:21], s[10:11], 20
	v_readlane_b32 s30, v254, 8
	v_readlane_b32 s31, v254, 9
	s_add_u32 s40, s30, s20
	s_addc_u32 s41, s31, s21
	v_mov_b32_e32 v2, v0
	s_and_b64 s[20:21], s[38:39], exec
	s_cselect_b32 s20, s41, s29
	s_cselect_b32 s21, s40, s28
	s_lshl_b32 s11, s24, 8
	v_and_or_b32 v2, v2, 63, s50
	v_or_b32_e32 v2, s11, v2
	v_ashrrev_i32_e32 v3, 31, v2
	v_readlane_b32 s24, v252, 61
	v_lshlrev_b64 v[2:3], 5, v[2:3]
	v_readlane_b32 s25, v252, 62
	s_add_u32 s8, s8, 0x80080
	s_addc_u32 s9, s9, 0
	v_lshl_add_u64 v[2:3], s[24:25], 0, v[2:3]
	global_load_dwordx4 v[116:119], v[2:3], off offset:16
	global_load_dwordx4 v[120:123], v[2:3], off
	s_add_u32 s24, s28, 0x100
	s_addc_u32 s25, s29, 0
	s_mov_b32 s30, -2
	v_readlane_b32 s57, v255, 20
	v_readlane_b32 s58, v255, 21
	v_readlane_b32 s59, v255, 22
	v_readlane_b32 s60, v255, 23
	s_mov_b64 s[62:63], 0x80
	s_add_u32 s28, s8, 0xfff80080
	s_addc_u32 s29, s9, -1
	s_add_i32 s31, 0, 0x10000
	s_cmp_eq_u32 s30, 28
	s_cselect_b32 s43, s13, s29
	s_cselect_b32 s42, s19, s28
	ds_read_b128 v[150:153], v1
	ds_read_b128 v[154:157], v146
	s_cselect_b32 s29, s20, s25
	s_cselect_b32 s28, s21, s24
	s_add_i32 s56, 0, 0x14000
	ds_read_b128 v[158:161], v1 offset:2048
	ds_read_b128 v[162:165], v146 offset:2048
	ds_read_b128 v[166:169], v1 offset:16384
	ds_read_b128 v[170:173], v146 offset:16384
	ds_read_b128 v[174:177], v1 offset:18432
	ds_read_b128 v[184:187], v146 offset:18432
	s_add_i32 m0, s34, 0xc000
	ds_read_b128 v[188:191], v147
	ds_read_b128 v[192:195], v147 offset:2048
	ds_read_b128 v[196:199], v148
	ds_read_b128 v[200:203], v148 offset:2048
	ds_read_b128 v[204:207], v147 offset:4096
	ds_read_b128 v[208:211], v147 offset:6144
	ds_read_b128 v[224:227], v148 offset:4096
	ds_read_b128 v[228:231], v148 offset:6144
	global_load_lds_dwordx4 v144, s[8:9]
	s_add_i32 m0, s34, 0xe000
	s_nop 0
	global_load_lds_dwordx4 v142, s[8:9]
	s_waitcnt vmcnt(8)
	s_waitcnt lgkmcnt(0)
	s_setprio 1
	s_barrier
	v_mfma_f32_16x16x32_bf16 v[132:135], v[150:153], v[188:191], 0
	v_mfma_f32_16x16x32_bf16 v[124:127], v[158:161], v[188:191], 0
	v_mfma_f32_16x16x32_bf16 v[108:111], v[150:153], v[192:195], 0
	v_mfma_f32_16x16x32_bf16 v[100:103], v[158:161], v[192:195], 0
	v_mfma_f32_16x16x32_bf16 v[92:95], v[150:153], v[204:207], 0
	v_mfma_f32_16x16x32_bf16 v[84:87], v[158:161], v[204:207], 0
	v_mfma_f32_16x16x32_bf16 v[76:79], v[150:153], v[208:211], 0
	v_mfma_f32_16x16x32_bf16 v[68:71], v[158:161], v[208:211], 0
	v_mfma_f32_16x16x32_bf16 v[132:135], v[154:157], v[196:199], v[132:135]
	v_mfma_f32_16x16x32_bf16 v[124:127], v[162:165], v[196:199], v[124:127]
	v_mfma_f32_16x16x32_bf16 v[108:111], v[154:157], v[200:203], v[108:111]
	v_mfma_f32_16x16x32_bf16 v[100:103], v[162:165], v[200:203], v[100:103]
	v_mfma_f32_16x16x32_bf16 v[92:95], v[154:157], v[224:227], v[92:95]
	v_mfma_f32_16x16x32_bf16 v[84:87], v[162:165], v[224:227], v[84:87]
	v_mfma_f32_16x16x32_bf16 v[76:79], v[154:157], v[228:231], v[76:79]
	v_mfma_f32_16x16x32_bf16 v[68:71], v[162:165], v[228:231], v[68:71]
	s_setprio 0
	s_setprio 1
	v_mfma_f32_16x16x32_bf16 v[136:139], v[166:169], v[188:191], 0
	v_mfma_f32_16x16x32_bf16 v[128:131], v[174:177], v[188:191], 0
	v_mfma_f32_16x16x32_bf16 v[112:115], v[166:169], v[192:195], 0
	v_mfma_f32_16x16x32_bf16 v[104:107], v[174:177], v[192:195], 0
	v_mfma_f32_16x16x32_bf16 v[96:99], v[166:169], v[204:207], 0
	v_mfma_f32_16x16x32_bf16 v[88:91], v[174:177], v[204:207], 0
	v_mfma_f32_16x16x32_bf16 v[80:83], v[166:169], v[208:211], 0
	v_mfma_f32_16x16x32_bf16 v[72:75], v[174:177], v[208:211], 0
	v_mfma_f32_16x16x32_bf16 v[136:139], v[170:173], v[196:199], v[136:139]
	v_mfma_f32_16x16x32_bf16 v[128:131], v[184:187], v[196:199], v[128:131]
	v_mfma_f32_16x16x32_bf16 v[112:115], v[170:173], v[200:203], v[112:115]
	v_mfma_f32_16x16x32_bf16 v[104:107], v[184:187], v[200:203], v[104:107]
	v_mfma_f32_16x16x32_bf16 v[96:99], v[170:173], v[224:227], v[96:99]
	v_mfma_f32_16x16x32_bf16 v[88:91], v[184:187], v[224:227], v[88:91]
	v_mfma_f32_16x16x32_bf16 v[80:83], v[170:173], v[228:231], v[80:83]
	v_mfma_f32_16x16x32_bf16 v[72:75], v[184:187], v[228:231], v[72:75]
	s_barrier
	s_setprio 0
	s_add_i32 s31, s31, s33
	s_mov_b32 m0, s31
	ds_read_b128 v[188:191], v147 offset:16384
	ds_read_b128 v[192:195], v147 offset:18432
	ds_read_b128 v[196:199], v148 offset:16384
	ds_read_b128 v[200:203], v148 offset:18432
	ds_read_b128 v[204:207], v147 offset:20480
	ds_read_b128 v[208:211], v147 offset:22528
	ds_read_b128 v[224:227], v148 offset:20480
	ds_read_b128 v[228:231], v148 offset:22528
	global_load_lds_dwordx4 v34, s[28:29]
	s_add_i32 m0, s31, 0x2000
	s_add_u32 s54, s28, 0x80000
	s_addc_u32 s55, s29, 0
	s_add_i32 s31, s56, s33
	global_load_lds_dwordx4 v140, s[28:29]
	s_mov_b32 m0, s31
	s_nop 0
	global_load_lds_dwordx4 v34, s[54:55]
	s_add_i32 m0, s31, 0x2000
	s_nop 0
	global_load_lds_dwordx4 v140, s[54:55]
	s_mov_b32 m0, s34
	s_nop 0
	global_load_lds_dwordx4 v144, s[42:43]
	s_mov_b32 m0, s35
	s_nop 0
	global_load_lds_dwordx4 v142, s[42:43]
	s_waitcnt vmcnt(8)
	s_waitcnt lgkmcnt(0)
	s_setprio 1
	s_barrier
	v_mfma_f32_16x16x32_bf16 v[60:63], v[150:153], v[188:191], 0
	v_mfma_f32_16x16x32_bf16 v[52:55], v[158:161], v[188:191], 0
	v_mfma_f32_16x16x32_bf16 v[44:47], v[150:153], v[192:195], 0
	v_mfma_f32_16x16x32_bf16 v[36:39], v[158:161], v[192:195], 0
	v_mfma_f32_16x16x32_bf16 v[26:29], v[150:153], v[204:207], 0
	v_mfma_f32_16x16x32_bf16 v[18:21], v[158:161], v[204:207], 0
	v_mfma_f32_16x16x32_bf16 v[10:13], v[150:153], v[208:211], 0
	v_mfma_f32_16x16x32_bf16 v[6:9], v[158:161], v[208:211], 0
	v_mfma_f32_16x16x32_bf16 v[60:63], v[154:157], v[196:199], v[60:63]
	v_mfma_f32_16x16x32_bf16 v[52:55], v[162:165], v[196:199], v[52:55]
	v_mfma_f32_16x16x32_bf16 v[44:47], v[154:157], v[200:203], v[44:47]
	v_mfma_f32_16x16x32_bf16 v[36:39], v[162:165], v[200:203], v[36:39]
	v_mfma_f32_16x16x32_bf16 v[26:29], v[154:157], v[224:227], v[26:29]
	v_mfma_f32_16x16x32_bf16 v[18:21], v[162:165], v[224:227], v[18:21]
	v_mfma_f32_16x16x32_bf16 v[10:13], v[154:157], v[228:231], v[10:13]
	v_mfma_f32_16x16x32_bf16 v[6:9], v[162:165], v[228:231], v[6:9]
	s_setprio 0
	s_setprio 1
	v_mfma_f32_16x16x32_bf16 v[64:67], v[166:169], v[188:191], 0
	v_mfma_f32_16x16x32_bf16 v[56:59], v[174:177], v[188:191], 0
	v_mfma_f32_16x16x32_bf16 v[48:51], v[166:169], v[192:195], 0
	v_mfma_f32_16x16x32_bf16 v[40:43], v[174:177], v[192:195], 0
	v_mfma_f32_16x16x32_bf16 v[30:33], v[166:169], v[204:207], 0
	v_mfma_f32_16x16x32_bf16 v[22:25], v[174:177], v[204:207], 0
	v_mfma_f32_16x16x32_bf16 v[14:17], v[166:169], v[208:211], 0
	v_mfma_f32_16x16x32_bf16 v[2:5], v[174:177], v[208:211], 0
	v_mfma_f32_16x16x32_bf16 v[64:67], v[170:173], v[196:199], v[64:67]
	v_mfma_f32_16x16x32_bf16 v[56:59], v[184:187], v[196:199], v[56:59]
	v_mfma_f32_16x16x32_bf16 v[48:51], v[170:173], v[200:203], v[48:51]
	v_mfma_f32_16x16x32_bf16 v[40:43], v[184:187], v[200:203], v[40:43]
	v_mfma_f32_16x16x32_bf16 v[30:33], v[170:173], v[224:227], v[30:33]
	v_mfma_f32_16x16x32_bf16 v[22:25], v[184:187], v[224:227], v[22:25]
	v_mfma_f32_16x16x32_bf16 v[14:17], v[170:173], v[228:231], v[14:17]
	v_mfma_f32_16x16x32_bf16 v[2:5], v[184:187], v[228:231], v[2:5]
	s_barrier
	s_setprio 0
	s_add_i32 s31, 0, 0x18000
	ds_read_b128 v[150:153], v1 offset:32768
	ds_read_b128 v[154:157], v146 offset:32768
	s_add_i32 s54, 0, 0x1c000
	ds_read_b128 v[158:161], v1 offset:34816
	ds_read_b128 v[162:165], v146 offset:34816
	ds_read_b128 v[166:169], v1 offset:49152
	ds_read_b128 v[170:173], v146 offset:49152
	ds_read_b128 v[174:177], v1 offset:51200
	ds_read_b128 v[184:187], v146 offset:51200
	s_mov_b64 s[100:101], s[42:43]
	s_add_u32 s42, s42, 0x80000
	s_addc_u32 s43, s43, 0
	s_mov_b32 m0, s44
	ds_read_b128 v[188:191], v147 offset:32768
	ds_read_b128 v[192:195], v147 offset:34816
	ds_read_b128 v[196:199], v148 offset:32768
	ds_read_b128 v[200:203], v148 offset:34816
	ds_read_b128 v[204:207], v147 offset:36864
	ds_read_b128 v[208:211], v147 offset:38912
	ds_read_b128 v[224:227], v148 offset:36864
	ds_read_b128 v[228:231], v148 offset:38912
	global_load_lds_dwordx4 v144, s[42:43]
	s_mov_b32 m0, s45
	s_nop 0
	global_load_lds_dwordx4 v142, s[42:43]
	s_waitcnt vmcnt(8)
	s_waitcnt lgkmcnt(0)
	s_setprio 1
	s_barrier
	v_mfma_f32_16x16x32_bf16 v[132:135], v[150:153], v[188:191], v[132:135]
	v_mfma_f32_16x16x32_bf16 v[124:127], v[158:161], v[188:191], v[124:127]
	v_mfma_f32_16x16x32_bf16 v[108:111], v[150:153], v[192:195], v[108:111]
	v_mfma_f32_16x16x32_bf16 v[100:103], v[158:161], v[192:195], v[100:103]
	v_mfma_f32_16x16x32_bf16 v[92:95], v[150:153], v[204:207], v[92:95]
	v_mfma_f32_16x16x32_bf16 v[84:87], v[158:161], v[204:207], v[84:87]
	v_mfma_f32_16x16x32_bf16 v[76:79], v[150:153], v[208:211], v[76:79]
	v_mfma_f32_16x16x32_bf16 v[68:71], v[158:161], v[208:211], v[68:71]
	v_mfma_f32_16x16x32_bf16 v[132:135], v[154:157], v[196:199], v[132:135]
	v_mfma_f32_16x16x32_bf16 v[124:127], v[162:165], v[196:199], v[124:127]
	v_mfma_f32_16x16x32_bf16 v[108:111], v[154:157], v[200:203], v[108:111]
	v_mfma_f32_16x16x32_bf16 v[100:103], v[162:165], v[200:203], v[100:103]
	v_mfma_f32_16x16x32_bf16 v[92:95], v[154:157], v[224:227], v[92:95]
	v_mfma_f32_16x16x32_bf16 v[84:87], v[162:165], v[224:227], v[84:87]
	v_mfma_f32_16x16x32_bf16 v[76:79], v[154:157], v[228:231], v[76:79]
	v_mfma_f32_16x16x32_bf16 v[68:71], v[162:165], v[228:231], v[68:71]
	s_setprio 0
	s_setprio 1
	v_mfma_f32_16x16x32_bf16 v[136:139], v[166:169], v[188:191], v[136:139]
	v_mfma_f32_16x16x32_bf16 v[128:131], v[174:177], v[188:191], v[128:131]
	v_mfma_f32_16x16x32_bf16 v[112:115], v[166:169], v[192:195], v[112:115]
	v_mfma_f32_16x16x32_bf16 v[104:107], v[174:177], v[192:195], v[104:107]
	v_mfma_f32_16x16x32_bf16 v[96:99], v[166:169], v[204:207], v[96:99]
	v_mfma_f32_16x16x32_bf16 v[88:91], v[174:177], v[204:207], v[88:91]
	v_mfma_f32_16x16x32_bf16 v[80:83], v[166:169], v[208:211], v[80:83]
	v_mfma_f32_16x16x32_bf16 v[72:75], v[174:177], v[208:211], v[72:75]
	v_mfma_f32_16x16x32_bf16 v[136:139], v[170:173], v[196:199], v[136:139]
	v_mfma_f32_16x16x32_bf16 v[128:131], v[184:187], v[196:199], v[128:131]
	v_mfma_f32_16x16x32_bf16 v[112:115], v[170:173], v[200:203], v[112:115]
	v_mfma_f32_16x16x32_bf16 v[104:107], v[184:187], v[200:203], v[104:107]
	v_mfma_f32_16x16x32_bf16 v[96:99], v[170:173], v[224:227], v[96:99]
	v_mfma_f32_16x16x32_bf16 v[88:91], v[184:187], v[224:227], v[88:91]
	v_mfma_f32_16x16x32_bf16 v[80:83], v[170:173], v[228:231], v[80:83]
	v_mfma_f32_16x16x32_bf16 v[72:75], v[184:187], v[228:231], v[72:75]
	s_barrier
	s_setprio 0
	s_add_i32 s31, s31, s33
	s_add_i32 m0, s31, 0xffffff80
	ds_read_b128 v[188:191], v147 offset:49152
	ds_read_b128 v[192:195], v147 offset:51200
	ds_read_b128 v[196:199], v148 offset:49152
	ds_read_b128 v[200:203], v148 offset:51200
	ds_read_b128 v[204:207], v147 offset:53248
	ds_read_b128 v[208:211], v147 offset:55296
	ds_read_b128 v[224:227], v148 offset:53248
	ds_read_b128 v[228:231], v148 offset:55296
	global_load_lds_dwordx4 v34, s[28:29] offset:128
	s_add_i32 m0, s31, 0x1f80
	s_mov_b64 s[98:99], s[28:29]
	s_add_u32 s28, s28, 0x80080
	s_addc_u32 s29, s29, 0
	s_add_i32 s31, s54, s33
	global_load_lds_dwordx4 v140, s[98:99] offset:128
	s_mov_b32 m0, s31
	s_nop 0
	global_load_lds_dwordx4 v34, s[28:29]
	s_add_i32 m0, s31, 0x2000
	s_nop 0
	global_load_lds_dwordx4 v140, s[28:29]
	s_add_i32 m0, s48, 0xffffff80
	s_nop 0
	global_load_lds_dwordx4 v144, s[100:101] offset:128
	s_add_i32 m0, s49, 0xffffff80
	s_nop 0
	global_load_lds_dwordx4 v142, s[100:101] offset:128
	s_waitcnt vmcnt(8)
	s_waitcnt lgkmcnt(0)
	s_setprio 1
	s_barrier
	v_mfma_f32_16x16x32_bf16 v[60:63], v[150:153], v[188:191], v[60:63]
	v_mfma_f32_16x16x32_bf16 v[52:55], v[158:161], v[188:191], v[52:55]
	v_mfma_f32_16x16x32_bf16 v[44:47], v[150:153], v[192:195], v[44:47]
	v_mfma_f32_16x16x32_bf16 v[36:39], v[158:161], v[192:195], v[36:39]
	v_mfma_f32_16x16x32_bf16 v[26:29], v[150:153], v[204:207], v[26:29]
	v_mfma_f32_16x16x32_bf16 v[18:21], v[158:161], v[204:207], v[18:21]
	v_mfma_f32_16x16x32_bf16 v[10:13], v[150:153], v[208:211], v[10:13]
	v_mfma_f32_16x16x32_bf16 v[6:9], v[158:161], v[208:211], v[6:9]
	v_mfma_f32_16x16x32_bf16 v[60:63], v[154:157], v[196:199], v[60:63]
	v_mfma_f32_16x16x32_bf16 v[52:55], v[162:165], v[196:199], v[52:55]
	v_mfma_f32_16x16x32_bf16 v[44:47], v[154:157], v[200:203], v[44:47]
	v_mfma_f32_16x16x32_bf16 v[36:39], v[162:165], v[200:203], v[36:39]
	v_mfma_f32_16x16x32_bf16 v[26:29], v[154:157], v[224:227], v[26:29]
	v_mfma_f32_16x16x32_bf16 v[18:21], v[162:165], v[224:227], v[18:21]
	v_mfma_f32_16x16x32_bf16 v[10:13], v[154:157], v[228:231], v[10:13]
	v_mfma_f32_16x16x32_bf16 v[6:9], v[162:165], v[228:231], v[6:9]
	s_setprio 0
	s_setprio 1
	v_mfma_f32_16x16x32_bf16 v[64:67], v[166:169], v[188:191], v[64:67]
	v_mfma_f32_16x16x32_bf16 v[56:59], v[174:177], v[188:191], v[56:59]
	v_mfma_f32_16x16x32_bf16 v[48:51], v[166:169], v[192:195], v[48:51]
	v_mfma_f32_16x16x32_bf16 v[40:43], v[174:177], v[192:195], v[40:43]
	v_mfma_f32_16x16x32_bf16 v[30:33], v[166:169], v[204:207], v[30:33]
	v_mfma_f32_16x16x32_bf16 v[22:25], v[174:177], v[204:207], v[22:25]
	v_mfma_f32_16x16x32_bf16 v[14:17], v[166:169], v[208:211], v[14:17]
	v_mfma_f32_16x16x32_bf16 v[2:5], v[174:177], v[208:211], v[2:5]
	v_mfma_f32_16x16x32_bf16 v[64:67], v[170:173], v[196:199], v[64:67]
	v_mfma_f32_16x16x32_bf16 v[56:59], v[184:187], v[196:199], v[56:59]
	v_mfma_f32_16x16x32_bf16 v[48:51], v[170:173], v[200:203], v[48:51]
	v_mfma_f32_16x16x32_bf16 v[40:43], v[184:187], v[200:203], v[40:43]
	v_mfma_f32_16x16x32_bf16 v[30:33], v[170:173], v[224:227], v[30:33]
	v_mfma_f32_16x16x32_bf16 v[22:25], v[184:187], v[224:227], v[22:25]
	v_mfma_f32_16x16x32_bf16 v[14:17], v[170:173], v[228:231], v[14:17]
	v_mfma_f32_16x16x32_bf16 v[2:5], v[184:187], v[228:231], v[2:5]
	s_barrier
	s_setprio 0
	s_add_i32 s30, s30, 2
	s_add_u32 s8, s8, 0x100
	s_addc_u32 s9, s9, 0
	s_add_u32 s24, s24, 0x100
	s_addc_u32 s25, s25, 0
	s_cmp_gt_u32 s30, 29
	s_cbranch_scc1 .Lpeel_done_P6
.LBB0_1114:
	s_add_u32 s28, s8, 0xfff80080
	s_addc_u32 s29, s9, -1
	s_add_i32 s31, 0, 0x10000
	s_cmp_eq_u32 s30, 28
	s_cselect_b32 s43, s13, s29
	s_cselect_b32 s42, s19, s28
	ds_read_b128 v[150:153], v1
	ds_read_b128 v[154:157], v146
	s_cselect_b32 s29, s20, s25
	s_cselect_b32 s28, s21, s24
	s_add_i32 s56, 0, 0x14000
	ds_read_b128 v[158:161], v1 offset:2048
	ds_read_b128 v[162:165], v146 offset:2048
	ds_read_b128 v[166:169], v1 offset:16384
	ds_read_b128 v[170:173], v146 offset:16384
	ds_read_b128 v[174:177], v1 offset:18432
	ds_read_b128 v[184:187], v146 offset:18432
	s_add_i32 m0, s34, 0xc000
	ds_read_b128 v[188:191], v147
	ds_read_b128 v[192:195], v147 offset:2048
	ds_read_b128 v[196:199], v148
	ds_read_b128 v[200:203], v148 offset:2048
	ds_read_b128 v[204:207], v147 offset:4096
	ds_read_b128 v[208:211], v147 offset:6144
	ds_read_b128 v[224:227], v148 offset:4096
	ds_read_b128 v[228:231], v148 offset:6144
	global_load_lds_dwordx4 v144, s[8:9]
	s_add_i32 m0, s34, 0xe000
	s_nop 0
	global_load_lds_dwordx4 v142, s[8:9]
	s_waitcnt vmcnt(8)
	s_waitcnt lgkmcnt(0)
	s_setprio 1
	s_barrier
	v_mfma_f32_16x16x32_bf16 v[132:135], v[150:153], v[188:191], v[132:135]
	v_mfma_f32_16x16x32_bf16 v[124:127], v[158:161], v[188:191], v[124:127]
	v_mfma_f32_16x16x32_bf16 v[108:111], v[150:153], v[192:195], v[108:111]
	v_mfma_f32_16x16x32_bf16 v[100:103], v[158:161], v[192:195], v[100:103]
	v_mfma_f32_16x16x32_bf16 v[92:95], v[150:153], v[204:207], v[92:95]
	v_mfma_f32_16x16x32_bf16 v[84:87], v[158:161], v[204:207], v[84:87]
	v_mfma_f32_16x16x32_bf16 v[76:79], v[150:153], v[208:211], v[76:79]
	v_mfma_f32_16x16x32_bf16 v[68:71], v[158:161], v[208:211], v[68:71]
	v_mfma_f32_16x16x32_bf16 v[132:135], v[154:157], v[196:199], v[132:135]
	v_mfma_f32_16x16x32_bf16 v[124:127], v[162:165], v[196:199], v[124:127]
	v_mfma_f32_16x16x32_bf16 v[108:111], v[154:157], v[200:203], v[108:111]
	v_mfma_f32_16x16x32_bf16 v[100:103], v[162:165], v[200:203], v[100:103]
	v_mfma_f32_16x16x32_bf16 v[92:95], v[154:157], v[224:227], v[92:95]
	v_mfma_f32_16x16x32_bf16 v[84:87], v[162:165], v[224:227], v[84:87]
	v_mfma_f32_16x16x32_bf16 v[76:79], v[154:157], v[228:231], v[76:79]
	v_mfma_f32_16x16x32_bf16 v[68:71], v[162:165], v[228:231], v[68:71]
	s_setprio 0
	s_setprio 1
	v_mfma_f32_16x16x32_bf16 v[136:139], v[166:169], v[188:191], v[136:139]
	v_mfma_f32_16x16x32_bf16 v[128:131], v[174:177], v[188:191], v[128:131]
	v_mfma_f32_16x16x32_bf16 v[112:115], v[166:169], v[192:195], v[112:115]
	v_mfma_f32_16x16x32_bf16 v[104:107], v[174:177], v[192:195], v[104:107]
	v_mfma_f32_16x16x32_bf16 v[96:99], v[166:169], v[204:207], v[96:99]
	v_mfma_f32_16x16x32_bf16 v[88:91], v[174:177], v[204:207], v[88:91]
	v_mfma_f32_16x16x32_bf16 v[80:83], v[166:169], v[208:211], v[80:83]
	v_mfma_f32_16x16x32_bf16 v[72:75], v[174:177], v[208:211], v[72:75]
	v_mfma_f32_16x16x32_bf16 v[136:139], v[170:173], v[196:199], v[136:139]
	v_mfma_f32_16x16x32_bf16 v[128:131], v[184:187], v[196:199], v[128:131]
	v_mfma_f32_16x16x32_bf16 v[112:115], v[170:173], v[200:203], v[112:115]
	v_mfma_f32_16x16x32_bf16 v[104:107], v[184:187], v[200:203], v[104:107]
	v_mfma_f32_16x16x32_bf16 v[96:99], v[170:173], v[224:227], v[96:99]
	v_mfma_f32_16x16x32_bf16 v[88:91], v[184:187], v[224:227], v[88:91]
	v_mfma_f32_16x16x32_bf16 v[80:83], v[170:173], v[228:231], v[80:83]
	v_mfma_f32_16x16x32_bf16 v[72:75], v[184:187], v[228:231], v[72:75]
	s_barrier
	s_setprio 0
	s_add_i32 s31, s31, s33
	s_mov_b32 m0, s31
	ds_read_b128 v[188:191], v147 offset:16384
	ds_read_b128 v[192:195], v147 offset:18432
	ds_read_b128 v[196:199], v148 offset:16384
	ds_read_b128 v[200:203], v148 offset:18432
	ds_read_b128 v[204:207], v147 offset:20480
	ds_read_b128 v[208:211], v147 offset:22528
	ds_read_b128 v[224:227], v148 offset:20480
	ds_read_b128 v[228:231], v148 offset:22528
	global_load_lds_dwordx4 v34, s[28:29]
	s_add_i32 m0, s31, 0x2000
	s_add_u32 s54, s28, 0x80000
	s_addc_u32 s55, s29, 0
	s_add_i32 s31, s56, s33
	global_load_lds_dwordx4 v140, s[28:29]
	s_mov_b32 m0, s31
	s_nop 0
	global_load_lds_dwordx4 v34, s[54:55]
	s_add_i32 m0, s31, 0x2000
	s_nop 0
	global_load_lds_dwordx4 v140, s[54:55]
	s_mov_b32 m0, s34
	s_nop 0
	global_load_lds_dwordx4 v144, s[42:43]
	s_mov_b32 m0, s35
	s_nop 0
	global_load_lds_dwordx4 v142, s[42:43]
	s_waitcnt vmcnt(8)
	s_waitcnt lgkmcnt(0)
	s_setprio 1
	s_barrier
	v_mfma_f32_16x16x32_bf16 v[60:63], v[150:153], v[188:191], v[60:63]
	v_mfma_f32_16x16x32_bf16 v[52:55], v[158:161], v[188:191], v[52:55]
	v_mfma_f32_16x16x32_bf16 v[44:47], v[150:153], v[192:195], v[44:47]
	v_mfma_f32_16x16x32_bf16 v[36:39], v[158:161], v[192:195], v[36:39]
	v_mfma_f32_16x16x32_bf16 v[26:29], v[150:153], v[204:207], v[26:29]
	v_mfma_f32_16x16x32_bf16 v[18:21], v[158:161], v[204:207], v[18:21]
	v_mfma_f32_16x16x32_bf16 v[10:13], v[150:153], v[208:211], v[10:13]
	v_mfma_f32_16x16x32_bf16 v[6:9], v[158:161], v[208:211], v[6:9]
	v_mfma_f32_16x16x32_bf16 v[60:63], v[154:157], v[196:199], v[60:63]
	v_mfma_f32_16x16x32_bf16 v[52:55], v[162:165], v[196:199], v[52:55]
	v_mfma_f32_16x16x32_bf16 v[44:47], v[154:157], v[200:203], v[44:47]
	v_mfma_f32_16x16x32_bf16 v[36:39], v[162:165], v[200:203], v[36:39]
	v_mfma_f32_16x16x32_bf16 v[26:29], v[154:157], v[224:227], v[26:29]
	v_mfma_f32_16x16x32_bf16 v[18:21], v[162:165], v[224:227], v[18:21]
	v_mfma_f32_16x16x32_bf16 v[10:13], v[154:157], v[228:231], v[10:13]
	v_mfma_f32_16x16x32_bf16 v[6:9], v[162:165], v[228:231], v[6:9]
	s_setprio 0
	s_setprio 1
	v_mfma_f32_16x16x32_bf16 v[64:67], v[166:169], v[188:191], v[64:67]
	v_mfma_f32_16x16x32_bf16 v[56:59], v[174:177], v[188:191], v[56:59]
	v_mfma_f32_16x16x32_bf16 v[48:51], v[166:169], v[192:195], v[48:51]
	v_mfma_f32_16x16x32_bf16 v[40:43], v[174:177], v[192:195], v[40:43]
	v_mfma_f32_16x16x32_bf16 v[30:33], v[166:169], v[204:207], v[30:33]
	v_mfma_f32_16x16x32_bf16 v[22:25], v[174:177], v[204:207], v[22:25]
	v_mfma_f32_16x16x32_bf16 v[14:17], v[166:169], v[208:211], v[14:17]
	v_mfma_f32_16x16x32_bf16 v[2:5], v[174:177], v[208:211], v[2:5]
	v_mfma_f32_16x16x32_bf16 v[64:67], v[170:173], v[196:199], v[64:67]
	v_mfma_f32_16x16x32_bf16 v[56:59], v[184:187], v[196:199], v[56:59]
	v_mfma_f32_16x16x32_bf16 v[48:51], v[170:173], v[200:203], v[48:51]
	v_mfma_f32_16x16x32_bf16 v[40:43], v[184:187], v[200:203], v[40:43]
	v_mfma_f32_16x16x32_bf16 v[30:33], v[170:173], v[224:227], v[30:33]
	v_mfma_f32_16x16x32_bf16 v[22:25], v[184:187], v[224:227], v[22:25]
	v_mfma_f32_16x16x32_bf16 v[14:17], v[170:173], v[228:231], v[14:17]
	v_mfma_f32_16x16x32_bf16 v[2:5], v[184:187], v[228:231], v[2:5]
	s_barrier
	s_setprio 0
	s_add_i32 s31, 0, 0x18000
	ds_read_b128 v[150:153], v1 offset:32768
	ds_read_b128 v[154:157], v146 offset:32768
	s_add_i32 s54, 0, 0x1c000
	ds_read_b128 v[158:161], v1 offset:34816
	ds_read_b128 v[162:165], v146 offset:34816
	ds_read_b128 v[166:169], v1 offset:49152
	ds_read_b128 v[170:173], v146 offset:49152
	ds_read_b128 v[174:177], v1 offset:51200
	ds_read_b128 v[184:187], v146 offset:51200
	s_mov_b64 s[100:101], s[42:43]
	s_add_u32 s42, s42, 0x80000
	s_addc_u32 s43, s43, 0
	s_mov_b32 m0, s44
	ds_read_b128 v[188:191], v147 offset:32768
	ds_read_b128 v[192:195], v147 offset:34816
	ds_read_b128 v[196:199], v148 offset:32768
	ds_read_b128 v[200:203], v148 offset:34816
	ds_read_b128 v[204:207], v147 offset:36864
	ds_read_b128 v[208:211], v147 offset:38912
	ds_read_b128 v[224:227], v148 offset:36864
	ds_read_b128 v[228:231], v148 offset:38912
	global_load_lds_dwordx4 v144, s[42:43]
	s_mov_b32 m0, s45
	s_nop 0
	global_load_lds_dwordx4 v142, s[42:43]
	s_waitcnt vmcnt(8)
	s_waitcnt lgkmcnt(0)
	s_setprio 1
	s_barrier
	v_mfma_f32_16x16x32_bf16 v[132:135], v[150:153], v[188:191], v[132:135]
	v_mfma_f32_16x16x32_bf16 v[124:127], v[158:161], v[188:191], v[124:127]
	v_mfma_f32_16x16x32_bf16 v[108:111], v[150:153], v[192:195], v[108:111]
	v_mfma_f32_16x16x32_bf16 v[100:103], v[158:161], v[192:195], v[100:103]
	v_mfma_f32_16x16x32_bf16 v[92:95], v[150:153], v[204:207], v[92:95]
	v_mfma_f32_16x16x32_bf16 v[84:87], v[158:161], v[204:207], v[84:87]
	v_mfma_f32_16x16x32_bf16 v[76:79], v[150:153], v[208:211], v[76:79]
	v_mfma_f32_16x16x32_bf16 v[68:71], v[158:161], v[208:211], v[68:71]
	v_mfma_f32_16x16x32_bf16 v[132:135], v[154:157], v[196:199], v[132:135]
	v_mfma_f32_16x16x32_bf16 v[124:127], v[162:165], v[196:199], v[124:127]
	v_mfma_f32_16x16x32_bf16 v[108:111], v[154:157], v[200:203], v[108:111]
	v_mfma_f32_16x16x32_bf16 v[100:103], v[162:165], v[200:203], v[100:103]
	v_mfma_f32_16x16x32_bf16 v[92:95], v[154:157], v[224:227], v[92:95]
	v_mfma_f32_16x16x32_bf16 v[84:87], v[162:165], v[224:227], v[84:87]
	v_mfma_f32_16x16x32_bf16 v[76:79], v[154:157], v[228:231], v[76:79]
	v_mfma_f32_16x16x32_bf16 v[68:71], v[162:165], v[228:231], v[68:71]
	s_setprio 0
	s_setprio 1
	v_mfma_f32_16x16x32_bf16 v[136:139], v[166:169], v[188:191], v[136:139]
	v_mfma_f32_16x16x32_bf16 v[128:131], v[174:177], v[188:191], v[128:131]
	v_mfma_f32_16x16x32_bf16 v[112:115], v[166:169], v[192:195], v[112:115]
	v_mfma_f32_16x16x32_bf16 v[104:107], v[174:177], v[192:195], v[104:107]
	v_mfma_f32_16x16x32_bf16 v[96:99], v[166:169], v[204:207], v[96:99]
	v_mfma_f32_16x16x32_bf16 v[88:91], v[174:177], v[204:207], v[88:91]
	v_mfma_f32_16x16x32_bf16 v[80:83], v[166:169], v[208:211], v[80:83]
	v_mfma_f32_16x16x32_bf16 v[72:75], v[174:177], v[208:211], v[72:75]
	v_mfma_f32_16x16x32_bf16 v[136:139], v[170:173], v[196:199], v[136:139]
	v_mfma_f32_16x16x32_bf16 v[128:131], v[184:187], v[196:199], v[128:131]
	v_mfma_f32_16x16x32_bf16 v[112:115], v[170:173], v[200:203], v[112:115]
	v_mfma_f32_16x16x32_bf16 v[104:107], v[184:187], v[200:203], v[104:107]
	v_mfma_f32_16x16x32_bf16 v[96:99], v[170:173], v[224:227], v[96:99]
	v_mfma_f32_16x16x32_bf16 v[88:91], v[184:187], v[224:227], v[88:91]
	v_mfma_f32_16x16x32_bf16 v[80:83], v[170:173], v[228:231], v[80:83]
	v_mfma_f32_16x16x32_bf16 v[72:75], v[184:187], v[228:231], v[72:75]
	s_barrier
	s_setprio 0
	s_add_i32 s31, s31, s33
	s_add_i32 m0, s31, 0xffffff80
	ds_read_b128 v[188:191], v147 offset:49152
	ds_read_b128 v[192:195], v147 offset:51200
	ds_read_b128 v[196:199], v148 offset:49152
	ds_read_b128 v[200:203], v148 offset:51200
	ds_read_b128 v[204:207], v147 offset:53248
	ds_read_b128 v[208:211], v147 offset:55296
	ds_read_b128 v[224:227], v148 offset:53248
	ds_read_b128 v[228:231], v148 offset:55296
	global_load_lds_dwordx4 v34, s[28:29] offset:128
	s_add_i32 m0, s31, 0x1f80
	s_mov_b64 s[98:99], s[28:29]
	s_add_u32 s28, s28, 0x80080
	s_addc_u32 s29, s29, 0
	s_add_i32 s31, s54, s33
	global_load_lds_dwordx4 v140, s[98:99] offset:128
	s_mov_b32 m0, s31
	s_nop 0
	global_load_lds_dwordx4 v34, s[28:29]
	s_add_i32 m0, s31, 0x2000
	s_nop 0
	global_load_lds_dwordx4 v140, s[28:29]
	s_add_i32 m0, s48, 0xffffff80
	s_nop 0
	global_load_lds_dwordx4 v144, s[100:101] offset:128
	s_add_i32 m0, s49, 0xffffff80
	s_nop 0
	global_load_lds_dwordx4 v142, s[100:101] offset:128
	s_waitcnt vmcnt(8)
	s_waitcnt lgkmcnt(0)
	s_setprio 1
	s_barrier
	v_mfma_f32_16x16x32_bf16 v[60:63], v[150:153], v[188:191], v[60:63]
	v_mfma_f32_16x16x32_bf16 v[52:55], v[158:161], v[188:191], v[52:55]
	v_mfma_f32_16x16x32_bf16 v[44:47], v[150:153], v[192:195], v[44:47]
	v_mfma_f32_16x16x32_bf16 v[36:39], v[158:161], v[192:195], v[36:39]
	v_mfma_f32_16x16x32_bf16 v[26:29], v[150:153], v[204:207], v[26:29]
	v_mfma_f32_16x16x32_bf16 v[18:21], v[158:161], v[204:207], v[18:21]
	v_mfma_f32_16x16x32_bf16 v[10:13], v[150:153], v[208:211], v[10:13]
	v_mfma_f32_16x16x32_bf16 v[6:9], v[158:161], v[208:211], v[6:9]
	v_mfma_f32_16x16x32_bf16 v[60:63], v[154:157], v[196:199], v[60:63]
	v_mfma_f32_16x16x32_bf16 v[52:55], v[162:165], v[196:199], v[52:55]
	v_mfma_f32_16x16x32_bf16 v[44:47], v[154:157], v[200:203], v[44:47]
	v_mfma_f32_16x16x32_bf16 v[36:39], v[162:165], v[200:203], v[36:39]
	v_mfma_f32_16x16x32_bf16 v[26:29], v[154:157], v[224:227], v[26:29]
	v_mfma_f32_16x16x32_bf16 v[18:21], v[162:165], v[224:227], v[18:21]
	v_mfma_f32_16x16x32_bf16 v[10:13], v[154:157], v[228:231], v[10:13]
	v_mfma_f32_16x16x32_bf16 v[6:9], v[162:165], v[228:231], v[6:9]
	s_setprio 0
	s_setprio 1
	v_mfma_f32_16x16x32_bf16 v[64:67], v[166:169], v[188:191], v[64:67]
	v_mfma_f32_16x16x32_bf16 v[56:59], v[174:177], v[188:191], v[56:59]
	v_mfma_f32_16x16x32_bf16 v[48:51], v[166:169], v[192:195], v[48:51]
	v_mfma_f32_16x16x32_bf16 v[40:43], v[174:177], v[192:195], v[40:43]
	v_mfma_f32_16x16x32_bf16 v[30:33], v[166:169], v[204:207], v[30:33]
	v_mfma_f32_16x16x32_bf16 v[22:25], v[174:177], v[204:207], v[22:25]
	v_mfma_f32_16x16x32_bf16 v[14:17], v[166:169], v[208:211], v[14:17]
	v_mfma_f32_16x16x32_bf16 v[2:5], v[174:177], v[208:211], v[2:5]
	v_mfma_f32_16x16x32_bf16 v[64:67], v[170:173], v[196:199], v[64:67]
	v_mfma_f32_16x16x32_bf16 v[56:59], v[184:187], v[196:199], v[56:59]
	v_mfma_f32_16x16x32_bf16 v[48:51], v[170:173], v[200:203], v[48:51]
	v_mfma_f32_16x16x32_bf16 v[40:43], v[184:187], v[200:203], v[40:43]
	v_mfma_f32_16x16x32_bf16 v[30:33], v[170:173], v[224:227], v[30:33]
	v_mfma_f32_16x16x32_bf16 v[22:25], v[184:187], v[224:227], v[22:25]
	v_mfma_f32_16x16x32_bf16 v[14:17], v[170:173], v[228:231], v[14:17]
	v_mfma_f32_16x16x32_bf16 v[2:5], v[184:187], v[228:231], v[2:5]
	s_barrier
	s_setprio 0
	s_add_i32 s30, s30, 2
	s_add_u32 s8, s8, 0x100
	s_addc_u32 s9, s9, 0
	s_add_u32 s24, s24, 0x100
	s_addc_u32 s25, s25, 0
	s_cmp_gt_u32 s30, 29
	s_cbranch_scc0 .LBB0_1114

.LBB0_1194:
	s_add_u32 s8, s8, 0x160080
	s_addc_u32 s9, s9, 0
	s_add_u32 s20, s18, 0x100
	s_addc_u32 s21, s19, 0
	s_mov_b32 s24, -2
	v_readlane_b32 s35, v255, 20
	v_readlane_b32 s40, v255, 21
	v_readlane_b32 s41, v255, 22
	v_readlane_b32 s57, v255, 23
	s_mov_b64 s[58:59], 0x80
	s_add_u32 s18, s8, 0xffea0080
	s_addc_u32 s19, s9, -1
	s_add_i32 s25, 0, 0x10000
	s_cmpk_eq_i32 s24, 0x54
	s_cselect_b32 s23, s45, s19
	s_cselect_b32 s22, s44, s18
	s_cselect_b32 s19, s47, s21
	s_cselect_b32 s18, s46, s20
	s_add_i32 s34, 0, 0x14000
	ds_read_b128 v[138:141], v1
	ds_read_b128 v[142:145], v160
	ds_read_b128 v[146:149], v1 offset:2048
	ds_read_b128 v[150:153], v160 offset:2048
	ds_read_b128 v[154:157], v1 offset:16384
	ds_read_b128 v[164:167], v160 offset:16384
	ds_read_b128 v[168:171], v1 offset:18432
	ds_read_b128 v[172:175], v160 offset:18432
	s_add_i32 m0, s29, 0xc000
	ds_read_b128 v[176:179], v161
	ds_read_b128 v[184:187], v161 offset:2048
	ds_read_b128 v[188:191], v162
	ds_read_b128 v[192:195], v162 offset:2048
	ds_read_b128 v[196:199], v161 offset:4096
	ds_read_b128 v[200:203], v161 offset:6144
	ds_read_b128 v[204:207], v162 offset:4096
	ds_read_b128 v[208:211], v162 offset:6144
	global_load_lds_dwordx4 v136, s[8:9]
	s_add_i32 m0, s29, 0xe000
	s_nop 0
	global_load_lds_dwordx4 v134, s[8:9]
	s_waitcnt vmcnt(8)
	s_waitcnt lgkmcnt(0)
	s_setprio 1
	s_barrier
	v_mfma_f32_16x16x32_bf16 v[128:131], v[138:141], v[176:179], 0
	v_mfma_f32_16x16x32_bf16 v[124:127], v[146:149], v[176:179], 0
	v_mfma_f32_16x16x32_bf16 v[112:115], v[138:141], v[184:187], 0
	v_mfma_f32_16x16x32_bf16 v[108:111], v[146:149], v[184:187], 0
	v_mfma_f32_16x16x32_bf16 v[96:99], v[138:141], v[196:199], 0
	v_mfma_f32_16x16x32_bf16 v[92:95], v[146:149], v[196:199], 0
	v_mfma_f32_16x16x32_bf16 v[80:83], v[138:141], v[200:203], 0
	v_mfma_f32_16x16x32_bf16 v[76:79], v[146:149], v[200:203], 0
	v_mfma_f32_16x16x32_bf16 v[128:131], v[142:145], v[188:191], v[128:131]
	v_mfma_f32_16x16x32_bf16 v[124:127], v[150:153], v[188:191], v[124:127]
	v_mfma_f32_16x16x32_bf16 v[112:115], v[142:145], v[192:195], v[112:115]
	v_mfma_f32_16x16x32_bf16 v[108:111], v[150:153], v[192:195], v[108:111]
	v_mfma_f32_16x16x32_bf16 v[96:99], v[142:145], v[204:207], v[96:99]
	v_mfma_f32_16x16x32_bf16 v[92:95], v[150:153], v[204:207], v[92:95]
	v_mfma_f32_16x16x32_bf16 v[80:83], v[142:145], v[208:211], v[80:83]
	v_mfma_f32_16x16x32_bf16 v[76:79], v[150:153], v[208:211], v[76:79]
	s_setprio 0
	s_setprio 1
	v_mfma_f32_16x16x32_bf16 v[120:123], v[154:157], v[176:179], 0
	v_mfma_f32_16x16x32_bf16 v[116:119], v[168:171], v[176:179], 0
	v_mfma_f32_16x16x32_bf16 v[104:107], v[154:157], v[184:187], 0
	v_mfma_f32_16x16x32_bf16 v[100:103], v[168:171], v[184:187], 0
	v_mfma_f32_16x16x32_bf16 v[88:91], v[154:157], v[196:199], 0
	v_mfma_f32_16x16x32_bf16 v[84:87], v[168:171], v[196:199], 0
	v_mfma_f32_16x16x32_bf16 v[72:75], v[154:157], v[200:203], 0
	v_mfma_f32_16x16x32_bf16 v[68:71], v[168:171], v[200:203], 0
	v_mfma_f32_16x16x32_bf16 v[120:123], v[164:167], v[188:191], v[120:123]
	v_mfma_f32_16x16x32_bf16 v[116:119], v[172:175], v[188:191], v[116:119]
	v_mfma_f32_16x16x32_bf16 v[104:107], v[164:167], v[192:195], v[104:107]
	v_mfma_f32_16x16x32_bf16 v[100:103], v[172:175], v[192:195], v[100:103]
	v_mfma_f32_16x16x32_bf16 v[88:91], v[164:167], v[204:207], v[88:91]
	v_mfma_f32_16x16x32_bf16 v[84:87], v[172:175], v[204:207], v[84:87]
	v_mfma_f32_16x16x32_bf16 v[72:75], v[164:167], v[208:211], v[72:75]
	v_mfma_f32_16x16x32_bf16 v[68:71], v[172:175], v[208:211], v[68:71]
	s_barrier
	s_setprio 0
	s_add_i32 s25, s25, s28
	s_mov_b32 m0, s25
	ds_read_b128 v[176:179], v161 offset:16384
	ds_read_b128 v[184:187], v161 offset:18432
	ds_read_b128 v[188:191], v162 offset:16384
	ds_read_b128 v[192:195], v162 offset:18432
	ds_read_b128 v[196:199], v161 offset:20480
	ds_read_b128 v[200:203], v161 offset:22528
	ds_read_b128 v[204:207], v162 offset:20480
	ds_read_b128 v[208:211], v162 offset:22528
	global_load_lds_dwordx4 v34, s[18:19]
	s_add_i32 m0, s25, 0x2000
	s_add_u32 s30, s18, 0x160000
	s_addc_u32 s31, s19, 0
	s_add_i32 s25, s34, s28
	global_load_lds_dwordx4 v132, s[18:19]
	s_mov_b32 m0, s25
	s_nop 0
	global_load_lds_dwordx4 v34, s[30:31]
	s_add_i32 m0, s25, 0x2000
	s_nop 0
	global_load_lds_dwordx4 v132, s[30:31]
	s_mov_b32 m0, s29
	s_nop 0
	global_load_lds_dwordx4 v136, s[22:23]
	s_mov_b32 m0, s33
	s_nop 0
	global_load_lds_dwordx4 v134, s[22:23]
	s_waitcnt vmcnt(8)
	s_waitcnt lgkmcnt(0)
	s_setprio 1
	s_barrier
	v_mfma_f32_16x16x32_bf16 v[64:67], v[138:141], v[176:179], 0
	v_mfma_f32_16x16x32_bf16 v[60:63], v[146:149], v[176:179], 0
	v_mfma_f32_16x16x32_bf16 v[48:51], v[138:141], v[184:187], 0
	v_mfma_f32_16x16x32_bf16 v[44:47], v[146:149], v[184:187], 0
	v_mfma_f32_16x16x32_bf16 v[30:33], v[138:141], v[196:199], 0
	v_mfma_f32_16x16x32_bf16 v[26:29], v[146:149], v[196:199], 0
	v_mfma_f32_16x16x32_bf16 v[14:17], v[138:141], v[200:203], 0
	v_mfma_f32_16x16x32_bf16 v[10:13], v[146:149], v[200:203], 0
	v_mfma_f32_16x16x32_bf16 v[64:67], v[142:145], v[188:191], v[64:67]
	v_mfma_f32_16x16x32_bf16 v[60:63], v[150:153], v[188:191], v[60:63]
	v_mfma_f32_16x16x32_bf16 v[48:51], v[142:145], v[192:195], v[48:51]
	v_mfma_f32_16x16x32_bf16 v[44:47], v[150:153], v[192:195], v[44:47]
	v_mfma_f32_16x16x32_bf16 v[30:33], v[142:145], v[204:207], v[30:33]
	v_mfma_f32_16x16x32_bf16 v[26:29], v[150:153], v[204:207], v[26:29]
	v_mfma_f32_16x16x32_bf16 v[14:17], v[142:145], v[208:211], v[14:17]
	v_mfma_f32_16x16x32_bf16 v[10:13], v[150:153], v[208:211], v[10:13]
	s_setprio 0
	s_setprio 1
	v_mfma_f32_16x16x32_bf16 v[56:59], v[154:157], v[176:179], 0
	v_mfma_f32_16x16x32_bf16 v[52:55], v[168:171], v[176:179], 0
	v_mfma_f32_16x16x32_bf16 v[40:43], v[154:157], v[184:187], 0
	v_mfma_f32_16x16x32_bf16 v[36:39], v[168:171], v[184:187], 0
	v_mfma_f32_16x16x32_bf16 v[22:25], v[154:157], v[196:199], 0
	v_mfma_f32_16x16x32_bf16 v[18:21], v[168:171], v[196:199], 0
	v_mfma_f32_16x16x32_bf16 v[6:9], v[154:157], v[200:203], 0
	v_mfma_f32_16x16x32_bf16 v[2:5], v[168:171], v[200:203], 0
	v_mfma_f32_16x16x32_bf16 v[56:59], v[164:167], v[188:191], v[56:59]
	v_mfma_f32_16x16x32_bf16 v[52:55], v[172:175], v[188:191], v[52:55]
	v_mfma_f32_16x16x32_bf16 v[40:43], v[164:167], v[192:195], v[40:43]
	v_mfma_f32_16x16x32_bf16 v[36:39], v[172:175], v[192:195], v[36:39]
	v_mfma_f32_16x16x32_bf16 v[22:25], v[164:167], v[204:207], v[22:25]
	v_mfma_f32_16x16x32_bf16 v[18:21], v[172:175], v[204:207], v[18:21]
	v_mfma_f32_16x16x32_bf16 v[6:9], v[164:167], v[208:211], v[6:9]
	v_mfma_f32_16x16x32_bf16 v[2:5], v[172:175], v[208:211], v[2:5]
	s_barrier
	s_setprio 0
	s_add_i32 s25, 0, 0x18000
	s_add_i32 s30, 0, 0x1c000
	ds_read_b128 v[138:141], v1 offset:32768
	ds_read_b128 v[142:145], v160 offset:32768
	ds_read_b128 v[146:149], v1 offset:34816
	ds_read_b128 v[150:153], v160 offset:34816
	ds_read_b128 v[154:157], v1 offset:49152
	ds_read_b128 v[164:167], v160 offset:49152
	ds_read_b128 v[168:171], v1 offset:51200
	ds_read_b128 v[172:175], v160 offset:51200
	s_mov_b64 s[100:101], s[22:23]
	s_add_u32 s22, s22, 0x160000
	s_addc_u32 s23, s23, 0
	s_mov_b32 m0, s48
	ds_read_b128 v[176:179], v161 offset:32768
	ds_read_b128 v[184:187], v161 offset:34816
	ds_read_b128 v[188:191], v162 offset:32768
	ds_read_b128 v[192:195], v162 offset:34816
	ds_read_b128 v[196:199], v161 offset:36864
	ds_read_b128 v[200:203], v161 offset:38912
	ds_read_b128 v[204:207], v162 offset:36864
	ds_read_b128 v[208:211], v162 offset:38912
	global_load_lds_dwordx4 v136, s[22:23]
	s_mov_b32 m0, s49
	s_nop 0
	global_load_lds_dwordx4 v134, s[22:23]
	s_waitcnt vmcnt(8)
	s_waitcnt lgkmcnt(0)
	s_setprio 1
	s_barrier
	v_mfma_f32_16x16x32_bf16 v[128:131], v[138:141], v[176:179], v[128:131]
	v_mfma_f32_16x16x32_bf16 v[124:127], v[146:149], v[176:179], v[124:127]
	v_mfma_f32_16x16x32_bf16 v[112:115], v[138:141], v[184:187], v[112:115]
	v_mfma_f32_16x16x32_bf16 v[108:111], v[146:149], v[184:187], v[108:111]
	v_mfma_f32_16x16x32_bf16 v[96:99], v[138:141], v[196:199], v[96:99]
	v_mfma_f32_16x16x32_bf16 v[92:95], v[146:149], v[196:199], v[92:95]
	v_mfma_f32_16x16x32_bf16 v[80:83], v[138:141], v[200:203], v[80:83]
	v_mfma_f32_16x16x32_bf16 v[76:79], v[146:149], v[200:203], v[76:79]
	v_mfma_f32_16x16x32_bf16 v[128:131], v[142:145], v[188:191], v[128:131]
	v_mfma_f32_16x16x32_bf16 v[124:127], v[150:153], v[188:191], v[124:127]
	v_mfma_f32_16x16x32_bf16 v[112:115], v[142:145], v[192:195], v[112:115]
	v_mfma_f32_16x16x32_bf16 v[108:111], v[150:153], v[192:195], v[108:111]
	v_mfma_f32_16x16x32_bf16 v[96:99], v[142:145], v[204:207], v[96:99]
	v_mfma_f32_16x16x32_bf16 v[92:95], v[150:153], v[204:207], v[92:95]
	v_mfma_f32_16x16x32_bf16 v[80:83], v[142:145], v[208:211], v[80:83]
	v_mfma_f32_16x16x32_bf16 v[76:79], v[150:153], v[208:211], v[76:79]
	s_setprio 0
	s_setprio 1
	v_mfma_f32_16x16x32_bf16 v[120:123], v[154:157], v[176:179], v[120:123]
	v_mfma_f32_16x16x32_bf16 v[116:119], v[168:171], v[176:179], v[116:119]
	v_mfma_f32_16x16x32_bf16 v[104:107], v[154:157], v[184:187], v[104:107]
	v_mfma_f32_16x16x32_bf16 v[100:103], v[168:171], v[184:187], v[100:103]
	v_mfma_f32_16x16x32_bf16 v[88:91], v[154:157], v[196:199], v[88:91]
	v_mfma_f32_16x16x32_bf16 v[84:87], v[168:171], v[196:199], v[84:87]
	v_mfma_f32_16x16x32_bf16 v[72:75], v[154:157], v[200:203], v[72:75]
	v_mfma_f32_16x16x32_bf16 v[68:71], v[168:171], v[200:203], v[68:71]
	v_mfma_f32_16x16x32_bf16 v[120:123], v[164:167], v[188:191], v[120:123]
	v_mfma_f32_16x16x32_bf16 v[116:119], v[172:175], v[188:191], v[116:119]
	v_mfma_f32_16x16x32_bf16 v[104:107], v[164:167], v[192:195], v[104:107]
	v_mfma_f32_16x16x32_bf16 v[100:103], v[172:175], v[192:195], v[100:103]
	v_mfma_f32_16x16x32_bf16 v[88:91], v[164:167], v[204:207], v[88:91]
	v_mfma_f32_16x16x32_bf16 v[84:87], v[172:175], v[204:207], v[84:87]
	v_mfma_f32_16x16x32_bf16 v[72:75], v[164:167], v[208:211], v[72:75]
	v_mfma_f32_16x16x32_bf16 v[68:71], v[172:175], v[208:211], v[68:71]
	s_barrier
	s_setprio 0
	s_add_i32 s22, s25, s28
	s_add_i32 m0, s22, 0xffffff80
	ds_read_b128 v[176:179], v161 offset:49152
	ds_read_b128 v[184:187], v161 offset:51200
	ds_read_b128 v[188:191], v162 offset:49152
	ds_read_b128 v[192:195], v162 offset:51200
	ds_read_b128 v[196:199], v161 offset:53248
	ds_read_b128 v[200:203], v161 offset:55296
	ds_read_b128 v[204:207], v162 offset:53248
	ds_read_b128 v[208:211], v162 offset:55296
	global_load_lds_dwordx4 v34, s[18:19] offset:128
	s_add_i32 m0, s22, 0x1f80
	s_mov_b64 s[98:99], s[18:19]
	s_add_u32 s18, s18, 0x160080
	s_addc_u32 s19, s19, 0
	s_add_i32 s22, s30, s28
	global_load_lds_dwordx4 v132, s[98:99] offset:128
	s_mov_b32 m0, s22
	s_nop 0
	global_load_lds_dwordx4 v34, s[18:19]
	s_add_i32 m0, s22, 0x2000
	s_nop 0
	global_load_lds_dwordx4 v132, s[18:19]
	s_add_i32 m0, s53, 0xffffff80
	s_nop 0
	global_load_lds_dwordx4 v136, s[100:101] offset:128
	s_add_i32 m0, s54, 0xffffff80
	s_nop 0
	global_load_lds_dwordx4 v134, s[100:101] offset:128
	s_waitcnt vmcnt(8)
	s_waitcnt lgkmcnt(0)
	s_setprio 1
	s_barrier
	v_mfma_f32_16x16x32_bf16 v[64:67], v[138:141], v[176:179], v[64:67]
	v_mfma_f32_16x16x32_bf16 v[60:63], v[146:149], v[176:179], v[60:63]
	v_mfma_f32_16x16x32_bf16 v[48:51], v[138:141], v[184:187], v[48:51]
	v_mfma_f32_16x16x32_bf16 v[44:47], v[146:149], v[184:187], v[44:47]
	v_mfma_f32_16x16x32_bf16 v[30:33], v[138:141], v[196:199], v[30:33]
	v_mfma_f32_16x16x32_bf16 v[26:29], v[146:149], v[196:199], v[26:29]
	v_mfma_f32_16x16x32_bf16 v[14:17], v[138:141], v[200:203], v[14:17]
	v_mfma_f32_16x16x32_bf16 v[10:13], v[146:149], v[200:203], v[10:13]
	v_mfma_f32_16x16x32_bf16 v[64:67], v[142:145], v[188:191], v[64:67]
	v_mfma_f32_16x16x32_bf16 v[60:63], v[150:153], v[188:191], v[60:63]
	v_mfma_f32_16x16x32_bf16 v[48:51], v[142:145], v[192:195], v[48:51]
	v_mfma_f32_16x16x32_bf16 v[44:47], v[150:153], v[192:195], v[44:47]
	v_mfma_f32_16x16x32_bf16 v[30:33], v[142:145], v[204:207], v[30:33]
	v_mfma_f32_16x16x32_bf16 v[26:29], v[150:153], v[204:207], v[26:29]
	v_mfma_f32_16x16x32_bf16 v[14:17], v[142:145], v[208:211], v[14:17]
	v_mfma_f32_16x16x32_bf16 v[10:13], v[150:153], v[208:211], v[10:13]
	s_setprio 0
	s_setprio 1
	v_mfma_f32_16x16x32_bf16 v[56:59], v[154:157], v[176:179], v[56:59]
	v_mfma_f32_16x16x32_bf16 v[52:55], v[168:171], v[176:179], v[52:55]
	v_mfma_f32_16x16x32_bf16 v[40:43], v[154:157], v[184:187], v[40:43]
	v_mfma_f32_16x16x32_bf16 v[36:39], v[168:171], v[184:187], v[36:39]
	v_mfma_f32_16x16x32_bf16 v[22:25], v[154:157], v[196:199], v[22:25]
	v_mfma_f32_16x16x32_bf16 v[18:21], v[168:171], v[196:199], v[18:21]
	v_mfma_f32_16x16x32_bf16 v[6:9], v[154:157], v[200:203], v[6:9]
	v_mfma_f32_16x16x32_bf16 v[2:5], v[168:171], v[200:203], v[2:5]
	v_mfma_f32_16x16x32_bf16 v[56:59], v[164:167], v[188:191], v[56:59]
	v_mfma_f32_16x16x32_bf16 v[52:55], v[172:175], v[188:191], v[52:55]
	v_mfma_f32_16x16x32_bf16 v[40:43], v[164:167], v[192:195], v[40:43]
	v_mfma_f32_16x16x32_bf16 v[36:39], v[172:175], v[192:195], v[36:39]
	v_mfma_f32_16x16x32_bf16 v[22:25], v[164:167], v[204:207], v[22:25]
	v_mfma_f32_16x16x32_bf16 v[18:21], v[172:175], v[204:207], v[18:21]
	v_mfma_f32_16x16x32_bf16 v[6:9], v[164:167], v[208:211], v[6:9]
	v_mfma_f32_16x16x32_bf16 v[2:5], v[172:175], v[208:211], v[2:5]
	s_barrier
	s_setprio 0
	s_add_i32 s24, s24, 2
	s_add_u32 s8, s8, 0x100
	s_addc_u32 s9, s9, 0
	s_add_u32 s20, s20, 0x100
	s_addc_u32 s21, s21, 0
	s_cmpk_gt_u32 s24, 0x55
	s_cbranch_scc1 .Lpeel_done_P7
.LBB0_1195:
	s_add_u32 s18, s8, 0xffea0080
	s_addc_u32 s19, s9, -1
	s_add_i32 s25, 0, 0x10000
	s_cmpk_eq_i32 s24, 0x54
	s_cselect_b32 s23, s45, s19
	s_cselect_b32 s22, s44, s18
	s_cselect_b32 s19, s47, s21
	s_cselect_b32 s18, s46, s20
	s_add_i32 s34, 0, 0x14000
	ds_read_b128 v[138:141], v1
	ds_read_b128 v[142:145], v160
	ds_read_b128 v[146:149], v1 offset:2048
	ds_read_b128 v[150:153], v160 offset:2048
	ds_read_b128 v[154:157], v1 offset:16384
	ds_read_b128 v[164:167], v160 offset:16384
	ds_read_b128 v[168:171], v1 offset:18432
	ds_read_b128 v[172:175], v160 offset:18432
	s_add_i32 m0, s29, 0xc000
	ds_read_b128 v[176:179], v161
	ds_read_b128 v[184:187], v161 offset:2048
	ds_read_b128 v[188:191], v162
	ds_read_b128 v[192:195], v162 offset:2048
	ds_read_b128 v[196:199], v161 offset:4096
	ds_read_b128 v[200:203], v161 offset:6144
	ds_read_b128 v[204:207], v162 offset:4096
	ds_read_b128 v[208:211], v162 offset:6144
	global_load_lds_dwordx4 v136, s[8:9]
	s_add_i32 m0, s29, 0xe000
	s_nop 0
	global_load_lds_dwordx4 v134, s[8:9]
	s_waitcnt vmcnt(8)
	s_waitcnt lgkmcnt(0)
	s_setprio 1
	s_barrier
	v_mfma_f32_16x16x32_bf16 v[128:131], v[138:141], v[176:179], v[128:131]
	v_mfma_f32_16x16x32_bf16 v[124:127], v[146:149], v[176:179], v[124:127]
	v_mfma_f32_16x16x32_bf16 v[112:115], v[138:141], v[184:187], v[112:115]
	v_mfma_f32_16x16x32_bf16 v[108:111], v[146:149], v[184:187], v[108:111]
	v_mfma_f32_16x16x32_bf16 v[96:99], v[138:141], v[196:199], v[96:99]
	v_mfma_f32_16x16x32_bf16 v[92:95], v[146:149], v[196:199], v[92:95]
	v_mfma_f32_16x16x32_bf16 v[80:83], v[138:141], v[200:203], v[80:83]
	v_mfma_f32_16x16x32_bf16 v[76:79], v[146:149], v[200:203], v[76:79]
	v_mfma_f32_16x16x32_bf16 v[128:131], v[142:145], v[188:191], v[128:131]
	v_mfma_f32_16x16x32_bf16 v[124:127], v[150:153], v[188:191], v[124:127]
	v_mfma_f32_16x16x32_bf16 v[112:115], v[142:145], v[192:195], v[112:115]
	v_mfma_f32_16x16x32_bf16 v[108:111], v[150:153], v[192:195], v[108:111]
	v_mfma_f32_16x16x32_bf16 v[96:99], v[142:145], v[204:207], v[96:99]
	v_mfma_f32_16x16x32_bf16 v[92:95], v[150:153], v[204:207], v[92:95]
	v_mfma_f32_16x16x32_bf16 v[80:83], v[142:145], v[208:211], v[80:83]
	v_mfma_f32_16x16x32_bf16 v[76:79], v[150:153], v[208:211], v[76:79]
	s_setprio 0
	s_setprio 1
	v_mfma_f32_16x16x32_bf16 v[120:123], v[154:157], v[176:179], v[120:123]
	v_mfma_f32_16x16x32_bf16 v[116:119], v[168:171], v[176:179], v[116:119]
	v_mfma_f32_16x16x32_bf16 v[104:107], v[154:157], v[184:187], v[104:107]
	v_mfma_f32_16x16x32_bf16 v[100:103], v[168:171], v[184:187], v[100:103]
	v_mfma_f32_16x16x32_bf16 v[88:91], v[154:157], v[196:199], v[88:91]
	v_mfma_f32_16x16x32_bf16 v[84:87], v[168:171], v[196:199], v[84:87]
	v_mfma_f32_16x16x32_bf16 v[72:75], v[154:157], v[200:203], v[72:75]
	v_mfma_f32_16x16x32_bf16 v[68:71], v[168:171], v[200:203], v[68:71]
	v_mfma_f32_16x16x32_bf16 v[120:123], v[164:167], v[188:191], v[120:123]
	v_mfma_f32_16x16x32_bf16 v[116:119], v[172:175], v[188:191], v[116:119]
	v_mfma_f32_16x16x32_bf16 v[104:107], v[164:167], v[192:195], v[104:107]
	v_mfma_f32_16x16x32_bf16 v[100:103], v[172:175], v[192:195], v[100:103]
	v_mfma_f32_16x16x32_bf16 v[88:91], v[164:167], v[204:207], v[88:91]
	v_mfma_f32_16x16x32_bf16 v[84:87], v[172:175], v[204:207], v[84:87]
	v_mfma_f32_16x16x32_bf16 v[72:75], v[164:167], v[208:211], v[72:75]
	v_mfma_f32_16x16x32_bf16 v[68:71], v[172:175], v[208:211], v[68:71]
	s_barrier
	s_setprio 0
	s_add_i32 s25, s25, s28
	s_mov_b32 m0, s25
	ds_read_b128 v[176:179], v161 offset:16384
	ds_read_b128 v[184:187], v161 offset:18432
	ds_read_b128 v[188:191], v162 offset:16384
	ds_read_b128 v[192:195], v162 offset:18432
	ds_read_b128 v[196:199], v161 offset:20480
	ds_read_b128 v[200:203], v161 offset:22528
	ds_read_b128 v[204:207], v162 offset:20480
	ds_read_b128 v[208:211], v162 offset:22528
	global_load_lds_dwordx4 v34, s[18:19]
	s_add_i32 m0, s25, 0x2000
	s_add_u32 s30, s18, 0x160000
	s_addc_u32 s31, s19, 0
	s_add_i32 s25, s34, s28
	global_load_lds_dwordx4 v132, s[18:19]
	s_mov_b32 m0, s25
	s_nop 0
	global_load_lds_dwordx4 v34, s[30:31]
	s_add_i32 m0, s25, 0x2000
	s_nop 0
	global_load_lds_dwordx4 v132, s[30:31]
	s_mov_b32 m0, s29
	s_nop 0
	global_load_lds_dwordx4 v136, s[22:23]
	s_mov_b32 m0, s33
	s_nop 0
	global_load_lds_dwordx4 v134, s[22:23]
	s_waitcnt vmcnt(8)
	s_waitcnt lgkmcnt(0)
	s_setprio 1
	s_barrier
	v_mfma_f32_16x16x32_bf16 v[64:67], v[138:141], v[176:179], v[64:67]
	v_mfma_f32_16x16x32_bf16 v[60:63], v[146:149], v[176:179], v[60:63]
	v_mfma_f32_16x16x32_bf16 v[48:51], v[138:141], v[184:187], v[48:51]
	v_mfma_f32_16x16x32_bf16 v[44:47], v[146:149], v[184:187], v[44:47]
	v_mfma_f32_16x16x32_bf16 v[30:33], v[138:141], v[196:199], v[30:33]
	v_mfma_f32_16x16x32_bf16 v[26:29], v[146:149], v[196:199], v[26:29]
	v_mfma_f32_16x16x32_bf16 v[14:17], v[138:141], v[200:203], v[14:17]
	v_mfma_f32_16x16x32_bf16 v[10:13], v[146:149], v[200:203], v[10:13]
	v_mfma_f32_16x16x32_bf16 v[64:67], v[142:145], v[188:191], v[64:67]
	v_mfma_f32_16x16x32_bf16 v[60:63], v[150:153], v[188:191], v[60:63]
	v_mfma_f32_16x16x32_bf16 v[48:51], v[142:145], v[192:195], v[48:51]
	v_mfma_f32_16x16x32_bf16 v[44:47], v[150:153], v[192:195], v[44:47]
	v_mfma_f32_16x16x32_bf16 v[30:33], v[142:145], v[204:207], v[30:33]
	v_mfma_f32_16x16x32_bf16 v[26:29], v[150:153], v[204:207], v[26:29]
	v_mfma_f32_16x16x32_bf16 v[14:17], v[142:145], v[208:211], v[14:17]
	v_mfma_f32_16x16x32_bf16 v[10:13], v[150:153], v[208:211], v[10:13]
	s_setprio 0
	s_setprio 1
	v_mfma_f32_16x16x32_bf16 v[56:59], v[154:157], v[176:179], v[56:59]
	v_mfma_f32_16x16x32_bf16 v[52:55], v[168:171], v[176:179], v[52:55]
	v_mfma_f32_16x16x32_bf16 v[40:43], v[154:157], v[184:187], v[40:43]
	v_mfma_f32_16x16x32_bf16 v[36:39], v[168:171], v[184:187], v[36:39]
	v_mfma_f32_16x16x32_bf16 v[22:25], v[154:157], v[196:199], v[22:25]
	v_mfma_f32_16x16x32_bf16 v[18:21], v[168:171], v[196:199], v[18:21]
	v_mfma_f32_16x16x32_bf16 v[6:9], v[154:157], v[200:203], v[6:9]
	v_mfma_f32_16x16x32_bf16 v[2:5], v[168:171], v[200:203], v[2:5]
	v_mfma_f32_16x16x32_bf16 v[56:59], v[164:167], v[188:191], v[56:59]
	v_mfma_f32_16x16x32_bf16 v[52:55], v[172:175], v[188:191], v[52:55]
	v_mfma_f32_16x16x32_bf16 v[40:43], v[164:167], v[192:195], v[40:43]
	v_mfma_f32_16x16x32_bf16 v[36:39], v[172:175], v[192:195], v[36:39]
	v_mfma_f32_16x16x32_bf16 v[22:25], v[164:167], v[204:207], v[22:25]
	v_mfma_f32_16x16x32_bf16 v[18:21], v[172:175], v[204:207], v[18:21]
	v_mfma_f32_16x16x32_bf16 v[6:9], v[164:167], v[208:211], v[6:9]
	v_mfma_f32_16x16x32_bf16 v[2:5], v[172:175], v[208:211], v[2:5]
	s_barrier
	s_setprio 0
	s_add_i32 s25, 0, 0x18000
	s_add_i32 s30, 0, 0x1c000
	ds_read_b128 v[138:141], v1 offset:32768
	ds_read_b128 v[142:145], v160 offset:32768
	ds_read_b128 v[146:149], v1 offset:34816
	ds_read_b128 v[150:153], v160 offset:34816
	ds_read_b128 v[154:157], v1 offset:49152
	ds_read_b128 v[164:167], v160 offset:49152
	ds_read_b128 v[168:171], v1 offset:51200
	ds_read_b128 v[172:175], v160 offset:51200
	s_mov_b64 s[100:101], s[22:23]
	s_add_u32 s22, s22, 0x160000
	s_addc_u32 s23, s23, 0
	s_mov_b32 m0, s48
	ds_read_b128 v[176:179], v161 offset:32768
	ds_read_b128 v[184:187], v161 offset:34816
	ds_read_b128 v[188:191], v162 offset:32768
	ds_read_b128 v[192:195], v162 offset:34816
	ds_read_b128 v[196:199], v161 offset:36864
	ds_read_b128 v[200:203], v161 offset:38912
	ds_read_b128 v[204:207], v162 offset:36864
	ds_read_b128 v[208:211], v162 offset:38912
	global_load_lds_dwordx4 v136, s[22:23]
	s_mov_b32 m0, s49
	s_nop 0
	global_load_lds_dwordx4 v134, s[22:23]
	s_waitcnt vmcnt(8)
	s_waitcnt lgkmcnt(0)
	s_setprio 1
	s_barrier
	v_mfma_f32_16x16x32_bf16 v[128:131], v[138:141], v[176:179], v[128:131]
	v_mfma_f32_16x16x32_bf16 v[124:127], v[146:149], v[176:179], v[124:127]
	v_mfma_f32_16x16x32_bf16 v[112:115], v[138:141], v[184:187], v[112:115]
	v_mfma_f32_16x16x32_bf16 v[108:111], v[146:149], v[184:187], v[108:111]
	v_mfma_f32_16x16x32_bf16 v[96:99], v[138:141], v[196:199], v[96:99]
	v_mfma_f32_16x16x32_bf16 v[92:95], v[146:149], v[196:199], v[92:95]
	v_mfma_f32_16x16x32_bf16 v[80:83], v[138:141], v[200:203], v[80:83]
	v_mfma_f32_16x16x32_bf16 v[76:79], v[146:149], v[200:203], v[76:79]
	v_mfma_f32_16x16x32_bf16 v[128:131], v[142:145], v[188:191], v[128:131]
	v_mfma_f32_16x16x32_bf16 v[124:127], v[150:153], v[188:191], v[124:127]
	v_mfma_f32_16x16x32_bf16 v[112:115], v[142:145], v[192:195], v[112:115]
	v_mfma_f32_16x16x32_bf16 v[108:111], v[150:153], v[192:195], v[108:111]
	v_mfma_f32_16x16x32_bf16 v[96:99], v[142:145], v[204:207], v[96:99]
	v_mfma_f32_16x16x32_bf16 v[92:95], v[150:153], v[204:207], v[92:95]
	v_mfma_f32_16x16x32_bf16 v[80:83], v[142:145], v[208:211], v[80:83]
	v_mfma_f32_16x16x32_bf16 v[76:79], v[150:153], v[208:211], v[76:79]
	s_setprio 0
	s_setprio 1
	v_mfma_f32_16x16x32_bf16 v[120:123], v[154:157], v[176:179], v[120:123]
	v_mfma_f32_16x16x32_bf16 v[116:119], v[168:171], v[176:179], v[116:119]
	v_mfma_f32_16x16x32_bf16 v[104:107], v[154:157], v[184:187], v[104:107]
	v_mfma_f32_16x16x32_bf16 v[100:103], v[168:171], v[184:187], v[100:103]
	v_mfma_f32_16x16x32_bf16 v[88:91], v[154:157], v[196:199], v[88:91]
	v_mfma_f32_16x16x32_bf16 v[84:87], v[168:171], v[196:199], v[84:87]
	v_mfma_f32_16x16x32_bf16 v[72:75], v[154:157], v[200:203], v[72:75]
	v_mfma_f32_16x16x32_bf16 v[68:71], v[168:171], v[200:203], v[68:71]
	v_mfma_f32_16x16x32_bf16 v[120:123], v[164:167], v[188:191], v[120:123]
	v_mfma_f32_16x16x32_bf16 v[116:119], v[172:175], v[188:191], v[116:119]
	v_mfma_f32_16x16x32_bf16 v[104:107], v[164:167], v[192:195], v[104:107]
	v_mfma_f32_16x16x32_bf16 v[100:103], v[172:175], v[192:195], v[100:103]
	v_mfma_f32_16x16x32_bf16 v[88:91], v[164:167], v[204:207], v[88:91]
	v_mfma_f32_16x16x32_bf16 v[84:87], v[172:175], v[204:207], v[84:87]
	v_mfma_f32_16x16x32_bf16 v[72:75], v[164:167], v[208:211], v[72:75]
	v_mfma_f32_16x16x32_bf16 v[68:71], v[172:175], v[208:211], v[68:71]
	s_barrier
	s_setprio 0
	s_add_i32 s22, s25, s28
	s_add_i32 m0, s22, 0xffffff80
	ds_read_b128 v[176:179], v161 offset:49152
	ds_read_b128 v[184:187], v161 offset:51200
	ds_read_b128 v[188:191], v162 offset:49152
	ds_read_b128 v[192:195], v162 offset:51200
	ds_read_b128 v[196:199], v161 offset:53248
	ds_read_b128 v[200:203], v161 offset:55296
	ds_read_b128 v[204:207], v162 offset:53248
	ds_read_b128 v[208:211], v162 offset:55296
	global_load_lds_dwordx4 v34, s[18:19] offset:128
	s_add_i32 m0, s22, 0x1f80
	s_mov_b64 s[98:99], s[18:19]
	s_add_u32 s18, s18, 0x160080
	s_addc_u32 s19, s19, 0
	s_add_i32 s22, s30, s28
	global_load_lds_dwordx4 v132, s[98:99] offset:128
	s_mov_b32 m0, s22
	s_nop 0
	global_load_lds_dwordx4 v34, s[18:19]
	s_add_i32 m0, s22, 0x2000
	s_nop 0
	global_load_lds_dwordx4 v132, s[18:19]
	s_add_i32 m0, s53, 0xffffff80
	s_nop 0
	global_load_lds_dwordx4 v136, s[100:101] offset:128
	s_add_i32 m0, s54, 0xffffff80
	s_nop 0
	global_load_lds_dwordx4 v134, s[100:101] offset:128
	s_waitcnt vmcnt(8)
	s_waitcnt lgkmcnt(0)
	s_setprio 1
	s_barrier
	v_mfma_f32_16x16x32_bf16 v[64:67], v[138:141], v[176:179], v[64:67]
	v_mfma_f32_16x16x32_bf16 v[60:63], v[146:149], v[176:179], v[60:63]
	v_mfma_f32_16x16x32_bf16 v[48:51], v[138:141], v[184:187], v[48:51]
	v_mfma_f32_16x16x32_bf16 v[44:47], v[146:149], v[184:187], v[44:47]
	v_mfma_f32_16x16x32_bf16 v[30:33], v[138:141], v[196:199], v[30:33]
	v_mfma_f32_16x16x32_bf16 v[26:29], v[146:149], v[196:199], v[26:29]
	v_mfma_f32_16x16x32_bf16 v[14:17], v[138:141], v[200:203], v[14:17]
	v_mfma_f32_16x16x32_bf16 v[10:13], v[146:149], v[200:203], v[10:13]
	v_mfma_f32_16x16x32_bf16 v[64:67], v[142:145], v[188:191], v[64:67]
	v_mfma_f32_16x16x32_bf16 v[60:63], v[150:153], v[188:191], v[60:63]
	v_mfma_f32_16x16x32_bf16 v[48:51], v[142:145], v[192:195], v[48:51]
	v_mfma_f32_16x16x32_bf16 v[44:47], v[150:153], v[192:195], v[44:47]
	v_mfma_f32_16x16x32_bf16 v[30:33], v[142:145], v[204:207], v[30:33]
	v_mfma_f32_16x16x32_bf16 v[26:29], v[150:153], v[204:207], v[26:29]
	v_mfma_f32_16x16x32_bf16 v[14:17], v[142:145], v[208:211], v[14:17]
	v_mfma_f32_16x16x32_bf16 v[10:13], v[150:153], v[208:211], v[10:13]
	s_setprio 0
	s_setprio 1
	v_mfma_f32_16x16x32_bf16 v[56:59], v[154:157], v[176:179], v[56:59]
	v_mfma_f32_16x16x32_bf16 v[52:55], v[168:171], v[176:179], v[52:55]
	v_mfma_f32_16x16x32_bf16 v[40:43], v[154:157], v[184:187], v[40:43]
	v_mfma_f32_16x16x32_bf16 v[36:39], v[168:171], v[184:187], v[36:39]
	v_mfma_f32_16x16x32_bf16 v[22:25], v[154:157], v[196:199], v[22:25]
	v_mfma_f32_16x16x32_bf16 v[18:21], v[168:171], v[196:199], v[18:21]
	v_mfma_f32_16x16x32_bf16 v[6:9], v[154:157], v[200:203], v[6:9]
	v_mfma_f32_16x16x32_bf16 v[2:5], v[168:171], v[200:203], v[2:5]
	v_mfma_f32_16x16x32_bf16 v[56:59], v[164:167], v[188:191], v[56:59]
	v_mfma_f32_16x16x32_bf16 v[52:55], v[172:175], v[188:191], v[52:55]
	v_mfma_f32_16x16x32_bf16 v[40:43], v[164:167], v[192:195], v[40:43]
	v_mfma_f32_16x16x32_bf16 v[36:39], v[172:175], v[192:195], v[36:39]
	v_mfma_f32_16x16x32_bf16 v[22:25], v[164:167], v[204:207], v[22:25]
	v_mfma_f32_16x16x32_bf16 v[18:21], v[172:175], v[204:207], v[18:21]
	v_mfma_f32_16x16x32_bf16 v[6:9], v[164:167], v[208:211], v[6:9]
	v_mfma_f32_16x16x32_bf16 v[2:5], v[172:175], v[208:211], v[2:5]
	s_barrier
	s_setprio 0
	s_add_i32 s24, s24, 2
	s_add_u32 s8, s8, 0x100
	s_addc_u32 s9, s9, 0
	s_add_u32 s20, s20, 0x100
	s_addc_u32 s21, s21, 0
	s_cmpk_gt_u32 s24, 0x55
	s_cbranch_scc0 .LBB0_1195
